# speedup vs baseline: 1.0148x; 1.0148x over previous
; __device__ __forceinline__ int otid() { int t = threadIdx.x; asm volatile("" : "+v"(t)); return t; }
; __device__ __forceinline__ int obid() { int t = blockIdx.x; asm volatile("" : "+s"(t)); return t; }
; __device__ __forceinline__ void ln_phase(const PRef& P, const float* __restrict__ gw, const float* __restrict__ bw, bool write_f32) {
;   float* H = P.out(); bfr* hb = (bfr*)(P.ws() + WS_HB); float2* st = (float2*)(P.ws() + WS_MISC + MS_STATS);
;   const int lane = otid() & 63, wv = obid() * 8 + (otid() >> 6), nw = gridDim.x * 8;
;   for (int row = wv; row < TT; row += 2 * nw) {
;     float4* hp0 = (float4*)(H + (long)row * DM); float4* hp1 = (float4*)(H + (long)(row + nw) * DM); float4 v[2][4]; float s0 = 0.f, s1 = 0.f;
; #pragma unroll
;     for (int i = 0; i < 4; ++i) { v[0][i] = hp0[lane + 64 * i]; v[1][i] = hp1[lane + 64 * i]; }
; #pragma unroll
;     for (int i = 0; i < 4; ++i) { s0 += v[0][i].x + v[0][i].y + v[0][i].z + v[0][i].w; s1 += v[1][i].x + v[1][i].y + v[1][i].z + v[1][i].w; }
; #pragma unroll
;     for (int o = 32; o > 0; o >>= 1) { s0 += __shfl_xor(s0, o); s1 += __shfl_xor(s1, o); }
;     const float mu0 = s0 * (1.f / DM), mu1 = s1 * (1.f / DM); float q0 = 0.f, q1 = 0.f;
; #pragma unroll
;     for (int i = 0; i < 4; ++i) { float a = v[0][i].x - mu0, b = v[0][i].y - mu0, c = v[0][i].z - mu0, d = v[0][i].w - mu0; q0 += a * a + b * b + c * c + d * d;
;       float e = v[1][i].x - mu1, f = v[1][i].y - mu1, g = v[1][i].z - mu1, h = v[1][i].w - mu1; q1 += e * e + f * f + g * g + h * h; }
; #pragma unroll
;     for (int o = 32; o > 0; o >>= 1) { q0 += __shfl_xor(q0, o); q1 += __shfl_xor(q1, o); }
;     const float rs0 = rsqrtf(q0 * (1.f / DM) + 1e-5f), rs1 = rsqrtf(q1 * (1.f / DM) + 1e-5f);
;     if (lane == 0) { st[row] = make_float2(mu0, rs0); st[row + nw] = make_float2(mu1, rs1); }
.LBB0_681:
	v_readlane_b32 s2, v255, 14
	s_cmp_gt_i32 s2, 14
	s_mov_b64 s[8:9], -1
	s_cbranch_scc0 .LBB0_688
	s_mov_b64 s[12:13], exec
	v_readlane_b32 s8, v255, 15
	v_readlane_b32 s9, v255, 16
	s_nop 0
	s_load_dwordx4 s[16:19], s[8:9], 0x10
	s_load_dwordx4 s[20:23], s[8:9], 0xf0
	v_readlane_b32 s2, v255, 13
	v_and_b32_e32 v2, 63, v182
	v_lshrrev_b32_e32 v3, 6, v182
	v_lshlrev_b32_e32 v4, 4, v2
	v_lshlrev_b32_e32 v5, 3, v2
	s_lshl_b32 s10, s2, 12
	s_mov_b32 s14, 0
	v_readfirstlane_b32 s15, v3
	s_lshl_b32 s11, s94, 3
	s_waitcnt lgkmcnt(0)
	s_add_u32 s16, s16, s10
	s_addc_u32 s17, s17, 0
	s_add_u32 s18, s18, s10
	s_addc_u32 s19, s19, 0
	global_load_dwordx4 v[8:11], v4, s[16:17]
	global_load_dwordx4 v[24:27], v4, s[18:19]
	global_load_dwordx4 v[12:15], v4, s[16:17] offset:1024
	global_load_dwordx4 v[28:31], v4, s[18:19] offset:1024
	global_load_dwordx4 v[16:19], v4, s[16:17] offset:2048
	global_load_dwordx4 v[32:35], v4, s[18:19] offset:2048
	global_load_dwordx4 v[20:23], v4, s[16:17] offset:3072
	global_load_dwordx4 v[36:39], v4, s[18:19] offset:3072
	s_add_u32 s11, s11, s15
	s_lshl_b32 s15, s96, 3
	s_add_u32 s8, s22, 0x3000000
	s_addc_u32 s9, s23, 0
	s_add_u32 s22, s22, 0x1d980000
	s_addc_u32 s23, s23, 0
	s_cmpk_ge_u32 s11, 0x8000
	s_cbranch_scc1 .Llna_done
	s_lshl_b32 s2, s11, 12
	s_add_u32 s16, s20, s2
	s_addc_u32 s17, s21, 0
	s_lshl_b32 s10, s15, 12
	s_add_u32 s18, s16, s10
	s_addc_u32 s19, s17, 0
	global_load_dwordx4 v[40:43], v4, s[16:17]
	global_load_dwordx4 v[44:47], v4, s[16:17] offset:1024
	global_load_dwordx4 v[48:51], v4, s[16:17] offset:2048
	global_load_dwordx4 v[52:55], v4, s[16:17] offset:3072
	global_load_dwordx4 v[56:59], v4, s[18:19]
	global_load_dwordx4 v[60:63], v4, s[18:19] offset:1024
	global_load_dwordx4 v[64:67], v4, s[18:19] offset:2048
	global_load_dwordx4 v[68:71], v4, s[18:19] offset:3072
	s_lshl_b32 s10, s15, 1
	s_add_u32 s10, s11, s10
	s_cmpk_lt_u32 s10, 0x8000
	s_cselect_b32 s10, s10, s11
	s_lshl_b32 s2, s10, 12
	s_add_u32 s16, s20, s2
	s_addc_u32 s17, s21, 0
	s_lshl_b32 s10, s15, 12
	s_add_u32 s18, s16, s10
	s_addc_u32 s19, s17, 0
	global_load_dwordx4 v[72:75], v4, s[16:17]
	global_load_dwordx4 v[76:79], v4, s[16:17] offset:1024
	global_load_dwordx4 v[80:83], v4, s[16:17] offset:2048
	global_load_dwordx4 v[84:87], v4, s[16:17] offset:3072
	global_load_dwordx4 v[88:91], v4, s[18:19]
	global_load_dwordx4 v[92:95], v4, s[18:19] offset:1024
	global_load_dwordx4 v[96:99], v4, s[18:19] offset:2048
	global_load_dwordx4 v[100:103], v4, s[18:19] offset:3072
	s_waitcnt vmcnt(8)
	v_add_f32_e32 v104, v40, v41
	v_add_f32_e32 v105, v56, v57
	v_add_f32_e32 v104, v104, v42
	v_add_f32_e32 v105, v105, v58
	v_add_f32_e32 v104, v104, v43
	v_add_f32_e32 v105, v105, v59
	v_add_f32_e32 v104, v104, v44
	v_add_f32_e32 v105, v105, v60
	v_add_f32_e32 v104, v104, v45
	v_add_f32_e32 v105, v105, v61
	v_add_f32_e32 v104, v104, v46
	v_add_f32_e32 v105, v105, v62
	v_add_f32_e32 v104, v104, v47
	v_add_f32_e32 v105, v105, v63
	v_add_f32_e32 v104, v104, v48
	v_add_f32_e32 v105, v105, v64
	v_add_f32_e32 v104, v104, v49
	v_add_f32_e32 v105, v105, v65
	v_add_f32_e32 v104, v104, v50
	v_add_f32_e32 v105, v105, v66
	v_add_f32_e32 v104, v104, v51
	v_add_f32_e32 v105, v105, v67
	v_add_f32_e32 v104, v104, v52
	v_add_f32_e32 v105, v105, v68
	v_add_f32_e32 v104, v104, v53
	v_add_f32_e32 v105, v105, v69
	v_add_f32_e32 v104, v104, v54
	v_add_f32_e32 v105, v105, v70
	v_add_f32_e32 v104, v104, v55
	v_add_f32_e32 v105, v105, v71
	s_nop 1
	v_add_f32_dpp v104, v104, v104 quad_perm:[1,0,3,2] row_mask:0xf bank_mask:0xf
	v_add_f32_dpp v105, v105, v105 quad_perm:[1,0,3,2] row_mask:0xf bank_mask:0xf
	s_nop 1
	v_add_f32_dpp v104, v104, v104 quad_perm:[2,3,0,1] row_mask:0xf bank_mask:0xf
	v_add_f32_dpp v105, v105, v105 quad_perm:[2,3,0,1] row_mask:0xf bank_mask:0xf
	s_nop 1
	v_add_f32_dpp v104, v104, v104 row_half_mirror row_mask:0xf bank_mask:0xf
	v_add_f32_dpp v105, v105, v105 row_half_mirror row_mask:0xf bank_mask:0xf
	s_nop 1
	v_add_f32_dpp v104, v104, v104 row_mirror row_mask:0xf bank_mask:0xf
	v_add_f32_dpp v105, v105, v105 row_mirror row_mask:0xf bank_mask:0xf
	s_nop 1
	v_readlane_b32 s2, v104, 0
	v_readlane_b32 s10, v104, 16
	v_readlane_b32 s16, v104, 32
	v_readlane_b32 s17, v104, 48
	v_readlane_b32 s18, v105, 0
	v_readlane_b32 s19, v105, 16
	v_mov_b32_e32 v104, s2
	v_add_f32_e32 v104, s10, v104
	v_add_f32_e32 v104, s16, v104
	v_add_f32_e32 v104, s17, v104
	v_readlane_b32 s2, v105, 32
	v_readlane_b32 s10, v105, 48
	v_mov_b32_e32 v105, s18
	v_add_f32_e32 v105, s19, v105
	s_nop 0
	v_add_f32_e32 v105, s2, v105
	v_add_f32_e32 v105, s10, v105
	v_mul_f32_e32 v108, 0x3a800000, v104
	v_mul_f32_e32 v110, 0x3a800000, v105
	v_sub_f32_e32 v40, v40, v108
	v_sub_f32_e32 v56, v56, v110
	v_sub_f32_e32 v41, v41, v108
	v_sub_f32_e32 v57, v57, v110
	v_sub_f32_e32 v42, v42, v108
	v_sub_f32_e32 v58, v58, v110
	v_sub_f32_e32 v43, v43, v108
	v_sub_f32_e32 v59, v59, v110
	v_sub_f32_e32 v44, v44, v108
	v_sub_f32_e32 v60, v60, v110
	v_sub_f32_e32 v45, v45, v108
	v_sub_f32_e32 v61, v61, v110
	v_sub_f32_e32 v46, v46, v108
	v_sub_f32_e32 v62, v62, v110
	v_sub_f32_e32 v47, v47, v108
	v_sub_f32_e32 v63, v63, v110
	v_sub_f32_e32 v48, v48, v108
	v_sub_f32_e32 v64, v64, v110
	v_sub_f32_e32 v49, v49, v108
	v_sub_f32_e32 v65, v65, v110
	v_sub_f32_e32 v50, v50, v108
	v_sub_f32_e32 v66, v66, v110
	v_sub_f32_e32 v51, v51, v108
	v_sub_f32_e32 v67, v67, v110
	v_sub_f32_e32 v52, v52, v108
	v_sub_f32_e32 v68, v68, v110
	v_sub_f32_e32 v53, v53, v108
	v_sub_f32_e32 v69, v69, v110
	v_sub_f32_e32 v54, v54, v108
	v_sub_f32_e32 v70, v70, v110
	v_sub_f32_e32 v55, v55, v108
	v_sub_f32_e32 v71, v71, v110
; __device__ __forceinline__ unsigned pk2(float a, float b) { unsigned r; asm("v_cvt_pk_bf16_f32 %0, %1, %2" : "=v"(r) : "v"(a), "v"(b)); return r; }
; __device__ __forceinline__ void ln_phase(const PRef& P, const float* __restrict__ gw, const float* __restrict__ bw, bool write_f32) {
;     ...
;     const float mu0 = s0 * (1.f / DM), mu1 = s1 * (1.f / DM); float q0 = 0.f, q1 = 0.f;
; #pragma unroll
;     for (int i = 0; i < 4; ++i) { float a = v[0][i].x - mu0, b = v[0][i].y - mu0, c = v[0][i].z - mu0, d = v[0][i].w - mu0; q0 += a * a + b * b + c * c + d * d;
;       float e = v[1][i].x - mu1, f = v[1][i].y - mu1, g = v[1][i].z - mu1, h = v[1][i].w - mu1; q1 += e * e + f * f + g * g + h * h; }
; #pragma unroll
;     for (int o = 32; o > 0; o >>= 1) { q0 += __shfl_xor(q0, o); q1 += __shfl_xor(q1, o); }
;     const float rs0 = rsqrtf(q0 * (1.f / DM) + 1e-5f), rs1 = rsqrtf(q1 * (1.f / DM) + 1e-5f);
;     if (lane == 0) { st[row] = make_float2(mu0, rs0); st[row + nw] = make_float2(mu1, rs1); }
; #pragma unroll
;     for (int i = 0; i < 4; ++i) { float4 g4 = ((const float4*)gw)[lane + 64 * i], b4 = ((const float4*)bw)[lane + 64 * i]; float4 o4, p4;
;       o4.x = (v[0][i].x - mu0) * rs0 * g4.x + b4.x; o4.y = (v[0][i].y - mu0) * rs0 * g4.y + b4.y; o4.z = (v[0][i].z - mu0) * rs0 * g4.z + b4.z; o4.w = (v[0][i].w - mu0) * rs0 * g4.w + b4.w;
;       p4.x = (v[1][i].x - mu1) * rs1 * g4.x + b4.x; p4.y = (v[1][i].y - mu1) * rs1 * g4.y + b4.y; p4.z = (v[1][i].z - mu1) * rs1 * g4.z + b4.z; p4.w = (v[1][i].w - mu1) * rs1 * g4.w + b4.w;
;       if (write_f32) { hp0[lane + 64 * i] = o4; hp1[lane + 64 * i] = p4; }
;       ((u32x2*)(hb + (long)row * DM))[lane + 64 * i] = u32x2{pk2(o4.x, o4.y), pk2(o4.z, o4.w)};
;       ((u32x2*)(hb + (long)(row + nw) * DM))[lane + 64 * i] = u32x2{pk2(p4.x, p4.y), pk2(p4.z, p4.w)}; }
	v_mul_f32_e32 v106, v40, v40
	v_mul_f32_e32 v107, v56, v56
	v_fmac_f32_e32 v106, v41, v41
	v_fmac_f32_e32 v107, v57, v57
	v_fmac_f32_e32 v106, v42, v42
	v_fmac_f32_e32 v107, v58, v58
	v_fmac_f32_e32 v106, v43, v43
	v_fmac_f32_e32 v107, v59, v59
	v_fmac_f32_e32 v106, v44, v44
	v_fmac_f32_e32 v107, v60, v60
	v_fmac_f32_e32 v106, v45, v45
	v_fmac_f32_e32 v107, v61, v61
	v_fmac_f32_e32 v106, v46, v46
	v_fmac_f32_e32 v107, v62, v62
	v_fmac_f32_e32 v106, v47, v47
	v_fmac_f32_e32 v107, v63, v63
	v_fmac_f32_e32 v106, v48, v48
	v_fmac_f32_e32 v107, v64, v64
	v_fmac_f32_e32 v106, v49, v49
	v_fmac_f32_e32 v107, v65, v65
	v_fmac_f32_e32 v106, v50, v50
	v_fmac_f32_e32 v107, v66, v66
	v_fmac_f32_e32 v106, v51, v51
	v_fmac_f32_e32 v107, v67, v67
	v_fmac_f32_e32 v106, v52, v52
	v_fmac_f32_e32 v107, v68, v68
	v_fmac_f32_e32 v106, v53, v53
	v_fmac_f32_e32 v107, v69, v69
	v_fmac_f32_e32 v106, v54, v54
	v_fmac_f32_e32 v107, v70, v70
	v_fmac_f32_e32 v106, v55, v55
	v_fmac_f32_e32 v107, v71, v71
	s_nop 1
	v_add_f32_dpp v106, v106, v106 quad_perm:[1,0,3,2] row_mask:0xf bank_mask:0xf
	v_add_f32_dpp v107, v107, v107 quad_perm:[1,0,3,2] row_mask:0xf bank_mask:0xf
	s_nop 1
	v_add_f32_dpp v106, v106, v106 quad_perm:[2,3,0,1] row_mask:0xf bank_mask:0xf
	v_add_f32_dpp v107, v107, v107 quad_perm:[2,3,0,1] row_mask:0xf bank_mask:0xf
	s_nop 1
	v_add_f32_dpp v106, v106, v106 row_half_mirror row_mask:0xf bank_mask:0xf
	v_add_f32_dpp v107, v107, v107 row_half_mirror row_mask:0xf bank_mask:0xf
	s_nop 1
	v_add_f32_dpp v106, v106, v106 row_mirror row_mask:0xf bank_mask:0xf
	v_add_f32_dpp v107, v107, v107 row_mirror row_mask:0xf bank_mask:0xf
	s_nop 1
	v_readlane_b32 s2, v106, 0
	v_readlane_b32 s10, v106, 16
	v_readlane_b32 s16, v106, 32
	v_readlane_b32 s17, v106, 48
	v_readlane_b32 s18, v107, 0
	v_readlane_b32 s19, v107, 16
	v_mov_b32_e32 v106, s2
	v_add_f32_e32 v106, s10, v106
	v_add_f32_e32 v106, s16, v106
	v_add_f32_e32 v106, s17, v106
	v_readlane_b32 s2, v107, 32
	v_readlane_b32 s10, v107, 48
	v_mov_b32_e32 v107, s18
	v_add_f32_e32 v107, s19, v107
	s_nop 0
	v_add_f32_e32 v107, s2, v107
	v_add_f32_e32 v107, s10, v107
	v_mul_f32_e32 v106, 0x3a800000, v106
	v_mul_f32_e32 v107, 0x3a800000, v107
	v_add_f32_e32 v106, 0x3727c5ac, v106
	v_add_f32_e32 v107, 0x3727c5ac, v107
	v_rsq_f32_e32 v109, v106
	v_rsq_f32_e32 v111, v107
	s_nop 0
	v_mul_f32_e32 v40, v40, v109
	v_mul_f32_e32 v56, v56, v111
	v_mul_f32_e32 v41, v41, v109
	v_mul_f32_e32 v57, v57, v111
	v_mul_f32_e32 v42, v42, v109
	v_mul_f32_e32 v58, v58, v111
	v_mul_f32_e32 v43, v43, v109
	v_mul_f32_e32 v59, v59, v111
	v_mul_f32_e32 v44, v44, v109
	v_mul_f32_e32 v60, v60, v111
	v_mul_f32_e32 v45, v45, v109
	v_mul_f32_e32 v61, v61, v111
	v_mul_f32_e32 v46, v46, v109
	v_mul_f32_e32 v62, v62, v111
	v_mul_f32_e32 v47, v47, v109
	v_mul_f32_e32 v63, v63, v111
	v_mul_f32_e32 v48, v48, v109
	v_mul_f32_e32 v64, v64, v111
	v_mul_f32_e32 v49, v49, v109
	v_mul_f32_e32 v65, v65, v111
	v_mul_f32_e32 v50, v50, v109
	v_mul_f32_e32 v66, v66, v111
	v_mul_f32_e32 v51, v51, v109
	v_mul_f32_e32 v67, v67, v111
	v_mul_f32_e32 v52, v52, v109
	v_mul_f32_e32 v68, v68, v111
	v_mul_f32_e32 v53, v53, v109
	v_mul_f32_e32 v69, v69, v111
	v_mul_f32_e32 v54, v54, v109
	v_mul_f32_e32 v70, v70, v111
	v_mul_f32_e32 v55, v55, v109
	v_mul_f32_e32 v71, v71, v111
	v_fma_f32 v40, v40, v8, v24
	v_fma_f32 v56, v56, v8, v24
	v_fma_f32 v41, v41, v9, v25
	v_fma_f32 v57, v57, v9, v25
	v_fma_f32 v42, v42, v10, v26
	v_fma_f32 v58, v58, v10, v26
	v_fma_f32 v43, v43, v11, v27
	v_fma_f32 v59, v59, v11, v27
	v_fma_f32 v44, v44, v12, v28
	v_fma_f32 v60, v60, v12, v28
	v_fma_f32 v45, v45, v13, v29
	v_fma_f32 v61, v61, v13, v29
	v_fma_f32 v46, v46, v14, v30
	v_fma_f32 v62, v62, v14, v30
	v_fma_f32 v47, v47, v15, v31
	v_fma_f32 v63, v63, v15, v31
	v_fma_f32 v48, v48, v16, v32
	v_fma_f32 v64, v64, v16, v32
	v_fma_f32 v49, v49, v17, v33
	v_fma_f32 v65, v65, v17, v33
	v_fma_f32 v50, v50, v18, v34
	v_fma_f32 v66, v66, v18, v34
	v_fma_f32 v51, v51, v19, v35
	v_fma_f32 v67, v67, v19, v35
	v_fma_f32 v52, v52, v20, v36
	v_fma_f32 v68, v68, v20, v36
	v_fma_f32 v53, v53, v21, v37
	v_fma_f32 v69, v69, v21, v37
	v_fma_f32 v54, v54, v22, v38
	v_fma_f32 v70, v70, v22, v38
	v_fma_f32 v55, v55, v23, v39
	v_fma_f32 v71, v71, v23, v39
	s_lshl_b32 s2, s11, 12
	s_add_u32 s16, s20, s2
	s_addc_u32 s17, s21, 0
	s_lshl_b32 s10, s15, 12
	s_add_u32 s18, s16, s10
	s_addc_u32 s19, s17, 0
	s_cmp_eq_u32 s14, 0
	s_cbranch_scc1 .Llna_nof32_p0
	global_store_dwordx4 v4, v[40:43], s[16:17]
	global_store_dwordx4 v4, v[44:47], s[16:17] offset:1024
	global_store_dwordx4 v4, v[48:51], s[16:17] offset:2048
	global_store_dwordx4 v4, v[52:55], s[16:17] offset:3072
	global_store_dwordx4 v4, v[56:59], s[18:19]
	global_store_dwordx4 v4, v[60:63], s[18:19] offset:1024
	global_store_dwordx4 v4, v[64:67], s[18:19] offset:2048
	global_store_dwordx4 v4, v[68:71], s[18:19] offset:3072
.Llna_nof32_p0:
	v_cvt_pk_bf16_f32 v112, v40, v41
	v_cvt_pk_bf16_f32 v113, v42, v43
	v_cvt_pk_bf16_f32 v114, v44, v45
	v_cvt_pk_bf16_f32 v115, v46, v47
	v_cvt_pk_bf16_f32 v116, v48, v49
	v_cvt_pk_bf16_f32 v117, v50, v51
	v_cvt_pk_bf16_f32 v118, v52, v53
	v_cvt_pk_bf16_f32 v119, v54, v55
	v_cvt_pk_bf16_f32 v120, v56, v57
	v_cvt_pk_bf16_f32 v121, v58, v59
	v_cvt_pk_bf16_f32 v122, v60, v61
	v_cvt_pk_bf16_f32 v123, v62, v63
	v_cvt_pk_bf16_f32 v124, v64, v65
	v_cvt_pk_bf16_f32 v125, v66, v67
	v_cvt_pk_bf16_f32 v126, v68, v69
	v_cvt_pk_bf16_f32 v127, v70, v71
	s_lshl_b32 s2, s11, 11
	s_add_u32 s16, s8, s2
	s_addc_u32 s17, s9, 0
	s_lshl_b32 s10, s15, 11
	s_add_u32 s18, s16, s10
	s_addc_u32 s19, s17, 0
	global_store_dwordx2 v5, v[112:113], s[16:17]
	global_store_dwordx2 v5, v[114:115], s[16:17] offset:512
	global_store_dwordx2 v5, v[116:117], s[16:17] offset:1024
	global_store_dwordx2 v5, v[118:119], s[16:17] offset:1536
	global_store_dwordx2 v5, v[120:121], s[18:19]
	global_store_dwordx2 v5, v[122:123], s[18:19] offset:512
	global_store_dwordx2 v5, v[124:125], s[18:19] offset:1024
	global_store_dwordx2 v5, v[126:127], s[18:19] offset:1536
	s_lshl_b32 s2, s11, 3
	s_add_u32 s16, s22, s2
	s_addc_u32 s17, s23, 0
	s_lshl_b32 s10, s15, 3
	s_add_u32 s18, s16, s10
	s_addc_u32 s19, s17, 0
	s_mov_b64 exec, 1
	global_store_dwordx2 v1, v[108:109], s[16:17]
	global_store_dwordx2 v1, v[110:111], s[18:19]
	s_mov_b64 exec, -1
; __device__ __forceinline__ void ln_phase(const PRef& P, const float* __restrict__ gw, const float* __restrict__ bw, bool write_f32) {
;     ...
;   for (int row = wv; row < TT; row += 2 * nw) {
;     float4* hp0 = (float4*)(H + (long)row * DM); float4* hp1 = (float4*)(H + (long)(row + nw) * DM); float4 v[2][4]; float s0 = 0.f, s1 = 0.f;
; #pragma unroll
;     for (int i = 0; i < 4; ++i) { v[0][i] = hp0[lane + 64 * i]; v[1][i] = hp1[lane + 64 * i]; }
; #pragma unroll
;     for (int i = 0; i < 4; ++i) { s0 += v[0][i].x + v[0][i].y + v[0][i].z + v[0][i].w; s1 += v[1][i].x + v[1][i].y + v[1][i].z + v[1][i].w; }
; #pragma unroll
;     for (int o = 32; o > 0; o >>= 1) { s0 += __shfl_xor(s0, o); s1 += __shfl_xor(s1, o); }
;     const float mu0 = s0 * (1.f / DM), mu1 = s1 * (1.f / DM); float q0 = 0.f, q1 = 0.f;
; #pragma unroll
;     for (int i = 0; i < 4; ++i) { float a = v[0][i].x - mu0, b = v[0][i].y - mu0, c = v[0][i].z - mu0, d = v[0][i].w - mu0; q0 += a * a + b * b + c * c + d * d;
;       float e = v[1][i].x - mu1, f = v[1][i].y - mu1, g = v[1][i].z - mu1, h = v[1][i].w - mu1; q1 += e * e + f * f + g * g + h * h; }
; #pragma unroll
;     for (int o = 32; o > 0; o >>= 1) { q0 += __shfl_xor(q0, o); q1 += __shfl_xor(q1, o); }
.Llna_loop:
	s_lshl_b32 s10, s15, 1
	s_add_u32 s11, s11, s10
	s_cmpk_ge_u32 s11, 0x8000
	s_cbranch_scc1 .Llna_done
	s_lshl_b32 s10, s15, 1
	s_add_u32 s10, s11, s10
	s_cmpk_lt_u32 s10, 0x8000
	s_cselect_b32 s10, s10, s11
	s_lshl_b32 s2, s10, 12
	s_add_u32 s16, s20, s2
	s_addc_u32 s17, s21, 0
	s_lshl_b32 s10, s15, 12
	s_add_u32 s18, s16, s10
	s_addc_u32 s19, s17, 0
	global_load_dwordx4 v[40:43], v4, s[16:17]
	global_load_dwordx4 v[44:47], v4, s[16:17] offset:1024
	global_load_dwordx4 v[48:51], v4, s[16:17] offset:2048
	global_load_dwordx4 v[52:55], v4, s[16:17] offset:3072
	global_load_dwordx4 v[56:59], v4, s[18:19]
	global_load_dwordx4 v[60:63], v4, s[18:19] offset:1024
	global_load_dwordx4 v[64:67], v4, s[18:19] offset:2048
	global_load_dwordx4 v[68:71], v4, s[18:19] offset:3072
	s_cmp_eq_u32 s14, 0
	s_cbranch_scc1 .Llna_w0
	s_waitcnt vmcnt(26)
	s_branch .Llna_x0
.Llna_w0:
	s_waitcnt vmcnt(18)
.Llna_x0:
	v_add_f32_e32 v104, v72, v73
	v_add_f32_e32 v105, v88, v89
	v_add_f32_e32 v104, v104, v74
	v_add_f32_e32 v105, v105, v90
	v_add_f32_e32 v104, v104, v75
	v_add_f32_e32 v105, v105, v91
	v_add_f32_e32 v104, v104, v76
	v_add_f32_e32 v105, v105, v92
	v_add_f32_e32 v104, v104, v77
	v_add_f32_e32 v105, v105, v93
	v_add_f32_e32 v104, v104, v78
	v_add_f32_e32 v105, v105, v94
	v_add_f32_e32 v104, v104, v79
	v_add_f32_e32 v105, v105, v95
	v_add_f32_e32 v104, v104, v80
	v_add_f32_e32 v105, v105, v96
	v_add_f32_e32 v104, v104, v81
	v_add_f32_e32 v105, v105, v97
	v_add_f32_e32 v104, v104, v82
	v_add_f32_e32 v105, v105, v98
	v_add_f32_e32 v104, v104, v83
	v_add_f32_e32 v105, v105, v99
	v_add_f32_e32 v104, v104, v84
	v_add_f32_e32 v105, v105, v100
	v_add_f32_e32 v104, v104, v85
	v_add_f32_e32 v105, v105, v101
	v_add_f32_e32 v104, v104, v86
	v_add_f32_e32 v105, v105, v102
	v_add_f32_e32 v104, v104, v87
	v_add_f32_e32 v105, v105, v103
	s_nop 1
	v_add_f32_dpp v104, v104, v104 quad_perm:[1,0,3,2] row_mask:0xf bank_mask:0xf
	v_add_f32_dpp v105, v105, v105 quad_perm:[1,0,3,2] row_mask:0xf bank_mask:0xf
	s_nop 1
	v_add_f32_dpp v104, v104, v104 quad_perm:[2,3,0,1] row_mask:0xf bank_mask:0xf
	v_add_f32_dpp v105, v105, v105 quad_perm:[2,3,0,1] row_mask:0xf bank_mask:0xf
	s_nop 1
	v_add_f32_dpp v104, v104, v104 row_half_mirror row_mask:0xf bank_mask:0xf
	v_add_f32_dpp v105, v105, v105 row_half_mirror row_mask:0xf bank_mask:0xf
	s_nop 1
	v_add_f32_dpp v104, v104, v104 row_mirror row_mask:0xf bank_mask:0xf
	v_add_f32_dpp v105, v105, v105 row_mirror row_mask:0xf bank_mask:0xf
	s_nop 1
	v_readlane_b32 s2, v104, 0
	v_readlane_b32 s10, v104, 16
	v_readlane_b32 s16, v104, 32
	v_readlane_b32 s17, v104, 48
	v_readlane_b32 s18, v105, 0
	v_readlane_b32 s19, v105, 16
	v_mov_b32_e32 v104, s2
	v_add_f32_e32 v104, s10, v104
	v_add_f32_e32 v104, s16, v104
	v_add_f32_e32 v104, s17, v104
	v_readlane_b32 s2, v105, 32
	v_readlane_b32 s10, v105, 48
	v_mov_b32_e32 v105, s18
	v_add_f32_e32 v105, s19, v105
	s_nop 0
	v_add_f32_e32 v105, s2, v105
	v_add_f32_e32 v105, s10, v105
	v_mul_f32_e32 v108, 0x3a800000, v104
	v_mul_f32_e32 v110, 0x3a800000, v105
	v_sub_f32_e32 v72, v72, v108
	v_sub_f32_e32 v88, v88, v110
	v_sub_f32_e32 v73, v73, v108
	v_sub_f32_e32 v89, v89, v110
	v_sub_f32_e32 v74, v74, v108
	v_sub_f32_e32 v90, v90, v110
	v_sub_f32_e32 v75, v75, v108
	v_sub_f32_e32 v91, v91, v110
	v_sub_f32_e32 v76, v76, v108
	v_sub_f32_e32 v92, v92, v110
	v_sub_f32_e32 v77, v77, v108
	v_sub_f32_e32 v93, v93, v110
	v_sub_f32_e32 v78, v78, v108
	v_sub_f32_e32 v94, v94, v110
	v_sub_f32_e32 v79, v79, v108
	v_sub_f32_e32 v95, v95, v110
	v_sub_f32_e32 v80, v80, v108
	v_sub_f32_e32 v96, v96, v110
	v_sub_f32_e32 v81, v81, v108
	v_sub_f32_e32 v97, v97, v110
	v_sub_f32_e32 v82, v82, v108
	v_sub_f32_e32 v98, v98, v110
	v_sub_f32_e32 v83, v83, v108
	v_sub_f32_e32 v99, v99, v110
	v_sub_f32_e32 v84, v84, v108
	v_sub_f32_e32 v100, v100, v110
	v_sub_f32_e32 v85, v85, v108
	v_sub_f32_e32 v101, v101, v110
	v_sub_f32_e32 v86, v86, v108
	v_sub_f32_e32 v102, v102, v110
	v_sub_f32_e32 v87, v87, v108
	v_sub_f32_e32 v103, v103, v110
	v_mul_f32_e32 v106, v72, v72
	v_mul_f32_e32 v107, v88, v88
	v_fmac_f32_e32 v106, v73, v73
	v_fmac_f32_e32 v107, v89, v89
	v_fmac_f32_e32 v106, v74, v74
	v_fmac_f32_e32 v107, v90, v90
	v_fmac_f32_e32 v106, v75, v75
	v_fmac_f32_e32 v107, v91, v91
	v_fmac_f32_e32 v106, v76, v76
	v_fmac_f32_e32 v107, v92, v92
	v_fmac_f32_e32 v106, v77, v77
	v_fmac_f32_e32 v107, v93, v93
	v_fmac_f32_e32 v106, v78, v78
	v_fmac_f32_e32 v107, v94, v94
	v_fmac_f32_e32 v106, v79, v79
	v_fmac_f32_e32 v107, v95, v95
	v_fmac_f32_e32 v106, v80, v80
	v_fmac_f32_e32 v107, v96, v96
	v_fmac_f32_e32 v106, v81, v81
	v_fmac_f32_e32 v107, v97, v97
	v_fmac_f32_e32 v106, v82, v82
	v_fmac_f32_e32 v107, v98, v98
	v_fmac_f32_e32 v106, v83, v83
	v_fmac_f32_e32 v107, v99, v99
	v_fmac_f32_e32 v106, v84, v84
	v_fmac_f32_e32 v107, v100, v100
	v_fmac_f32_e32 v106, v85, v85
	v_fmac_f32_e32 v107, v101, v101
	v_fmac_f32_e32 v106, v86, v86
	v_fmac_f32_e32 v107, v102, v102
	v_fmac_f32_e32 v106, v87, v87
	v_fmac_f32_e32 v107, v103, v103
	s_nop 1
	v_add_f32_dpp v106, v106, v106 quad_perm:[1,0,3,2] row_mask:0xf bank_mask:0xf
	v_add_f32_dpp v107, v107, v107 quad_perm:[1,0,3,2] row_mask:0xf bank_mask:0xf
	s_nop 1
	v_add_f32_dpp v106, v106, v106 quad_perm:[2,3,0,1] row_mask:0xf bank_mask:0xf
	v_add_f32_dpp v107, v107, v107 quad_perm:[2,3,0,1] row_mask:0xf bank_mask:0xf
	s_nop 1
	v_add_f32_dpp v106, v106, v106 row_half_mirror row_mask:0xf bank_mask:0xf
	v_add_f32_dpp v107, v107, v107 row_half_mirror row_mask:0xf bank_mask:0xf
	s_nop 1
	v_add_f32_dpp v106, v106, v106 row_mirror row_mask:0xf bank_mask:0xf
; __device__ __forceinline__ unsigned pk2(float a, float b) { unsigned r; asm("v_cvt_pk_bf16_f32 %0, %1, %2" : "=v"(r) : "v"(a), "v"(b)); return r; }
; __device__ __forceinline__ void ln_phase(const PRef& P, const float* __restrict__ gw, const float* __restrict__ bw, bool write_f32) {
;     ...
;   for (int row = wv; row < TT; row += 2 * nw) {
;     float4* hp0 = (float4*)(H + (long)row * DM); float4* hp1 = (float4*)(H + (long)(row + nw) * DM); float4 v[2][4]; float s0 = 0.f, s1 = 0.f;
; #pragma unroll
;     for (int i = 0; i < 4; ++i) { v[0][i] = hp0[lane + 64 * i]; v[1][i] = hp1[lane + 64 * i]; }
;     ...
;     const float rs0 = rsqrtf(q0 * (1.f / DM) + 1e-5f), rs1 = rsqrtf(q1 * (1.f / DM) + 1e-5f);
;     if (lane == 0) { st[row] = make_float2(mu0, rs0); st[row + nw] = make_float2(mu1, rs1); }
; #pragma unroll
;     for (int i = 0; i < 4; ++i) { float4 g4 = ((const float4*)gw)[lane + 64 * i], b4 = ((const float4*)bw)[lane + 64 * i]; float4 o4, p4;
;       o4.x = (v[0][i].x - mu0) * rs0 * g4.x + b4.x; o4.y = (v[0][i].y - mu0) * rs0 * g4.y + b4.y; o4.z = (v[0][i].z - mu0) * rs0 * g4.z + b4.z; o4.w = (v[0][i].w - mu0) * rs0 * g4.w + b4.w;
;       p4.x = (v[1][i].x - mu1) * rs1 * g4.x + b4.x; p4.y = (v[1][i].y - mu1) * rs1 * g4.y + b4.y; p4.z = (v[1][i].z - mu1) * rs1 * g4.z + b4.z; p4.w = (v[1][i].w - mu1) * rs1 * g4.w + b4.w;
;       if (write_f32) { hp0[lane + 64 * i] = o4; hp1[lane + 64 * i] = p4; }
;       ((u32x2*)(hb + (long)row * DM))[lane + 64 * i] = u32x2{pk2(o4.x, o4.y), pk2(o4.z, o4.w)};
;       ((u32x2*)(hb + (long)(row + nw) * DM))[lane + 64 * i] = u32x2{pk2(p4.x, p4.y), pk2(p4.z, p4.w)}; }
	v_add_f32_dpp v107, v107, v107 row_mirror row_mask:0xf bank_mask:0xf
	s_nop 1
	v_readlane_b32 s2, v106, 0
	v_readlane_b32 s10, v106, 16
	v_readlane_b32 s16, v106, 32
	v_readlane_b32 s17, v106, 48
	v_readlane_b32 s18, v107, 0
	v_readlane_b32 s19, v107, 16
	v_mov_b32_e32 v106, s2
	v_add_f32_e32 v106, s10, v106
	v_add_f32_e32 v106, s16, v106
	v_add_f32_e32 v106, s17, v106
	v_readlane_b32 s2, v107, 32
	v_readlane_b32 s10, v107, 48
	v_mov_b32_e32 v107, s18
	v_add_f32_e32 v107, s19, v107
	s_nop 0
	v_add_f32_e32 v107, s2, v107
	v_add_f32_e32 v107, s10, v107
	v_mul_f32_e32 v106, 0x3a800000, v106
	v_mul_f32_e32 v107, 0x3a800000, v107
	v_add_f32_e32 v106, 0x3727c5ac, v106
	v_add_f32_e32 v107, 0x3727c5ac, v107
	v_rsq_f32_e32 v109, v106
	v_rsq_f32_e32 v111, v107
	s_nop 0
	v_mul_f32_e32 v72, v72, v109
	v_mul_f32_e32 v88, v88, v111
	v_mul_f32_e32 v73, v73, v109
	v_mul_f32_e32 v89, v89, v111
	v_mul_f32_e32 v74, v74, v109
	v_mul_f32_e32 v90, v90, v111
	v_mul_f32_e32 v75, v75, v109
	v_mul_f32_e32 v91, v91, v111
	v_mul_f32_e32 v76, v76, v109
	v_mul_f32_e32 v92, v92, v111
	v_mul_f32_e32 v77, v77, v109
	v_mul_f32_e32 v93, v93, v111
	v_mul_f32_e32 v78, v78, v109
	v_mul_f32_e32 v94, v94, v111
	v_mul_f32_e32 v79, v79, v109
	v_mul_f32_e32 v95, v95, v111
	v_mul_f32_e32 v80, v80, v109
	v_mul_f32_e32 v96, v96, v111
	v_mul_f32_e32 v81, v81, v109
	v_mul_f32_e32 v97, v97, v111
	v_mul_f32_e32 v82, v82, v109
	v_mul_f32_e32 v98, v98, v111
	v_mul_f32_e32 v83, v83, v109
	v_mul_f32_e32 v99, v99, v111
	v_mul_f32_e32 v84, v84, v109
	v_mul_f32_e32 v100, v100, v111
	v_mul_f32_e32 v85, v85, v109
	v_mul_f32_e32 v101, v101, v111
	v_mul_f32_e32 v86, v86, v109
	v_mul_f32_e32 v102, v102, v111
	v_mul_f32_e32 v87, v87, v109
	v_mul_f32_e32 v103, v103, v111
	v_fma_f32 v72, v72, v8, v24
	v_fma_f32 v88, v88, v8, v24
	v_fma_f32 v73, v73, v9, v25
	v_fma_f32 v89, v89, v9, v25
	v_fma_f32 v74, v74, v10, v26
	v_fma_f32 v90, v90, v10, v26
	v_fma_f32 v75, v75, v11, v27
	v_fma_f32 v91, v91, v11, v27
	v_fma_f32 v76, v76, v12, v28
	v_fma_f32 v92, v92, v12, v28
	v_fma_f32 v77, v77, v13, v29
	v_fma_f32 v93, v93, v13, v29
	v_fma_f32 v78, v78, v14, v30
	v_fma_f32 v94, v94, v14, v30
	v_fma_f32 v79, v79, v15, v31
	v_fma_f32 v95, v95, v15, v31
	v_fma_f32 v80, v80, v16, v32
	v_fma_f32 v96, v96, v16, v32
	v_fma_f32 v81, v81, v17, v33
	v_fma_f32 v97, v97, v17, v33
	v_fma_f32 v82, v82, v18, v34
	v_fma_f32 v98, v98, v18, v34
	v_fma_f32 v83, v83, v19, v35
	v_fma_f32 v99, v99, v19, v35
	v_fma_f32 v84, v84, v20, v36
	v_fma_f32 v100, v100, v20, v36
	v_fma_f32 v85, v85, v21, v37
	v_fma_f32 v101, v101, v21, v37
	v_fma_f32 v86, v86, v22, v38
	v_fma_f32 v102, v102, v22, v38
	v_fma_f32 v87, v87, v23, v39
	v_fma_f32 v103, v103, v23, v39
	s_lshl_b32 s2, s11, 12
	s_add_u32 s16, s20, s2
	s_addc_u32 s17, s21, 0
	s_lshl_b32 s10, s15, 12
	s_add_u32 s18, s16, s10
	s_addc_u32 s19, s17, 0
	s_cmp_eq_u32 s14, 0
	s_cbranch_scc1 .Llna_nof32_p1
	global_store_dwordx4 v4, v[72:75], s[16:17]
	global_store_dwordx4 v4, v[76:79], s[16:17] offset:1024
	global_store_dwordx4 v4, v[80:83], s[16:17] offset:2048
	global_store_dwordx4 v4, v[84:87], s[16:17] offset:3072
	global_store_dwordx4 v4, v[88:91], s[18:19]
	global_store_dwordx4 v4, v[92:95], s[18:19] offset:1024
	global_store_dwordx4 v4, v[96:99], s[18:19] offset:2048
	global_store_dwordx4 v4, v[100:103], s[18:19] offset:3072
.Llna_nof32_p1:
	v_cvt_pk_bf16_f32 v112, v72, v73
	v_cvt_pk_bf16_f32 v113, v74, v75
	v_cvt_pk_bf16_f32 v114, v76, v77
	v_cvt_pk_bf16_f32 v115, v78, v79
	v_cvt_pk_bf16_f32 v116, v80, v81
	v_cvt_pk_bf16_f32 v117, v82, v83
	v_cvt_pk_bf16_f32 v118, v84, v85
	v_cvt_pk_bf16_f32 v119, v86, v87
	v_cvt_pk_bf16_f32 v120, v88, v89
	v_cvt_pk_bf16_f32 v121, v90, v91
	v_cvt_pk_bf16_f32 v122, v92, v93
	v_cvt_pk_bf16_f32 v123, v94, v95
	v_cvt_pk_bf16_f32 v124, v96, v97
	v_cvt_pk_bf16_f32 v125, v98, v99
	v_cvt_pk_bf16_f32 v126, v100, v101
	v_cvt_pk_bf16_f32 v127, v102, v103
	s_lshl_b32 s2, s11, 11
	s_add_u32 s16, s8, s2
	s_addc_u32 s17, s9, 0
	s_lshl_b32 s10, s15, 11
	s_add_u32 s18, s16, s10
	s_addc_u32 s19, s17, 0
	global_store_dwordx2 v5, v[112:113], s[16:17]
	global_store_dwordx2 v5, v[114:115], s[16:17] offset:512
	global_store_dwordx2 v5, v[116:117], s[16:17] offset:1024
	global_store_dwordx2 v5, v[118:119], s[16:17] offset:1536
	global_store_dwordx2 v5, v[120:121], s[18:19]
	global_store_dwordx2 v5, v[122:123], s[18:19] offset:512
	global_store_dwordx2 v5, v[124:125], s[18:19] offset:1024
	global_store_dwordx2 v5, v[126:127], s[18:19] offset:1536
	s_lshl_b32 s2, s11, 3
	s_add_u32 s16, s22, s2
	s_addc_u32 s17, s23, 0
	s_lshl_b32 s10, s15, 3
	s_add_u32 s18, s16, s10
	s_addc_u32 s19, s17, 0
	s_mov_b64 exec, 1
	global_store_dwordx2 v1, v[108:109], s[16:17]
	global_store_dwordx2 v1, v[110:111], s[18:19]
	s_mov_b64 exec, -1
	s_lshl_b32 s10, s15, 1
	s_add_u32 s11, s11, s10
	s_cmpk_ge_u32 s11, 0x8000
	s_cbranch_scc1 .Llna_done
	s_lshl_b32 s10, s15, 1
	s_add_u32 s10, s11, s10
	s_cmpk_lt_u32 s10, 0x8000
	s_cselect_b32 s10, s10, s11
	s_lshl_b32 s2, s10, 12
	s_add_u32 s16, s20, s2
	s_addc_u32 s17, s21, 0
	s_lshl_b32 s10, s15, 12
	s_add_u32 s18, s16, s10
	s_addc_u32 s19, s17, 0
	global_load_dwordx4 v[72:75], v4, s[16:17]
	global_load_dwordx4 v[76:79], v4, s[16:17] offset:1024
	global_load_dwordx4 v[80:83], v4, s[16:17] offset:2048
	global_load_dwordx4 v[84:87], v4, s[16:17] offset:3072
	global_load_dwordx4 v[88:91], v4, s[18:19]
	global_load_dwordx4 v[92:95], v4, s[18:19] offset:1024
	global_load_dwordx4 v[96:99], v4, s[18:19] offset:2048
	global_load_dwordx4 v[100:103], v4, s[18:19] offset:3072
	s_cmp_eq_u32 s14, 0
	s_cbranch_scc1 .Llna_w1
	s_waitcnt vmcnt(26)
	s_branch .Llna_x1

; __device__ __forceinline__ void ln_phase(const PRef& P, const float* __restrict__ gw, const float* __restrict__ bw, bool write_f32) {
;     ...
;     for (int i = 0; i < 4; ++i) { v[0][i] = hp0[lane + 64 * i]; v[1][i] = hp1[lane + 64 * i]; }
; #pragma unroll
;     for (int i = 0; i < 4; ++i) { s0 += v[0][i].x + v[0][i].y + v[0][i].z + v[0][i].w; s1 += v[1][i].x + v[1][i].y + v[1][i].z + v[1][i].w; }
; #pragma unroll
;     for (int o = 32; o > 0; o >>= 1) { s0 += __shfl_xor(s0, o); s1 += __shfl_xor(s1, o); }
;     const float mu0 = s0 * (1.f / DM), mu1 = s1 * (1.f / DM); float q0 = 0.f, q1 = 0.f;
; #pragma unroll
;     for (int i = 0; i < 4; ++i) { float a = v[0][i].x - mu0, b = v[0][i].y - mu0, c = v[0][i].z - mu0, d = v[0][i].w - mu0; q0 += a * a + b * b + c * c + d * d;
;       float e = v[1][i].x - mu1, f = v[1][i].y - mu1, g = v[1][i].z - mu1, h = v[1][i].w - mu1; q1 += e * e + f * f + g * g + h * h; }
; #pragma unroll
;     for (int o = 32; o > 0; o >>= 1) { q0 += __shfl_xor(q0, o); q1 += __shfl_xor(q1, o); }
.Llna_x1:
	v_add_f32_e32 v104, v40, v41
	v_add_f32_e32 v105, v56, v57
	v_add_f32_e32 v104, v104, v42
	v_add_f32_e32 v105, v105, v58
	v_add_f32_e32 v104, v104, v43
	v_add_f32_e32 v105, v105, v59
	v_add_f32_e32 v104, v104, v44
	v_add_f32_e32 v105, v105, v60
	v_add_f32_e32 v104, v104, v45
	v_add_f32_e32 v105, v105, v61
	v_add_f32_e32 v104, v104, v46
	v_add_f32_e32 v105, v105, v62
	v_add_f32_e32 v104, v104, v47
	v_add_f32_e32 v105, v105, v63
	v_add_f32_e32 v104, v104, v48
	v_add_f32_e32 v105, v105, v64
	v_add_f32_e32 v104, v104, v49
	v_add_f32_e32 v105, v105, v65
	v_add_f32_e32 v104, v104, v50
	v_add_f32_e32 v105, v105, v66
	v_add_f32_e32 v104, v104, v51
	v_add_f32_e32 v105, v105, v67
	v_add_f32_e32 v104, v104, v52
	v_add_f32_e32 v105, v105, v68
	v_add_f32_e32 v104, v104, v53
	v_add_f32_e32 v105, v105, v69
	v_add_f32_e32 v104, v104, v54
	v_add_f32_e32 v105, v105, v70
	v_add_f32_e32 v104, v104, v55
	v_add_f32_e32 v105, v105, v71
	s_nop 1
	v_add_f32_dpp v104, v104, v104 quad_perm:[1,0,3,2] row_mask:0xf bank_mask:0xf
	v_add_f32_dpp v105, v105, v105 quad_perm:[1,0,3,2] row_mask:0xf bank_mask:0xf
	s_nop 1
	v_add_f32_dpp v104, v104, v104 quad_perm:[2,3,0,1] row_mask:0xf bank_mask:0xf
	v_add_f32_dpp v105, v105, v105 quad_perm:[2,3,0,1] row_mask:0xf bank_mask:0xf
	s_nop 1
	v_add_f32_dpp v104, v104, v104 row_half_mirror row_mask:0xf bank_mask:0xf
	v_add_f32_dpp v105, v105, v105 row_half_mirror row_mask:0xf bank_mask:0xf
	s_nop 1
	v_add_f32_dpp v104, v104, v104 row_mirror row_mask:0xf bank_mask:0xf
	v_add_f32_dpp v105, v105, v105 row_mirror row_mask:0xf bank_mask:0xf
	s_nop 1
	v_readlane_b32 s2, v104, 0
	v_readlane_b32 s10, v104, 16
	v_readlane_b32 s16, v104, 32
	v_readlane_b32 s17, v104, 48
	v_readlane_b32 s18, v105, 0
	v_readlane_b32 s19, v105, 16
	v_mov_b32_e32 v104, s2
	v_add_f32_e32 v104, s10, v104
	v_add_f32_e32 v104, s16, v104
	v_add_f32_e32 v104, s17, v104
	v_readlane_b32 s2, v105, 32
	v_readlane_b32 s10, v105, 48
	v_mov_b32_e32 v105, s18
	v_add_f32_e32 v105, s19, v105
	s_nop 0
	v_add_f32_e32 v105, s2, v105
	v_add_f32_e32 v105, s10, v105
	v_mul_f32_e32 v108, 0x3a800000, v104
	v_mul_f32_e32 v110, 0x3a800000, v105
	v_sub_f32_e32 v40, v40, v108
	v_sub_f32_e32 v56, v56, v110
	v_sub_f32_e32 v41, v41, v108
	v_sub_f32_e32 v57, v57, v110
	v_sub_f32_e32 v42, v42, v108
	v_sub_f32_e32 v58, v58, v110
	v_sub_f32_e32 v43, v43, v108
	v_sub_f32_e32 v59, v59, v110
	v_sub_f32_e32 v44, v44, v108
	v_sub_f32_e32 v60, v60, v110
	v_sub_f32_e32 v45, v45, v108
	v_sub_f32_e32 v61, v61, v110
	v_sub_f32_e32 v46, v46, v108
	v_sub_f32_e32 v62, v62, v110
	v_sub_f32_e32 v47, v47, v108
	v_sub_f32_e32 v63, v63, v110
	v_sub_f32_e32 v48, v48, v108
	v_sub_f32_e32 v64, v64, v110
	v_sub_f32_e32 v49, v49, v108
	v_sub_f32_e32 v65, v65, v110
	v_sub_f32_e32 v50, v50, v108
	v_sub_f32_e32 v66, v66, v110
	v_sub_f32_e32 v51, v51, v108
	v_sub_f32_e32 v67, v67, v110
	v_sub_f32_e32 v52, v52, v108
	v_sub_f32_e32 v68, v68, v110
	v_sub_f32_e32 v53, v53, v108
	v_sub_f32_e32 v69, v69, v110
	v_sub_f32_e32 v54, v54, v108
	v_sub_f32_e32 v70, v70, v110
	v_sub_f32_e32 v55, v55, v108
	v_sub_f32_e32 v71, v71, v110
	v_mul_f32_e32 v106, v40, v40
	v_mul_f32_e32 v107, v56, v56
	v_fmac_f32_e32 v106, v41, v41
	v_fmac_f32_e32 v107, v57, v57
	v_fmac_f32_e32 v106, v42, v42
	v_fmac_f32_e32 v107, v58, v58
	v_fmac_f32_e32 v106, v43, v43
	v_fmac_f32_e32 v107, v59, v59
	v_fmac_f32_e32 v106, v44, v44
	v_fmac_f32_e32 v107, v60, v60
	v_fmac_f32_e32 v106, v45, v45
	v_fmac_f32_e32 v107, v61, v61
	v_fmac_f32_e32 v106, v46, v46
	v_fmac_f32_e32 v107, v62, v62
	v_fmac_f32_e32 v106, v47, v47
	v_fmac_f32_e32 v107, v63, v63
	v_fmac_f32_e32 v106, v48, v48
	v_fmac_f32_e32 v107, v64, v64
	v_fmac_f32_e32 v106, v49, v49
	v_fmac_f32_e32 v107, v65, v65
	v_fmac_f32_e32 v106, v50, v50
	v_fmac_f32_e32 v107, v66, v66
	v_fmac_f32_e32 v106, v51, v51
	v_fmac_f32_e32 v107, v67, v67
	v_fmac_f32_e32 v106, v52, v52
	v_fmac_f32_e32 v107, v68, v68
	v_fmac_f32_e32 v106, v53, v53
	v_fmac_f32_e32 v107, v69, v69
	v_fmac_f32_e32 v106, v54, v54
	v_fmac_f32_e32 v107, v70, v70
	v_fmac_f32_e32 v106, v55, v55
	v_fmac_f32_e32 v107, v71, v71
	s_nop 1
	v_add_f32_dpp v106, v106, v106 quad_perm:[1,0,3,2] row_mask:0xf bank_mask:0xf
	v_add_f32_dpp v107, v107, v107 quad_perm:[1,0,3,2] row_mask:0xf bank_mask:0xf
	s_nop 1
	v_add_f32_dpp v106, v106, v106 quad_perm:[2,3,0,1] row_mask:0xf bank_mask:0xf
	v_add_f32_dpp v107, v107, v107 quad_perm:[2,3,0,1] row_mask:0xf bank_mask:0xf
	s_nop 1
	v_add_f32_dpp v106, v106, v106 row_half_mirror row_mask:0xf bank_mask:0xf
	v_add_f32_dpp v107, v107, v107 row_half_mirror row_mask:0xf bank_mask:0xf
	s_nop 1
	v_add_f32_dpp v106, v106, v106 row_mirror row_mask:0xf bank_mask:0xf
	v_add_f32_dpp v107, v107, v107 row_mirror row_mask:0xf bank_mask:0xf
	s_nop 1
	v_readlane_b32 s2, v106, 0
	v_readlane_b32 s10, v106, 16
; __device__ __forceinline__ unsigned pk2(float a, float b) { unsigned r; asm("v_cvt_pk_bf16_f32 %0, %1, %2" : "=v"(r) : "v"(a), "v"(b)); return r; }
; __device__ __forceinline__ void ln_phase(const PRef& P, const float* __restrict__ gw, const float* __restrict__ bw, bool write_f32) {
;     ...
;     const float rs0 = rsqrtf(q0 * (1.f / DM) + 1e-5f), rs1 = rsqrtf(q1 * (1.f / DM) + 1e-5f);
;     if (lane == 0) { st[row] = make_float2(mu0, rs0); st[row + nw] = make_float2(mu1, rs1); }
; #pragma unroll
;     for (int i = 0; i < 4; ++i) { float4 g4 = ((const float4*)gw)[lane + 64 * i], b4 = ((const float4*)bw)[lane + 64 * i]; float4 o4, p4;
;       o4.x = (v[0][i].x - mu0) * rs0 * g4.x + b4.x; o4.y = (v[0][i].y - mu0) * rs0 * g4.y + b4.y; o4.z = (v[0][i].z - mu0) * rs0 * g4.z + b4.z; o4.w = (v[0][i].w - mu0) * rs0 * g4.w + b4.w;
;       p4.x = (v[1][i].x - mu1) * rs1 * g4.x + b4.x; p4.y = (v[1][i].y - mu1) * rs1 * g4.y + b4.y; p4.z = (v[1][i].z - mu1) * rs1 * g4.z + b4.z; p4.w = (v[1][i].w - mu1) * rs1 * g4.w + b4.w;
;       if (write_f32) { hp0[lane + 64 * i] = o4; hp1[lane + 64 * i] = p4; }
;       ((u32x2*)(hb + (long)row * DM))[lane + 64 * i] = u32x2{pk2(o4.x, o4.y), pk2(o4.z, o4.w)};
;       ((u32x2*)(hb + (long)(row + nw) * DM))[lane + 64 * i] = u32x2{pk2(p4.x, p4.y), pk2(p4.z, p4.w)}; }
;   }
	v_readlane_b32 s16, v106, 32
	v_readlane_b32 s17, v106, 48
	v_readlane_b32 s18, v107, 0
	v_readlane_b32 s19, v107, 16
	v_mov_b32_e32 v106, s2
	v_add_f32_e32 v106, s10, v106
	v_add_f32_e32 v106, s16, v106
	v_add_f32_e32 v106, s17, v106
	v_readlane_b32 s2, v107, 32
	v_readlane_b32 s10, v107, 48
	v_mov_b32_e32 v107, s18
	v_add_f32_e32 v107, s19, v107
	s_nop 0
	v_add_f32_e32 v107, s2, v107
	v_add_f32_e32 v107, s10, v107
	v_mul_f32_e32 v106, 0x3a800000, v106
	v_mul_f32_e32 v107, 0x3a800000, v107
	v_add_f32_e32 v106, 0x3727c5ac, v106
	v_add_f32_e32 v107, 0x3727c5ac, v107
	v_rsq_f32_e32 v109, v106
	v_rsq_f32_e32 v111, v107
	s_nop 0
	v_mul_f32_e32 v40, v40, v109
	v_mul_f32_e32 v56, v56, v111
	v_mul_f32_e32 v41, v41, v109
	v_mul_f32_e32 v57, v57, v111
	v_mul_f32_e32 v42, v42, v109
	v_mul_f32_e32 v58, v58, v111
	v_mul_f32_e32 v43, v43, v109
	v_mul_f32_e32 v59, v59, v111
	v_mul_f32_e32 v44, v44, v109
	v_mul_f32_e32 v60, v60, v111
	v_mul_f32_e32 v45, v45, v109
	v_mul_f32_e32 v61, v61, v111
	v_mul_f32_e32 v46, v46, v109
	v_mul_f32_e32 v62, v62, v111
	v_mul_f32_e32 v47, v47, v109
	v_mul_f32_e32 v63, v63, v111
	v_mul_f32_e32 v48, v48, v109
	v_mul_f32_e32 v64, v64, v111
	v_mul_f32_e32 v49, v49, v109
	v_mul_f32_e32 v65, v65, v111
	v_mul_f32_e32 v50, v50, v109
	v_mul_f32_e32 v66, v66, v111
	v_mul_f32_e32 v51, v51, v109
	v_mul_f32_e32 v67, v67, v111
	v_mul_f32_e32 v52, v52, v109
	v_mul_f32_e32 v68, v68, v111
	v_mul_f32_e32 v53, v53, v109
	v_mul_f32_e32 v69, v69, v111
	v_mul_f32_e32 v54, v54, v109
	v_mul_f32_e32 v70, v70, v111
	v_mul_f32_e32 v55, v55, v109
	v_mul_f32_e32 v71, v71, v111
	v_fma_f32 v40, v40, v8, v24
	v_fma_f32 v56, v56, v8, v24
	v_fma_f32 v41, v41, v9, v25
	v_fma_f32 v57, v57, v9, v25
	v_fma_f32 v42, v42, v10, v26
	v_fma_f32 v58, v58, v10, v26
	v_fma_f32 v43, v43, v11, v27
	v_fma_f32 v59, v59, v11, v27
	v_fma_f32 v44, v44, v12, v28
	v_fma_f32 v60, v60, v12, v28
	v_fma_f32 v45, v45, v13, v29
	v_fma_f32 v61, v61, v13, v29
	v_fma_f32 v46, v46, v14, v30
	v_fma_f32 v62, v62, v14, v30
	v_fma_f32 v47, v47, v15, v31
	v_fma_f32 v63, v63, v15, v31
	v_fma_f32 v48, v48, v16, v32
	v_fma_f32 v64, v64, v16, v32
	v_fma_f32 v49, v49, v17, v33
	v_fma_f32 v65, v65, v17, v33
	v_fma_f32 v50, v50, v18, v34
	v_fma_f32 v66, v66, v18, v34
	v_fma_f32 v51, v51, v19, v35
	v_fma_f32 v67, v67, v19, v35
	v_fma_f32 v52, v52, v20, v36
	v_fma_f32 v68, v68, v20, v36
	v_fma_f32 v53, v53, v21, v37
	v_fma_f32 v69, v69, v21, v37
	v_fma_f32 v54, v54, v22, v38
	v_fma_f32 v70, v70, v22, v38
	v_fma_f32 v55, v55, v23, v39
	v_fma_f32 v71, v71, v23, v39
	s_lshl_b32 s2, s11, 12
	s_add_u32 s16, s20, s2
	s_addc_u32 s17, s21, 0
	s_lshl_b32 s10, s15, 12
	s_add_u32 s18, s16, s10
	s_addc_u32 s19, s17, 0
	s_cmp_eq_u32 s14, 0
	s_cbranch_scc1 .Llna_nof32_p2
	global_store_dwordx4 v4, v[40:43], s[16:17]
	global_store_dwordx4 v4, v[44:47], s[16:17] offset:1024
	global_store_dwordx4 v4, v[48:51], s[16:17] offset:2048
	global_store_dwordx4 v4, v[52:55], s[16:17] offset:3072
	global_store_dwordx4 v4, v[56:59], s[18:19]
	global_store_dwordx4 v4, v[60:63], s[18:19] offset:1024
	global_store_dwordx4 v4, v[64:67], s[18:19] offset:2048
	global_store_dwordx4 v4, v[68:71], s[18:19] offset:3072
.Llna_nof32_p2:
	v_cvt_pk_bf16_f32 v112, v40, v41
	v_cvt_pk_bf16_f32 v113, v42, v43
	v_cvt_pk_bf16_f32 v114, v44, v45
	v_cvt_pk_bf16_f32 v115, v46, v47
	v_cvt_pk_bf16_f32 v116, v48, v49
	v_cvt_pk_bf16_f32 v117, v50, v51
	v_cvt_pk_bf16_f32 v118, v52, v53
	v_cvt_pk_bf16_f32 v119, v54, v55
	v_cvt_pk_bf16_f32 v120, v56, v57
	v_cvt_pk_bf16_f32 v121, v58, v59
	v_cvt_pk_bf16_f32 v122, v60, v61
	v_cvt_pk_bf16_f32 v123, v62, v63
	v_cvt_pk_bf16_f32 v124, v64, v65
	v_cvt_pk_bf16_f32 v125, v66, v67
	v_cvt_pk_bf16_f32 v126, v68, v69
	v_cvt_pk_bf16_f32 v127, v70, v71
	s_lshl_b32 s2, s11, 11
	s_add_u32 s16, s8, s2
	s_addc_u32 s17, s9, 0
	s_lshl_b32 s10, s15, 11
	s_add_u32 s18, s16, s10
	s_addc_u32 s19, s17, 0
	global_store_dwordx2 v5, v[112:113], s[16:17]
	global_store_dwordx2 v5, v[114:115], s[16:17] offset:512
	global_store_dwordx2 v5, v[116:117], s[16:17] offset:1024
	global_store_dwordx2 v5, v[118:119], s[16:17] offset:1536
	global_store_dwordx2 v5, v[120:121], s[18:19]
	global_store_dwordx2 v5, v[122:123], s[18:19] offset:512
	global_store_dwordx2 v5, v[124:125], s[18:19] offset:1024
	global_store_dwordx2 v5, v[126:127], s[18:19] offset:1536
	s_lshl_b32 s2, s11, 3
	s_add_u32 s16, s22, s2
	s_addc_u32 s17, s23, 0
	s_lshl_b32 s10, s15, 3
	s_add_u32 s18, s16, s10
	s_addc_u32 s19, s17, 0
	s_mov_b64 exec, 1
	global_store_dwordx2 v1, v[108:109], s[16:17]
	global_store_dwordx2 v1, v[110:111], s[18:19]
	s_mov_b64 exec, -1
	s_branch .Llna_loop
.Llna_done:
	s_waitcnt vmcnt(0)
	v_readlane_b32 s20, v255, 1
	v_readlane_b32 s22, v255, 3
	v_readlane_b32 s21, v255, 2
	v_readlane_b32 s23, v255, 4
	s_movk_i32 s24, 0x7fff

; __device__ __forceinline__ int otid() { int t = threadIdx.x; asm volatile("" : "+v"(t)); return t; }
; __device__ __forceinline__ int v_st(int k, int c) { const int kk = (k & ~0xC) | ((k & 4) << 1) | ((k & 8) >> 1); return ((kk >> 3) * 4 + (c >> 5)) * 512 + ((kk & 7) * 32 + (c & 31)) * 2; }
; __device__ __forceinline__ int v_rd_base(int lane) { return ((lane & 3) << 3) | (((lane >> 2) & 3) << 6) | (((lane >> 4) & 1) << 5) | (((lane >> 5) & 1) << 8); }
; #define SLOAD(k0) do { vs0 = *(const bf16x8*)(Vh + (long)((k0) + sr) * 128 + sc); vs1 = *(const bf16x8*)(Vh + (long)((k0) + 32 + sr) * 128 + sc); \
;     const bfr* kp_ = Kh + (long)((k0) + krow) * 192 + (kcb >> 1); ks0 = *(const bf16x8*)(kp_); ks1 = *(const bf16x8*)(kp_ + 64); ks2 = *(const bf16x8*)(kp_ + 128); } while (0)
; #define SWAIT() asm volatile("s_waitcnt vmcnt(0)" ::: "memory")
; __device__ __forceinline__ void attn_body(const bfr* __restrict__ Qb, const bfr* __restrict__ Kh, const bfr* __restrict__ Vh, bfr* __restrict__ Ob, int seq) {
;   char* lds = g_lds;
;   const int tid = otid(), wid = tid >> 6, lane = tid & 63, r32 = lane & 31, hi = lane >> 5;
;   char* V_lds = lds; char* K_lds = lds + 2 * A_SHM_V;
;   float* wsf = (float*)(lds + 2 * A_SHM_V + 2 * A_SHM_K) + wid * 64; float* li_l = wsf; float* al_l = wsf + 32;
;   float m_reg = -1e30f, l_reg = 0; f32x16 o[4]; bf16x8 qr[8];
;   char* qpe = lds + 2 * A_SHM_V + 2 * A_SHM_K + 2048 + wid * 4096 + lane * 16;
; #pragma unroll
;   for (int d = 0; d < 4; ++d)
; #pragma unroll
;     for (int r = 0; r < 16; ++r) o[d][r] = 0.f;
;   const bfr* Qw = Qb + (long)(wid * 32 + r32) * 192 + hi * 8;
; #pragma unroll
;   for (int d0 = 0; d0 < 8; ++d0) qr[d0] = *reinterpret_cast<const bf16x8*>(Qw + d0 * 16);
;   __syncthreads();
; #pragma unroll
;   for (int d0 = 8; d0 < 12; ++d0) *reinterpret_cast<bf16x8*>(qpe + (d0 - 8) * 1024) = *reinterpret_cast<const bf16x8*>(Qw + d0 * 16);
;   const int sr = tid >> 4, sc = (tid & 15) * 8, vst0 = v_st(sr, sc), vst1 = v_st(32 + sr, sc);
;   const int krow = tid >> 3, kcb = (tid & 7) * 16;
;   const int vb0 = (int)(uintptr_t)(lds_u32*)V_lds + v_rd_base(lane);
;   const int kst = KSWZ(krow, kcb);
;   bf16x8 vs0, vs1, ks0, ks1, ks2;
;     ...
;   f32x16 pA0, pA1, pB0, pB1; float mnA, mnB, alA, alB; bf16x8 pa0, pa1, pa2, pa3; const int NT = seq / 64;
;   __syncthreads();
;   SLOAD(0); SWAIT(); SWRITE(0); __syncthreads();
.LBB0_804:
	s_ashr_i32 s2, s16, 6
	s_add_i32 s12, s2, s24
	s_ashr_i32 s13, s12, 31
	s_lshl_b32 s2, s16, 8
	s_lshl_b64 s[8:9], s[12:13], 14
	s_and_b32 s26, s2, 0x3f00
	s_or_b32 s2, s8, s26
	s_mul_i32 s8, s9, 0x180
	s_mul_hi_u32 s9, s2, 0x180
	s_add_i32 s9, s9, s8
	s_mulk_i32 s2, 0x180
	v_mov_b32_e32 v60, v182
	s_add_u32 s8, s18, s2
	s_addc_u32 s9, s19, s9
	v_ashrrev_i32_e32 v18, 6, v60
	v_and_b32_e32 v164, 31, v60
	v_lshlrev_b32_e32 v154, 5, v18
	v_bfe_u32 v165, v60, 5, 1
	v_or_b32_e32 v0, v154, v164
	v_mov_b64_e32 v[2:3], s[8:9]
	s_movk_i32 s28, 0x180
	v_mad_i64_i32 v[2:3], s[8:9], v0, s28, v[2:3]
	v_lshlrev_b32_e32 v0, 4, v165
	v_lshl_add_u64 v[14:15], v[2:3], 0, v[0:1]
	global_load_dwordx4 v[126:129], v[14:15], off
	global_load_dwordx4 v[122:125], v[14:15], off offset:32
	global_load_dwordx4 v[118:121], v[14:15], off offset:64
	global_load_dwordx4 v[114:117], v[14:15], off offset:96
	global_load_dwordx4 v[110:113], v[14:15], off offset:128
	global_load_dwordx4 v[106:109], v[14:15], off offset:160
	global_load_dwordx4 v[102:105], v[14:15], off offset:192
	global_load_dwordx4 v[98:101], v[14:15], off offset:224
	s_waitcnt vmcnt(0) lgkmcnt(0)
	s_barrier
	global_load_dwordx4 v[2:5], v[14:15], off offset:256
	global_load_dwordx4 v[6:9], v[14:15], off offset:288
	global_load_dwordx4 v[10:13], v[14:15], off offset:320
	s_nop 0
	global_load_dwordx4 v[14:17], v[14:15], off offset:352
	s_mul_i32 s8, s12, 0x600000
	s_mul_hi_i32 s2, s12, 0x600000
	v_ashrrev_i32_e32 v22, 4, v60
	s_add_u32 s8, s20, s8
	v_add_u32_e32 v24, 32, v22
	s_addc_u32 s9, s21, s2
	s_lshl_b64 s[10:11], s[12:13], 22
	v_lshlrev_b32_e32 v30, 3, v60
	v_ashrrev_i32_e32 v23, 31, v22
	v_ashrrev_i32_e32 v25, 31, v24
	s_add_u32 s14, s22, s10
	v_and_b32_e32 v61, 63, v60
	v_lshl_add_u32 v171, v18, 12, v220
	v_and_b32_e32 v18, 0x78, v30
	v_lshlrev_b64 v[50:51], 8, v[22:23]
	v_lshlrev_b64 v[20:21], 8, v[24:25]
	s_addc_u32 s15, s23, s11
	v_mov_b32_e32 v19, v1
	v_lshlrev_b32_e32 v31, 4, v60
	v_ashrrev_i32_e32 v78, 3, v60
	v_lshlrev_b32_e32 v170, 4, v61
	v_lshlrev_b32_e32 v18, 1, v18
	v_mov_b64_e32 v[58:59], s[8:9]
	v_lshl_add_u64 v[28:29], s[14:15], 0, v[50:51]
	v_lshl_add_u64 v[20:21], s[14:15], 0, v[20:21]
	v_mov_b32_e32 v55, v1
	v_and_b32_e32 v54, 0x70, v31
	v_or_b32_e32 v79, v171, v170
	v_mad_i64_i32 v[26:27], s[8:9], v78, s28, v[58:59]
	v_lshl_add_u64 v[56:57], v[28:29], 0, v[18:19]
	v_lshl_add_u64 v[18:19], v[20:21], 0, v[18:19]
	v_lshl_add_u64 v[26:27], v[26:27], 0, v[54:55]
	v_and_b32_e32 v23, 0xfffff0, v22
	v_lshlrev_b32_e32 v25, 1, v22
	v_and_or_b32 v23, v25, 8, v23
	v_and_b32_e32 v25, 0xfffff0, v24
	v_lshlrev_b32_e32 v24, 1, v24
	v_lshrrev_b32_e32 v23, 1, v23
	v_and_or_b32 v24, v24, 8, v25
	v_lshrrev_b32_e32 v24, 1, v24
	v_and_b32_e32 v28, 48, v31
	v_mul_u32_u24_e32 v62, 0x180, v164
	v_and_b32_e32 v80, 0x70, v30
	v_xor_b32_e32 v29, v31, v60
	v_mad_i64_i32 v[52:53], s[8:9], v78, s28, 0
	s_movk_i32 s2, 0x70
	v_bitop3_b32 v172, v0, v62, v80 bitop3:0xde
	v_and_or_b32 v173, v29, s2, v52
	v_or_b32_e32 v81, 32, v0
	v_bitop3_b32 v176, v81, v62, v80 bitop3:0xde
	v_or_b32_e32 v82, 64, v0
	v_bitop3_b32 v177, v82, v62, v80 bitop3:0xde
	v_or_b32_e32 v83, 0x60, v0
	v_bitop3_b32 v178, v83, v62, v80 bitop3:0xde
	s_movk_i32 s2, 0x80
	v_bitop3_b32 v84, v0, v80, s2 bitop3:0x36
	v_mad_u32_u24 v181, v164, s28, v84
	s_movk_i32 s2, 0xa0
	v_bitop3_b32 v85, v0, v80, s2 bitop3:0x36
	s_waitcnt vmcnt(3)
	ds_write_b128 v79, v[2:5]
	s_waitcnt vmcnt(2)
	ds_write_b128 v79, v[6:9] offset:1024
	s_waitcnt vmcnt(1)
	ds_write_b128 v79, v[10:13] offset:2048
	s_waitcnt vmcnt(0)
	ds_write_b128 v79, v[14:17] offset:3072
	s_waitcnt lgkmcnt(0)
	s_barrier
	global_load_dwordx4 v[2:5], v[56:57], off
	global_load_dwordx4 v[6:9], v[18:19], off
	global_load_dwordx4 v[10:13], v[26:27], off
	global_load_dwordx4 v[14:17], v[26:27], off offset:128
	s_nop 0
	global_load_dwordx4 v[18:21], v[26:27], off offset:256
	v_lshrrev_b32_e32 v26, 1, v22
	v_bfe_u32 v27, v30, 5, 2
	v_and_b32_e32 v22, 3, v22
	v_and_or_b32 v22, v26, 4, v22
	v_or_b32_e32 v23, v23, v27
	v_lshlrev_b32_e32 v22, 6, v22
	v_lshlrev_b32_e32 v23, 9, v23
	v_or_b32_e32 v24, v24, v27
	v_or3_b32 v174, v23, v22, v28
	v_lshlrev_b32_e32 v23, 9, v24
	v_or3_b32 v175, v23, v22, v28
	s_waitcnt vmcnt(0)
	v_mad_u32_u24 v185, v164, s28, v85
	s_movk_i32 s8, 0xc0
	v_bitop3_b32 v86, v0, v80, s8 bitop3:0x36
	v_mad_u32_u24 v179, v164, s28, v86
	s_movk_i32 s2, 0xe0
	v_bitop3_b32 v87, v0, v80, s2 bitop3:0x36
	v_mad_u32_u24 v180, v164, s28, v87
	s_movk_i32 s2, 0x100
	v_bitop3_b32 v88, v0, v80, s2 bitop3:0x36
	v_mad_u32_u24 v188, v164, s28, v88
	s_movk_i32 s2, 0x120
	v_bitop3_b32 v91, v0, v80, s2 bitop3:0x36
	v_mad_u32_u24 v192, v164, s28, v91
	s_movk_i32 s2, 0x140
	v_bitop3_b32 v93, v0, v80, s2 bitop3:0x36
	v_mad_u32_u24 v193, v164, s28, v93
	v_and_b32_e32 v89, 0x3fffffc0, v60
	v_lshl_add_u32 v155, v89, 2, v219
	v_lshlrev_b32_e32 v89, 3, v61
	v_bitop3_b32 v94, v0, v80, s95 bitop3:0x36
	v_mad_u32_u24 v195, v164, s28, v94
	v_add_u32_e32 v78, 64, v78
	s_movk_i32 s2, 0x6000
	v_mad_u32_u24 v92, v164, s28, v221
	v_bitop3_b32 v204, v0, v92, v80 bitop3:0xde
	v_bitop3_b32 v206, v81, v92, v80 bitop3:0xde
	v_bitop3_b32 v205, v82, v92, v80 bitop3:0xde
	v_bitop3_b32 v203, v83, v92, v80 bitop3:0xde
	v_add_u32_e32 v202, v84, v92
	v_add_u32_e32 v201, v85, v92
	s_mov_b32 s68, s69
	s_mov_b32 s70, s69
	s_mov_b32 s71, s69
	s_mov_b32 s72, s69
	s_mov_b32 s73, s69
	s_mov_b32 s74, s69
	s_mov_b32 s75, s69
	s_mov_b32 s76, s69
	s_mov_b32 s77, s69
	s_mov_b32 s78, s69
	s_mov_b32 s79, s69
	s_mov_b32 s80, s69
	s_mov_b32 s81, s69
	s_mov_b32 s82, s69
	s_mov_b32 s83, s69
	s_waitcnt vmcnt(4)
	ds_write_b128 v174, v[2:5]
	s_waitcnt vmcnt(3)
	ds_write_b128 v175, v[6:9]
	s_waitcnt vmcnt(2)
	ds_write_b128 v173, v[10:13] offset:32768
	s_waitcnt vmcnt(1)
	ds_write_b128 v173, v[14:17] offset:32896
	s_waitcnt vmcnt(0)
	ds_write_b128 v173, v[18:21] offset:33024
	s_waitcnt lgkmcnt(0)
	s_barrier
; #define SLOAD(k0) do { vs0 = *(const bf16x8*)(Vh + (long)((k0) + sr) * 128 + sc); vs1 = *(const bf16x8*)(Vh + (long)((k0) + 32 + sr) * 128 + sc); \
;     const bfr* kp_ = Kh + (long)((k0) + krow) * 192 + (kcb >> 1); ks0 = *(const bf16x8*)(kp_); ks1 = *(const bf16x8*)(kp_ + 64); ks2 = *(const bf16x8*)(kp_ + 128); } while (0)
; #define SWRITE(bq) do { *(bf16x8*)(V_lds + (bq) * A_SHM_V + vst0) = vs0; *(bf16x8*)(V_lds + (bq) * A_SHM_V + vst1) = vs1;    \
;     *(bf16x8*)(K_lds + (bq) * A_SHM_K + kst) = ks0; *(bf16x8*)(K_lds + (bq) * A_SHM_K + kst + 128) = ks1; *(bf16x8*)(K_lds + (bq) * A_SHM_K + kst + 256) = ks2; } while (0)
; #define SWAIT() asm volatile("s_waitcnt vmcnt(0)" ::: "memory")
; __device__ __forceinline__ void qkt(f32x16& p0, f32x16& p1, const char* Ks, const bf16x8* qr, const char* qpe, int r32, int hi) {
; #pragma unroll
;   for (int r = 0; r < 16; ++r) { p0[r] = 0.f; p1[r] = 0.f; }
; #pragma unroll
;   for (int d0 = 0; d0 < 12; ++d0) { int cb = (d0 * 16 + hi * 8) * 2;
;     bf16x8 b0 = *reinterpret_cast<const bf16x8*>(Ks + KSWZ(r32, cb));
;     bf16x8 b1 = *reinterpret_cast<const bf16x8*>(Ks + KSWZ(32 + r32, cb));
;     bf16x8 qv; if (d0 < 8) qv = qr[d0]; else qv = *reinterpret_cast<const bf16x8*>(qpe + (d0 - 8) * 1024);
;     p0 = __builtin_amdgcn_mfma_f32_32x32x16_bf16(b0, qv, p0, 0, 0, 0);
;     p1 = __builtin_amdgcn_mfma_f32_32x32x16_bf16(b1, qv, p1, 0, 0, 0); }
; __device__ __forceinline__ void attn_body(const bfr* __restrict__ Qb, const bfr* __restrict__ Kh, const bfr* __restrict__ Vh, bfr* __restrict__ Ob, int seq) {
;     ...
;   qkt(pA0, pA1, K_lds, qr, qpe, r32, hi); partialSM(pA0, pA1, m_reg, mnA, alA);
;   SLOAD(64); SWAIT(); SWRITE(1); __syncthreads();
	ds_read_b128 v[2:5], v172 offset:32768
	ds_read_b128 v[6:9], v172 offset:45056
	s_waitcnt lgkmcnt(1)
	v_mfma_f32_32x32x16_bf16 v[18:33], v[2:5], v[126:129], 0
	v_lshl_add_u64 v[156:157], s[10:11], 0, v[50:51]
	v_mad_i64_i32 v[158:159], s[10:11], s12, v223, v[52:53]
	v_add_u32_e32 v200, v86, v92
	v_add_u32_e32 v199, v87, v92
	v_add_u32_e32 v198, v88, v92
	v_add_u32_e32 v197, v91, v92
	s_waitcnt lgkmcnt(0)
	v_mfma_f32_32x32x16_bf16 v[34:49], v[6:9], v[126:129], 0
	ds_read_b128 v[2:5], v176 offset:32768
	ds_read_b128 v[6:9], v176 offset:45056
	v_add_u32_e32 v196, v93, v92
	v_add_u32_e32 v194, v94, v92
	v_lshl_or_b32 v166, v164, 2, v155
	v_mov_b32_e32 v167, 0
	s_mov_b32 s13, -1
	s_mov_b32 s31, 0x19008000
	s_waitcnt lgkmcnt(1)
	v_mfma_f32_32x32x16_bf16 v[18:33], v[2:5], v[122:125], v[18:33]
	s_mov_b32 s34, 0x1900a000
	s_mov_b32 s35, 0x1300c000
	s_mov_b32 s36, 0x1900c000
	s_mov_b32 s37, 0x1900e000
	s_mov_b32 s38, 0x13012000
	s_mov_b64 s[40:41], 0x8000
	s_mov_b64 s[42:43], 0xc000
	s_waitcnt lgkmcnt(0)
	v_mfma_f32_32x32x16_bf16 v[34:49], v[6:9], v[122:125], v[34:49]
	ds_read_b128 v[2:5], v177 offset:32768
	ds_read_b128 v[6:9], v177 offset:45056
	s_waitcnt lgkmcnt(1)
	v_mfma_f32_32x32x16_bf16 v[18:33], v[2:5], v[118:121], v[18:33]
	s_waitcnt lgkmcnt(0)
	v_mfma_f32_32x32x16_bf16 v[34:49], v[6:9], v[118:121], v[34:49]
	ds_read_b128 v[2:5], v178 offset:32768
	ds_read_b128 v[6:9], v178 offset:45056
	s_waitcnt lgkmcnt(1)
	v_mfma_f32_32x32x16_bf16 v[18:33], v[2:5], v[114:117], v[18:33]
	s_waitcnt lgkmcnt(0)
	v_mfma_f32_32x32x16_bf16 v[34:49], v[6:9], v[114:117], v[34:49]
	ds_read_b128 v[2:5], v181 offset:32768
	ds_read_b128 v[6:9], v181 offset:45056
	s_waitcnt lgkmcnt(1)
	v_mfma_f32_32x32x16_bf16 v[18:33], v[2:5], v[110:113], v[18:33]
	s_waitcnt lgkmcnt(0)
	v_mfma_f32_32x32x16_bf16 v[34:49], v[6:9], v[110:113], v[34:49]
	ds_read_b128 v[2:5], v185 offset:32768
	ds_read_b128 v[6:9], v185 offset:45056
	s_waitcnt lgkmcnt(1)
	v_mfma_f32_32x32x16_bf16 v[18:33], v[2:5], v[106:109], v[18:33]
	s_waitcnt lgkmcnt(0)
	v_mfma_f32_32x32x16_bf16 v[34:49], v[6:9], v[106:109], v[34:49]
	ds_read_b128 v[2:5], v179 offset:32768
	ds_read_b128 v[6:9], v179 offset:45056
	ds_read_b128 v[62:65], v188 offset:32768
	ds_read_b128 v[66:69], v79
	s_waitcnt lgkmcnt(3)
	v_mfma_f32_32x32x16_bf16 v[18:33], v[2:5], v[102:105], v[18:33]
	ds_read_b128 v[2:5], v180 offset:32768
	s_waitcnt lgkmcnt(3)
	v_mfma_f32_32x32x16_bf16 v[34:49], v[6:9], v[102:105], v[34:49]
	ds_read_b128 v[6:9], v180 offset:45056
	ds_read_b128 v[70:73], v188 offset:45056
	ds_read_b128 v[74:77], v79 offset:1024
	s_waitcnt lgkmcnt(3)
	v_mfma_f32_32x32x16_bf16 v[18:33], v[2:5], v[98:101], v[18:33]
	s_waitcnt lgkmcnt(2)
	v_mfma_f32_32x32x16_bf16 v[34:49], v[6:9], v[98:101], v[34:49]
	v_mov_b64_e32 v[2:3], s[68:69]
	v_mov_b64_e32 v[16:17], s[82:83]
	v_mov_b64_e32 v[4:5], s[70:71]
	v_mov_b64_e32 v[6:7], s[72:73]
	v_mov_b64_e32 v[8:9], s[74:75]
	v_mov_b64_e32 v[10:11], s[76:77]
	v_mov_b64_e32 v[12:13], s[78:79]
	v_mfma_f32_32x32x16_bf16 v[18:33], v[62:65], v[66:69], v[18:33]
	v_lshlrev_b32_e32 v62, 1, v60
	v_and_b32_e32 v90, 32, v62
	ds_read_b128 v[62:65], v192 offset:32768
	v_mov_b64_e32 v[14:15], s[80:81]
	s_waitcnt lgkmcnt(2)
	v_mfma_f32_32x32x16_bf16 v[34:49], v[70:73], v[66:69], v[34:49]
	ds_read_b128 v[66:69], v192 offset:45056
	v_and_b32_e32 v70, 24, v89
	v_and_or_b32 v95, v170, s8, v70
	v_mad_i64_i32 v[58:59], s[8:9], v78, s28, v[58:59]
	v_lshl_add_u64 v[58:59], v[58:59], 0, v[54:55]
	v_add_co_u32_e32 v54, vcc, s27, v56
	s_waitcnt lgkmcnt(0)
	v_mfma_f32_32x32x16_bf16 v[34:49], v[66:69], v[74:77], v[34:49]
	ds_read_b128 v[66:69], v79 offset:2048
	v_addc_co_u32_e32 v55, vcc, 0, v57, vcc
	v_and_b32_e32 v89, 0x100, v89
	v_or3_b32 v169, v95, v90, v89
	v_cmp_gt_u32_e64 s[8:9], 32, v61
	v_or_b32_e32 v168, 0x4000, v169
	v_mfma_f32_32x32x16_bf16 v[18:33], v[62:65], v[74:77], v[18:33]
	ds_read_b128 v[62:65], v193 offset:32768
	ds_read_b128 v[70:73], v193 offset:45056
	ds_read_b128 v[74:77], v79 offset:3072
	s_movk_i32 s27, 0x4000
	s_waitcnt lgkmcnt(2)
	v_mfma_f32_32x32x16_bf16 v[18:33], v[62:65], v[66:69], v[18:33]
	ds_read_b128 v[62:65], v195 offset:32768
	s_waitcnt lgkmcnt(2)
	v_mfma_f32_32x32x16_bf16 v[34:49], v[70:73], v[66:69], v[34:49]
	ds_read_b128 v[66:69], v195 offset:45056
	s_waitcnt lgkmcnt(1)
	v_mfma_f32_32x32x16_bf16 v[18:33], v[62:65], v[74:77], v[18:33]
	v_add_co_u32_e32 v62, vcc, s2, v56
	s_mov_b32 s2, 0x41000000
	s_nop 0
	v_addc_co_u32_e32 v63, vcc, 0, v57, vcc
	global_load_dwordx4 v[54:57], v[54:55], off
	s_nop 0
	global_load_dwordx4 v[62:65], v[62:63], off
	s_nop 0
	global_load_dwordx4 v[70:73], v[58:59], off
	global_load_dwordx4 v[78:81], v[58:59], off offset:128
	global_load_dwordx4 v[82:85], v[58:59], off offset:256
	s_waitcnt vmcnt(0)
	s_nop 0
	v_max_f32_e32 v58, v19, v19
	v_max_f32_e32 v59, v18, v18
	s_waitcnt lgkmcnt(0)
; __device__ __forceinline__ void partialSM(f32x16& p0, f32x16& p1, float& m_reg, float& mn, float& alpha) {
;   constexpr float C = 1.4426950408889634f;
;   float pmax = p0[0];
; #pragma unroll
;   for (int r = 1; r < 16; ++r) pmax = fmaxf(pmax, p0[r]);
; #pragma unroll
;   for (int r = 0; r < 16; ++r) pmax = fmaxf(pmax, p1[r]);
;   { auto rr = __builtin_amdgcn_permlane32_swap(__float_as_uint(pmax), __float_as_uint(pmax), false, false);
;     pmax = fmaxf(__uint_as_float(rr[0]), __uint_as_float(rr[1])); }
;   if (__builtin_expect(__all(pmax - m_reg <= A_THR), 1)) { mn = m_reg; alpha = 1.f; }
;   else { mn = fmaxf(m_reg, pmax); alpha = __builtin_amdgcn_exp2f((m_reg - mn) * C); m_reg = mn; }
;   float mnC = -mn * C;
; #pragma unroll
;   for (int r = 0; r < 16; ++r) p0[r] = fmaf(p0[r], C, mnC);
; #pragma unroll
;   for (int r = 0; r < 16; ++r) p1[r] = fmaf(p1[r], C, mnC);
; #pragma unroll
;   for (int r = 0; r < 16; ++r) p0[r] = __builtin_amdgcn_exp2f(p0[r]);
; }
; __device__ __forceinline__ void qkt(f32x16& p0, f32x16& p1, const char* Ks, const bf16x8* qr, const char* qpe, int r32, int hi) {
; #pragma unroll
;   for (int r = 0; r < 16; ++r) { p0[r] = 0.f; p1[r] = 0.f; }
; #pragma unroll
;   for (int d0 = 0; d0 < 12; ++d0) { int cb = (d0 * 16 + hi * 8) * 2;
;     bf16x8 b0 = *reinterpret_cast<const bf16x8*>(Ks + KSWZ(r32, cb));
;     bf16x8 b1 = *reinterpret_cast<const bf16x8*>(Ks + KSWZ(32 + r32, cb));
;     bf16x8 qv; if (d0 < 8) qv = qr[d0]; else qv = *reinterpret_cast<const bf16x8*>(qpe + (d0 - 8) * 1024);
;     p0 = __builtin_amdgcn_mfma_f32_32x32x16_bf16(b0, qv, p0, 0, 0, 0);
;     p1 = __builtin_amdgcn_mfma_f32_32x32x16_bf16(b1, qv, p1, 0, 0, 0); }
	v_mfma_f32_32x32x16_bf16 v[34:49], v[66:69], v[74:77], v[34:49]
	v_max_f32_e32 v58, v59, v58
	v_max3_f32 v58, v58, v20, v21
	v_max3_f32 v58, v58, v22, v23
	v_max3_f32 v58, v58, v24, v25
	v_max3_f32 v58, v58, v26, v27
	v_max3_f32 v58, v58, v28, v29
	v_max3_f32 v58, v58, v30, v31
	v_max3_f32 v58, v58, v32, v33
	s_nop 3
	v_max3_f32 v58, v58, v34, v35
	v_max3_f32 v58, v58, v36, v37
	v_max3_f32 v58, v58, v38, v39
	v_max3_f32 v58, v58, v40, v41
	v_max3_f32 v58, v58, v42, v43
	v_max3_f32 v58, v58, v44, v45
	v_max3_f32 v58, v58, v46, v47
	v_max3_f32 v58, v58, v48, v49
	v_mov_b32_e32 v59, v58
	s_nop 1
	v_permlane32_swap_b32_e32 v58, v59
	v_max_f32_e32 v59, v59, v59
	v_max_f32_e32 v58, v58, v58
	v_max_f32_e32 v58, v58, v59
	v_add_f32_e32 v59, 0x7149f2ca, v58
	v_cmp_ge_f32_e32 vcc, s2, v59
	s_cmp_eq_u64 vcc, exec
	v_max_f32_e32 v58, 0xf149f2ca, v58
	s_cselect_b64 vcc, -1, 0
	v_sub_f32_e32 v59, 0xf149f2ca, v58
	v_cndmask_b32_e32 v208, v58, v222, vcc
	v_mul_f32_e32 v59, 0x3fb8aa3b, v59
	v_mul_f32_e32 v58, 0xbfb8aa3b, v208
	v_exp_f32_e32 v59, v59
	v_mov_b32_e32 v66, v58
	v_fmamk_f32 v18, v18, 0x3fb8aa3b, v58
	v_fmamk_f32 v19, v19, 0x3fb8aa3b, v58
	v_fmamk_f32 v20, v20, 0x3fb8aa3b, v58
	v_fmamk_f32 v21, v21, 0x3fb8aa3b, v58
	v_fmamk_f32 v22, v22, 0x3fb8aa3b, v58
	v_fmamk_f32 v23, v23, 0x3fb8aa3b, v58
	v_fmamk_f32 v24, v24, 0x3fb8aa3b, v58
	v_fmamk_f32 v25, v25, 0x3fb8aa3b, v58
	v_fmamk_f32 v26, v26, 0x3fb8aa3b, v58
	v_fmamk_f32 v27, v27, 0x3fb8aa3b, v58
	v_fmamk_f32 v28, v28, 0x3fb8aa3b, v58
	v_fmamk_f32 v29, v29, 0x3fb8aa3b, v58
	v_fmamk_f32 v30, v30, 0x3fb8aa3b, v58
	v_fmamk_f32 v31, v31, 0x3fb8aa3b, v58
	v_fmamk_f32 v32, v32, 0x3fb8aa3b, v58
	v_fmac_f32_e32 v66, 0x3fb8aa3b, v33
	v_exp_f32_e32 v215, v18
	v_exp_f32_e32 v217, v19
	v_exp_f32_e32 v151, v20
	v_exp_f32_e32 v216, v21
	v_exp_f32_e32 v152, v22
	v_exp_f32_e32 v214, v23
	v_exp_f32_e32 v153, v24
	v_exp_f32_e32 v213, v25
	v_exp_f32_e32 v161, v26
	v_exp_f32_e32 v163, v27
	v_exp_f32_e32 v160, v28
	v_exp_f32_e32 v162, v29
	v_exp_f32_e32 v147, v30
	v_exp_f32_e32 v149, v31
	v_exp_f32_e32 v146, v32
	v_exp_f32_e32 v148, v66
	v_and_b32_e32 v18, 15, v60
	v_lshl_or_b32 v156, v18, 4, v156
	v_and_b32_e32 v18, 7, v60
	v_pk_fma_f32 v[134:135], v[48:49], s[84:85], v[58:59] op_sel_hi:[1,0,0]
	v_pk_fma_f32 v[138:139], v[46:47], s[84:85], v[58:59] op_sel_hi:[1,0,0]
	v_pk_fma_f32 v[144:145], v[44:45], s[84:85], v[58:59] op_sel_hi:[1,0,0]
	v_pk_fma_f32 v[130:131], v[42:43], s[84:85], v[58:59] op_sel_hi:[1,0,0]
	v_cndmask_b32_e64 v207, v59, 1.0, vcc
	v_pk_fma_f32 v[132:133], v[40:41], s[84:85], v[58:59] op_sel_hi:[1,0,0]
	v_pk_fma_f32 v[136:137], v[38:39], s[84:85], v[58:59] op_sel_hi:[1,0,0]
	v_pk_fma_f32 v[140:141], v[36:37], s[84:85], v[58:59] op_sel_hi:[1,0,0]
	v_pk_fma_f32 v[142:143], v[34:35], s[84:85], v[58:59] op_sel_hi:[1,0,0]
	s_waitcnt vmcnt(4)
	ds_write_b128 v174, v[54:57] offset:16384
	s_waitcnt vmcnt(3)
	ds_write_b128 v175, v[62:65] offset:16384
	s_waitcnt vmcnt(2)
	ds_write_b128 v173, v[70:73] offset:57344
	s_waitcnt vmcnt(1)
	ds_write_b128 v173, v[78:81] offset:57472
	s_waitcnt vmcnt(0)
	ds_write_b128 v173, v[82:85] offset:57600
	v_lshl_or_b32 v158, v18, 4, v158
	v_mov_b64_e32 v[64:65], v[16:17]
	v_mov_b64_e32 v[48:49], v[16:17]
	v_mov_b64_e32 v[32:33], v[16:17]
	v_mov_b64_e32 v[62:63], v[14:15]
	v_mov_b64_e32 v[60:61], v[12:13]
	v_mov_b64_e32 v[58:59], v[10:11]
	v_mov_b64_e32 v[56:57], v[8:9]
	v_mov_b64_e32 v[54:55], v[6:7]
	v_mov_b64_e32 v[52:53], v[4:5]
	v_mov_b64_e32 v[50:51], v[2:3]
	v_mov_b64_e32 v[46:47], v[14:15]
	v_mov_b64_e32 v[44:45], v[12:13]
	v_mov_b64_e32 v[42:43], v[10:11]
	v_mov_b64_e32 v[40:41], v[8:9]
	v_mov_b64_e32 v[38:39], v[6:7]
	v_mov_b64_e32 v[36:37], v[4:5]
	v_mov_b64_e32 v[34:35], v[2:3]
	v_mov_b64_e32 v[30:31], v[14:15]
	v_mov_b64_e32 v[28:29], v[12:13]
	v_mov_b64_e32 v[26:27], v[10:11]
	v_mov_b64_e32 v[24:25], v[8:9]
	v_mov_b64_e32 v[22:23], v[6:7]
	v_mov_b64_e32 v[20:21], v[4:5]
	v_mov_b64_e32 v[18:19], v[2:3]
	s_waitcnt lgkmcnt(0)
	s_barrier
	ds_read_b128 v[66:69], v172 offset:57344
	ds_read_b128 v[70:73], v204 offset:57344
.LBB0_805:
	ds_read_b128 v[230:233], v176 offset:57344
	ds_read_b128 v[234:237], v206 offset:57344
	v_add_u32_e32 v209, v171, v170
	v_add_f32_e32 v150, 0, v215
	s_waitcnt lgkmcnt(3)
	v_mfma_f32_32x32x16_bf16 v[82:97], v[66:69], v[126:129], 0
	v_add_f32_e32 v150, v217, v150
	v_add_f32_e32 v150, v151, v150
	v_add_f32_e32 v150, v216, v150
	v_add_f32_e32 v150, v152, v150
	v_add_f32_e32 v150, v214, v150
	v_add_f32_e32 v150, v153, v150
	v_add_f32_e32 v150, v213, v150
	s_waitcnt lgkmcnt(2)
	v_mfma_f32_32x32x16_bf16 v[66:81], v[70:73], v[126:129], 0
	v_add_f32_e32 v150, v161, v150
	v_add_f32_e32 v150, v163, v150
	v_add_f32_e32 v150, v160, v150
	v_add_f32_e32 v150, v162, v150
	v_exp_f32_e32 v142, v142
	v_add_f32_e32 v150, v147, v150
	v_exp_f32_e32 v143, v143
	s_waitcnt lgkmcnt(1)
	v_mfma_f32_32x32x16_bf16 v[82:97], v[230:233], v[122:125], v[82:97]
	ds_read_b128 v[230:233], v177 offset:57344
	v_add_f32_e32 v150, v149, v150
	v_exp_f32_e32 v140, v140
	v_add_f32_e32 v150, v146, v150
	v_exp_f32_e32 v141, v141
	v_add_f32_e32 v150, v148, v150
	v_exp_f32_e32 v136, v136
	v_add_f32_e32 v150, v142, v150
	s_waitcnt lgkmcnt(1)
	v_mfma_f32_32x32x16_bf16 v[66:81], v[234:237], v[122:125], v[66:81]
	ds_read_b128 v[234:237], v205 offset:57344
	v_exp_f32_e32 v137, v137
	v_add_f32_e32 v150, v143, v150
	v_exp_f32_e32 v132, v132
	v_add_f32_e32 v150, v140, v150
	v_exp_f32_e32 v133, v133
	v_add_f32_e32 v150, v141, v150
	s_waitcnt lgkmcnt(1)
; __device__ __forceinline__ void finishSM(f32x16& p0, f32x16& p1, float alpha, float& l_reg, bf16x8& pa0, bf16x8& pa1, bf16x8& pa2, bf16x8& pa3) {
; #pragma unroll
;   for (int r = 0; r < 16; ++r) p1[r] = __builtin_amdgcn_exp2f(p1[r]);
;   float ps = 0;
; #pragma unroll
;   for (int r = 0; r < 16; ++r) ps += p0[r];
; #pragma unroll
;   for (int r = 0; r < 16; ++r) ps += p1[r];
;   { auto rr = __builtin_amdgcn_permlane32_swap(__float_as_uint(ps), __float_as_uint(ps), false, false);
;     ps = __uint_as_float(rr[0]) + __uint_as_float(rr[1]); }
;   l_reg = l_reg * alpha + ps;
;     ...
;   PK4(p0, 0, pa0); PK4(p0, 8, pa1); PK4(p1, 0, pa2); PK4(p1, 8, pa3);
; __device__ __forceinline__ void qkt(f32x16& p0, f32x16& p1, const char* Ks, const bf16x8* qr, const char* qpe, int r32, int hi) {
; #pragma unroll
;   for (int r = 0; r < 16; ++r) { p0[r] = 0.f; p1[r] = 0.f; }
; #pragma unroll
;   for (int d0 = 0; d0 < 12; ++d0) { int cb = (d0 * 16 + hi * 8) * 2;
;     bf16x8 b0 = *reinterpret_cast<const bf16x8*>(Ks + KSWZ(r32, cb));
;     bf16x8 b1 = *reinterpret_cast<const bf16x8*>(Ks + KSWZ(32 + r32, cb));
;     bf16x8 qv; if (d0 < 8) qv = qr[d0]; else qv = *reinterpret_cast<const bf16x8*>(qpe + (d0 - 8) * 1024);
;     p0 = __builtin_amdgcn_mfma_f32_32x32x16_bf16(b0, qv, p0, 0, 0, 0);
;     p1 = __builtin_amdgcn_mfma_f32_32x32x16_bf16(b1, qv, p1, 0, 0, 0); }
	v_mfma_f32_32x32x16_bf16 v[82:97], v[230:233], v[118:121], v[82:97]
	ds_read_b128 v[230:233], v178 offset:57344
	v_exp_f32_e32 v130, v130
	v_add_f32_e32 v150, v136, v150
	v_exp_f32_e32 v131, v131
	v_add_f32_e32 v150, v137, v150
	v_exp_f32_e32 v144, v144
	v_add_f32_e32 v150, v132, v150
	v_exp_f32_e32 v145, v145
	s_waitcnt lgkmcnt(1)
	v_mfma_f32_32x32x16_bf16 v[66:81], v[234:237], v[118:121], v[66:81]
	ds_read_b128 v[234:237], v203 offset:57344
	v_add_f32_e32 v150, v133, v150
	v_exp_f32_e32 v138, v138
	v_add_f32_e32 v150, v130, v150
	v_exp_f32_e32 v139, v139
	v_add_f32_e32 v150, v131, v150
	v_exp_f32_e32 v134, v134
	s_waitcnt lgkmcnt(1)
	v_mfma_f32_32x32x16_bf16 v[82:97], v[230:233], v[114:117], v[82:97]
	ds_read_b128 v[230:233], v181 offset:57344
	v_add_f32_e32 v150, v144, v150
	v_exp_f32_e32 v135, v135
	v_add_f32_e32 v150, v145, v150
	v_add_f32_e32 v150, v138, v150
	v_add_f32_e32 v150, v139, v150
	v_add_f32_e32 v150, v134, v150
	v_add_f32_e32 v210, v135, v150
	s_waitcnt lgkmcnt(1)
	v_mfma_f32_32x32x16_bf16 v[66:81], v[234:237], v[114:117], v[66:81]
	ds_read_b128 v[234:237], v202 offset:57344
	v_mov_b32_e32 v211, v210
	s_nop 1
	v_permlane32_swap_b32_e32 v210, v211
	s_waitcnt lgkmcnt(1)
	v_mfma_f32_32x32x16_bf16 v[82:97], v[230:233], v[110:113], v[82:97]
	ds_read_b128 v[230:233], v185 offset:57344
	s_waitcnt lgkmcnt(1)
	v_mfma_f32_32x32x16_bf16 v[66:81], v[234:237], v[110:113], v[66:81]
	ds_read_b128 v[234:237], v201 offset:57344
	s_waitcnt lgkmcnt(1)
	v_mfma_f32_32x32x16_bf16 v[82:97], v[230:233], v[106:109], v[82:97]
	ds_read_b128 v[230:233], v179 offset:57344
	s_waitcnt lgkmcnt(1)
	v_mfma_f32_32x32x16_bf16 v[66:81], v[234:237], v[106:109], v[66:81]
	ds_read_b128 v[234:237], v200 offset:57344
	s_waitcnt lgkmcnt(1)
	v_mfma_f32_32x32x16_bf16 v[82:97], v[230:233], v[102:105], v[82:97]
	ds_read_b128 v[230:233], v180 offset:57344
	s_waitcnt lgkmcnt(1)
	v_mfma_f32_32x32x16_bf16 v[66:81], v[234:237], v[102:105], v[66:81]
	ds_read_b128 v[234:237], v199 offset:57344
	s_waitcnt lgkmcnt(1)
	v_mfma_f32_32x32x16_bf16 v[82:97], v[230:233], v[98:101], v[82:97]
	ds_read_b128 v[230:233], v188 offset:57344
	ds_read_b128 v[238:241], v209
	s_waitcnt lgkmcnt(2)
	v_mfma_f32_32x32x16_bf16 v[66:81], v[234:237], v[98:101], v[66:81]
	ds_read_b128 v[234:237], v198 offset:57344
	s_waitcnt lgkmcnt(1)
	v_mfma_f32_32x32x16_bf16 v[82:97], v[230:233], v[238:241], v[82:97]
	ds_read_b128 v[230:233], v192 offset:57344
	ds_read_b128 v[242:245], v209 offset:1024
	s_waitcnt lgkmcnt(2)
	v_mfma_f32_32x32x16_bf16 v[66:81], v[234:237], v[238:241], v[66:81]
	ds_read_b128 v[234:237], v197 offset:57344
	s_waitcnt lgkmcnt(1)
	v_mfma_f32_32x32x16_bf16 v[82:97], v[230:233], v[242:245], v[82:97]
	ds_read_b128 v[230:233], v193 offset:57344
	ds_read_b128 v[238:241], v209 offset:2048
	s_waitcnt lgkmcnt(2)
	v_mfma_f32_32x32x16_bf16 v[66:81], v[234:237], v[242:245], v[66:81]
	ds_read_b128 v[234:237], v196 offset:57344
	s_waitcnt lgkmcnt(1)
	v_mfma_f32_32x32x16_bf16 v[82:97], v[230:233], v[238:241], v[82:97]
	ds_read_b128 v[230:233], v195 offset:57344
	ds_read_b128 v[242:245], v209 offset:3072
	s_waitcnt lgkmcnt(2)
	v_mfma_f32_32x32x16_bf16 v[66:81], v[234:237], v[238:241], v[66:81]
	ds_read_b128 v[234:237], v194 offset:57344
	v_cvt_pk_bf16_f32 v150, v215, v217
	v_cvt_pk_bf16_f32 v151, v151, v216
	v_cvt_pk_bf16_f32 v152, v152, v214
	v_cvt_pk_bf16_f32 v153, v153, v213
	v_cvt_pk_bf16_f32 v212, v161, v163
	v_cvt_pk_bf16_f32 v213, v160, v162
	s_waitcnt lgkmcnt(1)
	v_mfma_f32_32x32x16_bf16 v[82:97], v[230:233], v[242:245], v[82:97]
	v_cvt_pk_bf16_f32 v214, v147, v149
	v_permlane32_swap_b32_e32 v150, v152
	v_cvt_pk_bf16_f32 v215, v146, v148
	v_permlane32_swap_b32_e32 v212, v214
	v_cvt_pk_bf16_f32 v230, v142, v143
	s_waitcnt lgkmcnt(0)
	v_mfma_f32_32x32x16_bf16 v[66:81], v[234:237], v[242:245], v[66:81]
	v_cvt_pk_bf16_f32 v231, v140, v141
	v_cvt_pk_bf16_f32 v232, v136, v137
	v_cvt_pk_bf16_f32 v233, v132, v133
	v_cvt_pk_bf16_f32 v234, v130, v131
	v_cvt_pk_bf16_f32 v235, v144, v145
	v_cvt_pk_bf16_f32 v236, v138, v139
	v_cvt_pk_bf16_f32 v237, v134, v135
	v_permlane32_swap_b32_e32 v151, v153
	v_permlane32_swap_b32_e32 v213, v215
	v_permlane32_swap_b32_e32 v230, v232
	v_permlane32_swap_b32_e32 v231, v233
	v_permlane32_swap_b32_e32 v234, v236
	v_permlane32_swap_b32_e32 v235, v237
	v_lshl_add_u64 v[160:161], s[88:89], 0, v[156:157]
	v_add_co_u32_e32 v130, vcc, s31, v160
	v_lshl_add_u64 v[162:163], s[88:89], 0, v[158:159]
	s_nop 0
	v_addc_co_u32_e32 v131, vcc, 0, v161, vcc
	v_add_co_u32_e32 v134, vcc, s34, v160
	s_nop 1
	v_addc_co_u32_e32 v135, vcc, 0, v161, vcc
	v_add_co_u32_e32 v146, vcc, s35, v162
	global_load_dwordx4 v[130:133], v[130:131], off
	s_nop 0
	global_load_dwordx4 v[134:137], v[134:135], off
	v_addc_co_u32_e32 v147, vcc, 0, v163, vcc
	global_load_dwordx4 v[138:141], v[146:147], off
	global_load_dwordx4 v[142:145], v[146:147], off offset:128
	s_nop 0
	global_load_dwordx4 v[146:149], v[146:147], off offset:256
	ds_read_b64_tr_b16 v[238:239], v169 offset:0
	ds_read_b64_tr_b16 v[240:241], v169 offset:0x800
	ds_read_b64_tr_b16 v[242:243], v169 offset:0x1000
	ds_read_b64_tr_b16 v[244:245], v169 offset:0x1800
	ds_read_b64_tr_b16 v[246:247], v169 offset:0x2000
	ds_read_b64_tr_b16 v[248:249], v169 offset:0x2800
	ds_read_b64_tr_b16 v[250:251], v169 offset:0x3000
	ds_read_b64_tr_b16 v[252:253], v169 offset:0x3800
	s_waitcnt lgkmcnt(0)
; #define SCHEDB() __builtin_amdgcn_sched_barrier(0)
; __device__ __forceinline__ void partialSM(f32x16& p0, f32x16& p1, float& m_reg, float& mn, float& alpha) {
;   constexpr float C = 1.4426950408889634f;
;   float pmax = p0[0];
; #pragma unroll
;   for (int r = 1; r < 16; ++r) pmax = fmaxf(pmax, p0[r]);
; #pragma unroll
;   for (int r = 0; r < 16; ++r) pmax = fmaxf(pmax, p1[r]);
;   { auto rr = __builtin_amdgcn_permlane32_swap(__float_as_uint(pmax), __float_as_uint(pmax), false, false);
;     pmax = fmaxf(__uint_as_float(rr[0]), __uint_as_float(rr[1])); }
;   if (__builtin_expect(__all(pmax - m_reg <= A_THR), 1)) { mn = m_reg; alpha = 1.f; }
;   else { mn = fmaxf(m_reg, pmax); alpha = __builtin_amdgcn_exp2f((m_reg - mn) * C); m_reg = mn; }
; template <int D0> __device__ __forceinline__ void pv_one(f32x16& od, int vb, bf16x8 pa0, bf16x8 pa1, bf16x8 pa2, bf16x8 pa3) {
;   const s16x4 l0 = tr_read<v_rd_off(D0, 0, 0)>(vb), h0 = tr_read<v_rd_off(D0, 0, 1)>(vb), l1 = tr_read<v_rd_off(D0, 1, 0)>(vb), h1 = tr_read<v_rd_off(D0, 1, 1)>(vb);
;   const s16x4 l2 = tr_read<v_rd_off(D0, 2, 0)>(vb), h2 = tr_read<v_rd_off(D0, 2, 1)>(vb), l3 = tr_read<v_rd_off(D0, 3, 0)>(vb), h3 = tr_read<v_rd_off(D0, 3, 1)>(vb);
;   asm volatile("s_waitcnt lgkmcnt(0)" ::: "memory"); SCHEDB();
;     ...
;   od = __builtin_amdgcn_mfma_f32_32x32x16_bf16(pa0, PKV(l0, h0), od, 0, 0, 0);
;   od = __builtin_amdgcn_mfma_f32_32x32x16_bf16(pa1, PKV(l1, h1), od, 0, 0, 0);
;   od = __builtin_amdgcn_mfma_f32_32x32x16_bf16(pa2, PKV(l2, h2), od, 0, 0, 0);
;   od = __builtin_amdgcn_mfma_f32_32x32x16_bf16(pa3, PKV(l3, h3), od, 0, 0, 0);
;     ...
; }
; __device__ __forceinline__ void pv_d0(f32x16* o, int vb, bf16x8 pa0, bf16x8 pa1, bf16x8 pa2, bf16x8 pa3) {
;   pv_one<0>(o[0], vb, pa0, pa1, pa2, pa3); pv_one<1>(o[1], vb, pa0, pa1, pa2, pa3); pv_one<2>(o[2], vb, pa0, pa1, pa2, pa3); pv_one<3>(o[3], vb, pa0, pa1, pa2, pa3);
	s_nop 0
	v_mfma_f32_32x32x16_bf16 v[2:17], v[150:153], v[238:241], v[2:17]
	ds_read_b64_tr_b16 v[238:239], v169 offset:0x200
	ds_read_b64_tr_b16 v[240:241], v169 offset:0xa00
	v_mfma_f32_32x32x16_bf16 v[2:17], v[212:215], v[242:245], v[2:17]
	ds_read_b64_tr_b16 v[242:243], v169 offset:0x1200
	ds_read_b64_tr_b16 v[244:245], v169 offset:0x1a00
	v_mfma_f32_32x32x16_bf16 v[2:17], v[230:233], v[246:249], v[2:17]
	ds_read_b64_tr_b16 v[246:247], v169 offset:0x2200
	ds_read_b64_tr_b16 v[248:249], v169 offset:0x2a00
	v_mfma_f32_32x32x16_bf16 v[2:17], v[234:237], v[250:253], v[2:17]
	ds_read_b64_tr_b16 v[250:251], v169 offset:0x3200
	ds_read_b64_tr_b16 v[252:253], v169 offset:0x3a00
	s_waitcnt lgkmcnt(0)
	v_mfma_f32_32x32x16_bf16 v[50:65], v[150:153], v[238:241], v[50:65]
	ds_read_b64_tr_b16 v[238:239], v169 offset:0x400
	ds_read_b64_tr_b16 v[240:241], v169 offset:0xc00
	v_mfma_f32_32x32x16_bf16 v[50:65], v[212:215], v[242:245], v[50:65]
	ds_read_b64_tr_b16 v[242:243], v169 offset:0x1400
	ds_read_b64_tr_b16 v[244:245], v169 offset:0x1c00
	v_mfma_f32_32x32x16_bf16 v[50:65], v[230:233], v[246:249], v[50:65]
	ds_read_b64_tr_b16 v[246:247], v169 offset:0x2400
	ds_read_b64_tr_b16 v[248:249], v169 offset:0x2c00
	v_mfma_f32_32x32x16_bf16 v[50:65], v[234:237], v[250:253], v[50:65]
	ds_read_b64_tr_b16 v[250:251], v169 offset:0x3400
	ds_read_b64_tr_b16 v[252:253], v169 offset:0x3c00
	s_waitcnt lgkmcnt(0)
	v_mfma_f32_32x32x16_bf16 v[34:49], v[150:153], v[238:241], v[34:49]
	ds_read_b64_tr_b16 v[238:239], v169 offset:0x600
	ds_read_b64_tr_b16 v[240:241], v169 offset:0xe00
	v_mfma_f32_32x32x16_bf16 v[34:49], v[212:215], v[242:245], v[34:49]
	ds_read_b64_tr_b16 v[242:243], v169 offset:0x1600
	ds_read_b64_tr_b16 v[244:245], v169 offset:0x1e00
	v_mfma_f32_32x32x16_bf16 v[34:49], v[230:233], v[246:249], v[34:49]
	ds_read_b64_tr_b16 v[246:247], v169 offset:0x2600
	ds_read_b64_tr_b16 v[248:249], v169 offset:0x2e00
	v_mfma_f32_32x32x16_bf16 v[34:49], v[234:237], v[250:253], v[34:49]
	ds_read_b64_tr_b16 v[250:251], v169 offset:0x3600
	ds_read_b64_tr_b16 v[252:253], v169 offset:0x3e00
	s_waitcnt lgkmcnt(0)
	v_mfma_f32_32x32x16_bf16 v[18:33], v[150:153], v[238:241], v[18:33]
	v_max_f32_e32 v150, v83, v83
	v_max_f32_e32 v151, v82, v82
	v_max_f32_e32 v150, v151, v150
	v_max3_f32 v150, v150, v84, v85
	v_max3_f32 v150, v150, v86, v87
	v_max3_f32 v150, v150, v88, v89
	v_max3_f32 v150, v150, v90, v91
	v_max3_f32 v150, v150, v92, v93
	v_max3_f32 v150, v150, v94, v95
	v_mfma_f32_32x32x16_bf16 v[18:33], v[212:215], v[242:245], v[18:33]
	v_max3_f32 v150, v150, v96, v97
	v_max3_f32 v150, v150, v66, v67
	v_max3_f32 v150, v150, v68, v69
	v_max3_f32 v150, v150, v70, v71
	v_max3_f32 v150, v150, v72, v73
	v_max3_f32 v150, v150, v74, v75
	v_max3_f32 v150, v150, v76, v77
	v_max3_f32 v150, v150, v78, v79
	v_mfma_f32_32x32x16_bf16 v[18:33], v[230:233], v[246:249], v[18:33]
	v_max3_f32 v150, v150, v80, v81
	v_mov_b32_e32 v151, v150
	s_nop 1
	v_permlane32_swap_b32_e32 v150, v151
	v_max_f32_e32 v151, v151, v151
	v_max_f32_e32 v150, v150, v150
	v_max_f32_e32 v150, v150, v151
	v_sub_f32_e32 v151, v150, v208
	v_cmp_ge_f32_e32 vcc, s2, v151
	v_max_f32_e32 v151, v208, v208
	v_max_f32_e32 v150, v151, v150
	v_mfma_f32_32x32x16_bf16 v[18:33], v[234:237], v[250:253], v[18:33]
	v_sub_f32_e32 v151, v208, v150
	v_mul_f32_e32 v151, 0x3fb8aa3b, v151
	v_exp_f32_e32 v151, v151
	s_cmp_eq_u64 vcc, exec
	s_cselect_b64 s[10:11], -1, 0
	s_waitcnt vmcnt(0)
	v_cndmask_b32_e64 v212, v151, 1.0, s[10:11]
	v_cmp_gt_f32_e32 vcc, 1.0, v212
	ds_write_b128 v173, v[138:141] offset:32768
	ds_write_b128 v173, v[142:145] offset:32896
	ds_write_b128 v173, v[146:149] offset:33024
	s_waitcnt lgkmcnt(0)
	s_barrier
	ds_write_b128 v174, v[130:133]
	ds_write_b128 v175, v[134:137]
	s_cbranch_vccz .LBB0_809
	s_and_saveexec_b64 s[14:15], s[8:9]
	ds_write_b32 v166, v212 offset:128
	s_or_b64 exec, exec, s[14:15]
	s_waitcnt lgkmcnt(0)
	v_add_u32_e32 v142, v155, v0
	ds_read_b128 v[130:133], v142 offset:224
	ds_read_b128 v[134:137], v142 offset:192
	ds_read_b128 v[138:141], v142 offset:160
	ds_read_b128 v[142:145], v142 offset:128
	s_waitcnt lgkmcnt(3)
	v_pk_mul_f32 v[14:15], v[14:15], v[130:131]
	s_waitcnt lgkmcnt(2)
	v_pk_mul_f32 v[10:11], v[10:11], v[134:135]
	s_waitcnt lgkmcnt(1)
	v_pk_mul_f32 v[6:7], v[6:7], v[138:139]
	v_pk_mul_f32 v[16:17], v[16:17], v[132:133]
	v_pk_mul_f32 v[12:13], v[12:13], v[136:137]
	v_pk_mul_f32 v[8:9], v[8:9], v[140:141]
	s_waitcnt lgkmcnt(0)
	v_pk_mul_f32 v[4:5], v[4:5], v[144:145]
	v_pk_mul_f32 v[2:3], v[2:3], v[142:143]
	v_pk_mul_f32 v[62:63], v[62:63], v[130:131]
	v_pk_mul_f32 v[58:59], v[58:59], v[134:135]
	v_pk_mul_f32 v[54:55], v[54:55], v[138:139]
	v_pk_mul_f32 v[64:65], v[64:65], v[132:133]
	v_pk_mul_f32 v[60:61], v[60:61], v[136:137]
	v_pk_mul_f32 v[56:57], v[56:57], v[140:141]
	v_pk_mul_f32 v[52:53], v[52:53], v[144:145]
	v_pk_mul_f32 v[50:51], v[50:51], v[142:143]
	v_pk_mul_f32 v[46:47], v[46:47], v[130:131]
	v_pk_mul_f32 v[42:43], v[42:43], v[134:135]
	v_pk_mul_f32 v[38:39], v[38:39], v[138:139]
	v_pk_mul_f32 v[48:49], v[48:49], v[132:133]
	v_pk_mul_f32 v[44:45], v[44:45], v[136:137]
	v_pk_mul_f32 v[40:41], v[40:41], v[140:141]
	v_pk_mul_f32 v[36:37], v[36:37], v[144:145]
	v_pk_mul_f32 v[34:35], v[34:35], v[142:143]
	v_pk_mul_f32 v[30:31], v[30:31], v[130:131]
	v_pk_mul_f32 v[26:27], v[26:27], v[134:135]
	v_pk_mul_f32 v[22:23], v[22:23], v[138:139]
	v_pk_mul_f32 v[32:33], v[32:33], v[132:133]
	v_pk_mul_f32 v[28:29], v[28:29], v[136:137]
	v_pk_mul_f32 v[24:25], v[24:25], v[140:141]
	v_pk_mul_f32 v[20:21], v[20:21], v[144:145]
	v_pk_mul_f32 v[18:19], v[18:19], v[142:143]
; __device__ __forceinline__ void partialSM(f32x16& p0, f32x16& p1, float& m_reg, float& mn, float& alpha) {
;     ...
;   else { mn = fmaxf(m_reg, pmax); alpha = __builtin_amdgcn_exp2f((m_reg - mn) * C); m_reg = mn; }
;   float mnC = -mn * C;
; #pragma unroll
;   for (int r = 0; r < 16; ++r) p0[r] = fmaf(p0[r], C, mnC);
; #pragma unroll
;   for (int r = 0; r < 16; ++r) p1[r] = fmaf(p1[r], C, mnC);
; #pragma unroll
;   for (int r = 0; r < 16; ++r) p0[r] = __builtin_amdgcn_exp2f(p0[r]);
; }
; __device__ __forceinline__ void finishSM(f32x16& p0, f32x16& p1, float alpha, float& l_reg, bf16x8& pa0, bf16x8& pa1, bf16x8& pa2, bf16x8& pa3) {
; #pragma unroll
;   for (int r = 0; r < 16; ++r) p1[r] = __builtin_amdgcn_exp2f(p1[r]);
; __device__ __forceinline__ void qkt(f32x16& p0, f32x16& p1, const char* Ks, const bf16x8* qr, const char* qpe, int r32, int hi) {
; #pragma unroll
;   for (int r = 0; r < 16; ++r) { p0[r] = 0.f; p1[r] = 0.f; }
; #pragma unroll
;   for (int d0 = 0; d0 < 12; ++d0) { int cb = (d0 * 16 + hi * 8) * 2;
;     bf16x8 b0 = *reinterpret_cast<const bf16x8*>(Ks + KSWZ(r32, cb));
;     bf16x8 b1 = *reinterpret_cast<const bf16x8*>(Ks + KSWZ(32 + r32, cb));
;     bf16x8 qv; if (d0 < 8) qv = qr[d0]; else qv = *reinterpret_cast<const bf16x8*>(qpe + (d0 - 8) * 1024);
;     p0 = __builtin_amdgcn_mfma_f32_32x32x16_bf16(b0, qv, p0, 0, 0, 0);
;     p1 = __builtin_amdgcn_mfma_f32_32x32x16_bf16(b1, qv, p1, 0, 0, 0); }
.LBB0_809:
	v_cndmask_b32_e64 v208, v150, v208, s[10:11]
	v_mul_f32_e32 v146, 0xbfb8aa3b, v208
	v_fmamk_f32 v214, v66, 0x3fb8aa3b, v146
	v_fmamk_f32 v215, v67, 0x3fb8aa3b, v146
	v_fmamk_f32 v216, v68, 0x3fb8aa3b, v146
	v_fmamk_f32 v217, v69, 0x3fb8aa3b, v146
	v_fmamk_f32 v229, v70, 0x3fb8aa3b, v146
	v_fmamk_f32 v148, v71, 0x3fb8aa3b, v146
	v_fmamk_f32 v149, v72, 0x3fb8aa3b, v146
	v_fmamk_f32 v150, v73, 0x3fb8aa3b, v146
	ds_read_b128 v[66:69], v172 offset:32768
	ds_read_b128 v[70:73], v172 offset:45056
	ds_read_b128 v[232:235], v176 offset:32768
	ds_read_b128 v[236:239], v176 offset:45056
	v_fmamk_f32 v82, v82, 0x3fb8aa3b, v146
	v_fmamk_f32 v83, v83, 0x3fb8aa3b, v146
	v_fmamk_f32 v84, v84, 0x3fb8aa3b, v146
	v_fmamk_f32 v85, v85, 0x3fb8aa3b, v146
	v_fmamk_f32 v86, v86, 0x3fb8aa3b, v146
	v_fmamk_f32 v87, v87, 0x3fb8aa3b, v146
	v_fmamk_f32 v88, v88, 0x3fb8aa3b, v146
	v_fmamk_f32 v89, v89, 0x3fb8aa3b, v146
	v_fmamk_f32 v90, v90, 0x3fb8aa3b, v146
	v_fmamk_f32 v91, v91, 0x3fb8aa3b, v146
	v_fmamk_f32 v92, v92, 0x3fb8aa3b, v146
	v_fmamk_f32 v93, v93, 0x3fb8aa3b, v146
	v_fmamk_f32 v94, v94, 0x3fb8aa3b, v146
	v_fmamk_f32 v95, v95, 0x3fb8aa3b, v146
	v_fmamk_f32 v96, v96, 0x3fb8aa3b, v146
	v_fmamk_f32 v97, v97, 0x3fb8aa3b, v146
	v_fmamk_f32 v151, v74, 0x3fb8aa3b, v146
	v_fmamk_f32 v230, v79, 0x3fb8aa3b, v146
	v_fmamk_f32 v152, v75, 0x3fb8aa3b, v146
	v_fmamk_f32 v153, v76, 0x3fb8aa3b, v146
	v_fmamk_f32 v213, v77, 0x3fb8aa3b, v146
	v_fmamk_f32 v147, v78, 0x3fb8aa3b, v146
	v_exp_f32_e32 v143, v82
	v_exp_f32_e32 v145, v83
	v_exp_f32_e32 v141, v84
	v_exp_f32_e32 v144, v85
	v_exp_f32_e32 v140, v86
	v_exp_f32_e32 v142, v87
	v_exp_f32_e32 v138, v88
	v_exp_f32_e32 v139, v89
	v_exp_f32_e32 v135, v90
	v_exp_f32_e32 v137, v91
	v_exp_f32_e32 v134, v92
	v_exp_f32_e32 v136, v93
	v_exp_f32_e32 v131, v94
	v_exp_f32_e32 v133, v95
	v_exp_f32_e32 v130, v96
	v_exp_f32_e32 v132, v97
	v_fmamk_f32 v231, v80, 0x3fb8aa3b, v146
	v_fmac_f32_e32 v146, 0x3fb8aa3b, v81
	v_exp_f32_e32 v224, v214
	v_exp_f32_e32 v225, v215
	s_waitcnt lgkmcnt(3)
	v_mfma_f32_32x32x16_bf16 v[82:97], v[66:69], v[126:129], 0
	v_exp_f32_e32 v148, v148
	v_exp_f32_e32 v149, v149
	v_exp_f32_e32 v213, v213
	v_exp_f32_e32 v147, v147
	v_exp_f32_e32 v231, v231
	v_exp_f32_e32 v146, v146
	s_waitcnt lgkmcnt(2)
	v_mfma_f32_32x32x16_bf16 v[66:81], v[70:73], v[126:129], 0
	s_waitcnt lgkmcnt(0)
	v_mfma_f32_32x32x16_bf16 v[66:81], v[236:239], v[122:125], v[66:81]
	ds_read_b128 v[236:239], v177 offset:45056
	s_waitcnt lgkmcnt(1)
	v_mfma_f32_32x32x16_bf16 v[82:97], v[232:235], v[122:125], v[82:97]
	ds_read_b128 v[232:235], v177 offset:32768
	s_waitcnt lgkmcnt(1)
	v_mfma_f32_32x32x16_bf16 v[66:81], v[236:239], v[118:121], v[66:81]
	ds_read_b128 v[236:239], v178 offset:45056
	s_waitcnt lgkmcnt(1)
	v_mfma_f32_32x32x16_bf16 v[82:97], v[232:235], v[118:121], v[82:97]
	ds_read_b128 v[232:235], v178 offset:32768
	s_waitcnt lgkmcnt(1)
	v_mfma_f32_32x32x16_bf16 v[66:81], v[236:239], v[114:117], v[66:81]
	ds_read_b128 v[236:239], v181 offset:45056
	s_waitcnt lgkmcnt(1)
	v_mfma_f32_32x32x16_bf16 v[82:97], v[232:235], v[114:117], v[82:97]
	ds_read_b128 v[232:235], v181 offset:32768
	s_waitcnt lgkmcnt(1)
	v_mfma_f32_32x32x16_bf16 v[66:81], v[236:239], v[110:113], v[66:81]
	ds_read_b128 v[236:239], v185 offset:45056
	s_waitcnt lgkmcnt(1)
	v_mfma_f32_32x32x16_bf16 v[82:97], v[232:235], v[110:113], v[82:97]
	ds_read_b128 v[232:235], v185 offset:32768
	s_waitcnt lgkmcnt(1)
	v_mfma_f32_32x32x16_bf16 v[66:81], v[236:239], v[106:109], v[66:81]
	ds_read_b128 v[236:239], v179 offset:45056
	s_waitcnt lgkmcnt(1)
	v_mfma_f32_32x32x16_bf16 v[82:97], v[232:235], v[106:109], v[82:97]
	ds_read_b128 v[232:235], v179 offset:32768
	s_waitcnt lgkmcnt(1)
	v_mfma_f32_32x32x16_bf16 v[66:81], v[236:239], v[102:105], v[66:81]
	ds_read_b128 v[236:239], v180 offset:45056
	s_waitcnt lgkmcnt(1)
	v_mfma_f32_32x32x16_bf16 v[82:97], v[232:235], v[102:105], v[82:97]
	ds_read_b128 v[232:235], v180 offset:32768
	s_waitcnt lgkmcnt(1)
	v_mfma_f32_32x32x16_bf16 v[66:81], v[236:239], v[98:101], v[66:81]
	ds_read_b128 v[236:239], v188 offset:45056
	ds_read_b128 v[240:243], v209
	s_waitcnt lgkmcnt(2)
	v_mfma_f32_32x32x16_bf16 v[82:97], v[232:235], v[98:101], v[82:97]
	ds_read_b128 v[232:235], v188 offset:32768
	s_waitcnt lgkmcnt(1)
	v_mfma_f32_32x32x16_bf16 v[66:81], v[236:239], v[240:243], v[66:81]
	ds_read_b128 v[236:239], v192 offset:45056
	ds_read_b128 v[244:247], v209 offset:1024
	s_waitcnt lgkmcnt(2)
	v_mfma_f32_32x32x16_bf16 v[82:97], v[232:235], v[240:243], v[82:97]
	ds_read_b128 v[232:235], v192 offset:32768
	s_waitcnt lgkmcnt(1)
	v_mfma_f32_32x32x16_bf16 v[66:81], v[236:239], v[244:247], v[66:81]
	ds_read_b128 v[236:239], v193 offset:45056
	ds_read_b128 v[240:243], v209 offset:2048
	s_waitcnt lgkmcnt(2)
	v_mfma_f32_32x32x16_bf16 v[82:97], v[232:235], v[244:247], v[82:97]
	ds_read_b128 v[232:235], v193 offset:32768
	s_waitcnt lgkmcnt(1)
	v_mfma_f32_32x32x16_bf16 v[66:81], v[236:239], v[240:243], v[66:81]
	ds_read_b128 v[236:239], v195 offset:45056
	ds_read_b128 v[244:247], v209 offset:3072
	s_waitcnt lgkmcnt(2)
	v_mfma_f32_32x32x16_bf16 v[82:97], v[232:235], v[240:243], v[82:97]
	ds_read_b128 v[232:235], v195 offset:32768
	s_waitcnt lgkmcnt(1)
	v_mfma_f32_32x32x16_bf16 v[66:81], v[236:239], v[244:247], v[66:81]
	v_exp_f32_e32 v236, v150
	v_add_f32_e32 v150, 0, v143
	v_add_f32_e32 v150, v145, v150
	v_add_f32_e32 v150, v141, v150
	v_add_f32_e32 v150, v144, v150
	v_add_f32_e32 v150, v140, v150
	v_add_f32_e32 v150, v142, v150
	v_add_f32_e32 v150, v138, v150
	v_add_f32_e32 v150, v139, v150
	v_add_f32_e32 v150, v135, v150
	v_add_f32_e32 v150, v137, v150
	v_add_f32_e32 v150, v134, v150
	v_add_f32_e32 v150, v136, v150
	v_add_f32_e32 v150, v131, v150
	v_add_f32_e32 v150, v133, v150
	s_waitcnt lgkmcnt(0)
; #define SCHEDB() __builtin_amdgcn_sched_barrier(0)
; __device__ __forceinline__ void finishSM(f32x16& p0, f32x16& p1, float alpha, float& l_reg, bf16x8& pa0, bf16x8& pa1, bf16x8& pa2, bf16x8& pa3) {
; #pragma unroll
;   for (int r = 0; r < 16; ++r) p1[r] = __builtin_amdgcn_exp2f(p1[r]);
;   float ps = 0;
; #pragma unroll
;   for (int r = 0; r < 16; ++r) ps += p0[r];
; #pragma unroll
;   for (int r = 0; r < 16; ++r) ps += p1[r];
;   { auto rr = __builtin_amdgcn_permlane32_swap(__float_as_uint(ps), __float_as_uint(ps), false, false);
;     ps = __uint_as_float(rr[0]) + __uint_as_float(rr[1]); }
;   l_reg = l_reg * alpha + ps;
;     ...
;   PK4(p0, 0, pa0); PK4(p0, 8, pa1); PK4(p1, 0, pa2); PK4(p1, 8, pa3);
; template <int D0> __device__ __forceinline__ void pv_one(f32x16& od, int vb, bf16x8 pa0, bf16x8 pa1, bf16x8 pa2, bf16x8 pa3) {
;   const s16x4 l0 = tr_read<v_rd_off(D0, 0, 0)>(vb), h0 = tr_read<v_rd_off(D0, 0, 1)>(vb), l1 = tr_read<v_rd_off(D0, 1, 0)>(vb), h1 = tr_read<v_rd_off(D0, 1, 1)>(vb);
;   const s16x4 l2 = tr_read<v_rd_off(D0, 2, 0)>(vb), h2 = tr_read<v_rd_off(D0, 2, 1)>(vb), l3 = tr_read<v_rd_off(D0, 3, 0)>(vb), h3 = tr_read<v_rd_off(D0, 3, 1)>(vb);
;   asm volatile("s_waitcnt lgkmcnt(0)" ::: "memory"); SCHEDB();
;     ...
;   od = __builtin_amdgcn_mfma_f32_32x32x16_bf16(pa0, PKV(l0, h0), od, 0, 0, 0);
;   od = __builtin_amdgcn_mfma_f32_32x32x16_bf16(pa1, PKV(l1, h1), od, 0, 0, 0);
;   od = __builtin_amdgcn_mfma_f32_32x32x16_bf16(pa2, PKV(l2, h2), od, 0, 0, 0);
;   od = __builtin_amdgcn_mfma_f32_32x32x16_bf16(pa3, PKV(l3, h3), od, 0, 0, 0);
;     ...
; }
; __device__ __forceinline__ void pv_d0(f32x16* o, int vb, bf16x8 pa0, bf16x8 pa1, bf16x8 pa2, bf16x8 pa3) {
;   pv_one<0>(o[0], vb, pa0, pa1, pa2, pa3); pv_one<1>(o[1], vb, pa0, pa1, pa2, pa3); pv_one<2>(o[2], vb, pa0, pa1, pa2, pa3); pv_one<3>(o[3], vb, pa0, pa1, pa2, pa3);
	v_mfma_f32_32x32x16_bf16 v[82:97], v[232:235], v[244:247], v[82:97]
	v_exp_f32_e32 v233, v216
	v_add_f32_e32 v150, v130, v150
	v_exp_f32_e32 v234, v217
	v_add_f32_e32 v150, v132, v150
	v_exp_f32_e32 v235, v229
	v_add_f32_e32 v150, v224, v150
	v_add_f32_e32 v150, v225, v150
	v_add_f32_e32 v150, v233, v150
	v_add_f32_e32 v150, v234, v150
	v_exp_f32_e32 v237, v151
	v_add_f32_e32 v150, v235, v150
	v_exp_f32_e32 v238, v152
	v_add_f32_e32 v150, v148, v150
	v_exp_f32_e32 v239, v153
	v_add_f32_e32 v150, v149, v150
	v_add_f32_e32 v150, v236, v150
	v_add_f32_e32 v150, v237, v150
	v_exp_f32_e32 v240, v230
	v_add_f32_e32 v150, v238, v150
	v_add_f32_e32 v150, v239, v150
	v_add_f32_e32 v150, v213, v150
	v_add_f32_e32 v150, v147, v150
	v_add_f32_e32 v150, v240, v150
	v_add_f32_e32 v150, v231, v150
	v_add_f32_e32 v229, v146, v150
	v_mov_b32_e32 v230, v229
	v_cvt_pk_bf16_f32 v150, v143, v145
	v_cvt_pk_bf16_f32 v151, v141, v144
	v_cvt_pk_bf16_f32 v152, v140, v142
	v_cvt_pk_bf16_f32 v153, v138, v139
	s_nop 1
	v_permlane32_swap_b32_e32 v229, v230
	v_permlane32_swap_b32_e32 v150, v152
	v_permlane32_swap_b32_e32 v151, v153
	v_cvt_pk_bf16_f32 v214, v135, v137
	v_cvt_pk_bf16_f32 v215, v134, v136
	v_cvt_pk_bf16_f32 v216, v131, v133
	v_cvt_pk_bf16_f32 v217, v130, v132
	v_cvt_pk_bf16_f32 v232, v224, v225
	v_cvt_pk_bf16_f32 v233, v233, v234
	v_cvt_pk_bf16_f32 v234, v235, v148
	v_cvt_pk_bf16_f32 v235, v149, v236
	v_cvt_pk_bf16_f32 v236, v237, v238
	v_cvt_pk_bf16_f32 v237, v239, v213
	v_cvt_pk_bf16_f32 v238, v147, v240
	v_cvt_pk_bf16_f32 v239, v231, v146
	s_nop 0
	v_permlane32_swap_b32_e32 v214, v216
	v_permlane32_swap_b32_e32 v215, v217
	v_permlane32_swap_b32_e32 v232, v234
	v_permlane32_swap_b32_e32 v233, v235
	v_permlane32_swap_b32_e32 v236, v238
	v_permlane32_swap_b32_e32 v237, v239
	v_add_co_u32_e32 v130, vcc, s36, v160
	s_nop 1
	v_addc_co_u32_e32 v131, vcc, 0, v161, vcc
	v_add_co_u32_e32 v134, vcc, s37, v160
	s_nop 1
	v_addc_co_u32_e32 v135, vcc, 0, v161, vcc
	v_add_co_u32_e32 v146, vcc, s38, v162
	global_load_dwordx4 v[130:133], v[130:131], off
	s_nop 0
	global_load_dwordx4 v[134:137], v[134:135], off
	v_addc_co_u32_e32 v147, vcc, 0, v163, vcc
	global_load_dwordx4 v[138:141], v[146:147], off
	global_load_dwordx4 v[142:145], v[146:147], off offset:128
	s_nop 0
	global_load_dwordx4 v[146:149], v[146:147], off offset:256
	ds_read_b64_tr_b16 v[160:161], v168 offset:0
	ds_read_b64_tr_b16 v[162:163], v168 offset:0x800
	ds_read_b64_tr_b16 v[240:241], v168 offset:0x1000
	ds_read_b64_tr_b16 v[242:243], v168 offset:0x1800
	ds_read_b64_tr_b16 v[244:245], v168 offset:0x2000
	ds_read_b64_tr_b16 v[246:247], v168 offset:0x2800
	ds_read_b64_tr_b16 v[248:249], v168 offset:0x3000
	ds_read_b64_tr_b16 v[250:251], v168 offset:0x3800
	s_waitcnt lgkmcnt(0)
	s_nop 0
	v_mfma_f32_32x32x16_bf16 v[2:17], v[150:153], v[160:163], v[2:17]
	ds_read_b64_tr_b16 v[160:161], v168 offset:0x200
	ds_read_b64_tr_b16 v[162:163], v168 offset:0xa00
	v_mfma_f32_32x32x16_bf16 v[2:17], v[214:217], v[240:243], v[2:17]
	ds_read_b64_tr_b16 v[240:241], v168 offset:0x1200
	ds_read_b64_tr_b16 v[242:243], v168 offset:0x1a00
	v_mfma_f32_32x32x16_bf16 v[2:17], v[232:235], v[244:247], v[2:17]
	ds_read_b64_tr_b16 v[244:245], v168 offset:0x2200
	ds_read_b64_tr_b16 v[246:247], v168 offset:0x2a00
	v_mfma_f32_32x32x16_bf16 v[2:17], v[236:239], v[248:251], v[2:17]
	ds_read_b64_tr_b16 v[248:249], v168 offset:0x3200
	ds_read_b64_tr_b16 v[250:251], v168 offset:0x3a00
	s_waitcnt lgkmcnt(0)
	v_mfma_f32_32x32x16_bf16 v[50:65], v[150:153], v[160:163], v[50:65]
	ds_read_b64_tr_b16 v[160:161], v168 offset:0x400
	ds_read_b64_tr_b16 v[162:163], v168 offset:0xc00
	v_mfma_f32_32x32x16_bf16 v[50:65], v[214:217], v[240:243], v[50:65]
	ds_read_b64_tr_b16 v[240:241], v168 offset:0x1400
	ds_read_b64_tr_b16 v[242:243], v168 offset:0x1c00
	v_mfma_f32_32x32x16_bf16 v[50:65], v[232:235], v[244:247], v[50:65]
	ds_read_b64_tr_b16 v[244:245], v168 offset:0x2400
	ds_read_b64_tr_b16 v[246:247], v168 offset:0x2c00
	v_mfma_f32_32x32x16_bf16 v[50:65], v[236:239], v[248:251], v[50:65]
	ds_read_b64_tr_b16 v[248:249], v168 offset:0x3400
	ds_read_b64_tr_b16 v[250:251], v168 offset:0x3c00
	s_waitcnt lgkmcnt(0)
	v_mfma_f32_32x32x16_bf16 v[34:49], v[150:153], v[160:163], v[34:49]
	ds_read_b64_tr_b16 v[160:161], v168 offset:0x600
	ds_read_b64_tr_b16 v[162:163], v168 offset:0xe00
	v_mfma_f32_32x32x16_bf16 v[34:49], v[214:217], v[240:243], v[34:49]
	ds_read_b64_tr_b16 v[240:241], v168 offset:0x1600
	ds_read_b64_tr_b16 v[242:243], v168 offset:0x1e00
	v_mfma_f32_32x32x16_bf16 v[34:49], v[232:235], v[244:247], v[34:49]
	ds_read_b64_tr_b16 v[244:245], v168 offset:0x2600
	ds_read_b64_tr_b16 v[246:247], v168 offset:0x2e00
	v_mfma_f32_32x32x16_bf16 v[34:49], v[236:239], v[248:251], v[34:49]
	ds_read_b64_tr_b16 v[248:249], v168 offset:0x3600
	ds_read_b64_tr_b16 v[250:251], v168 offset:0x3e00
	s_waitcnt lgkmcnt(0)
	v_mfma_f32_32x32x16_bf16 v[18:33], v[150:153], v[160:163], v[18:33]
	v_max_f32_e32 v150, v83, v83
	v_max_f32_e32 v151, v82, v82
	v_max_f32_e32 v150, v151, v150
	v_max3_f32 v150, v150, v84, v85
	v_max3_f32 v150, v150, v86, v87
	v_max3_f32 v150, v150, v88, v89
	v_max3_f32 v150, v150, v90, v91
	v_max3_f32 v150, v150, v92, v93
	v_max3_f32 v150, v150, v94, v95
	v_mfma_f32_32x32x16_bf16 v[18:33], v[214:217], v[240:243], v[18:33]
	v_max3_f32 v150, v150, v96, v97
	v_max3_f32 v150, v150, v66, v67
	v_max3_f32 v150, v150, v68, v69
	v_max3_f32 v150, v150, v70, v71
	v_max3_f32 v150, v150, v72, v73
	v_max3_f32 v150, v150, v74, v75
	v_max3_f32 v150, v150, v76, v77
	v_max3_f32 v150, v150, v78, v79
	v_mfma_f32_32x32x16_bf16 v[18:33], v[232:235], v[244:247], v[18:33]
	v_max3_f32 v150, v150, v80, v81
	v_mov_b32_e32 v151, v150
	s_nop 1
	v_permlane32_swap_b32_e32 v150, v151
	v_max_f32_e32 v151, v151, v151
	v_max_f32_e32 v150, v150, v150
	v_max_f32_e32 v150, v150, v151
	v_sub_f32_e32 v151, v150, v208
	v_cmp_ge_f32_e32 vcc, s2, v151
	v_max_f32_e32 v151, v208, v208
	v_max_f32_e32 v151, v151, v150
	v_mfma_f32_32x32x16_bf16 v[18:33], v[236:239], v[248:251], v[18:33]
	v_sub_f32_e32 v150, v208, v151
	v_mul_f32_e32 v150, 0x3fb8aa3b, v150
	v_exp_f32_e32 v150, v150
	s_cmp_eq_u64 vcc, exec
	s_cselect_b64 s[10:11], -1, 0
	s_waitcnt vmcnt(0)
	v_cndmask_b32_e64 v150, v150, 1.0, s[10:11]
	v_cmp_gt_f32_e32 vcc, 1.0, v150
	ds_write_b128 v173, v[138:141] offset:57344
	ds_write_b128 v173, v[142:145] offset:57472
	ds_write_b128 v173, v[146:149] offset:57600
	s_waitcnt lgkmcnt(0)
	s_barrier
; __device__ __forceinline__ void partialSM(f32x16& p0, f32x16& p1, float& m_reg, float& mn, float& alpha) {
;     ...
;   else { mn = fmaxf(m_reg, pmax); alpha = __builtin_amdgcn_exp2f((m_reg - mn) * C); m_reg = mn; }
;   float mnC = -mn * C;
; #pragma unroll
;   for (int r = 0; r < 16; ++r) p0[r] = fmaf(p0[r], C, mnC);
; #pragma unroll
;   for (int r = 0; r < 16; ++r) p1[r] = fmaf(p1[r], C, mnC);
; #pragma unroll
;   for (int r = 0; r < 16; ++r) p0[r] = __builtin_amdgcn_exp2f(p0[r]);
; }
	ds_write_b128 v174, v[130:133] offset:16384
	ds_write_b128 v175, v[134:137] offset:16384
	s_cbranch_vccz .LBB0_813
	s_and_saveexec_b64 s[14:15], s[8:9]
	ds_write_b32 v166, v150 offset:128
	s_or_b64 exec, exec, s[14:15]
	s_waitcnt lgkmcnt(0)
	v_add_u32_e32 v142, v155, v0
	ds_read_b128 v[130:133], v142 offset:224
	ds_read_b128 v[134:137], v142 offset:192
	ds_read_b128 v[138:141], v142 offset:160
	ds_read_b128 v[142:145], v142 offset:128
	s_waitcnt lgkmcnt(3)
	v_pk_mul_f32 v[14:15], v[14:15], v[130:131]
	s_waitcnt lgkmcnt(2)
	v_pk_mul_f32 v[10:11], v[10:11], v[134:135]
	s_waitcnt lgkmcnt(1)
	v_pk_mul_f32 v[6:7], v[6:7], v[138:139]
	v_pk_mul_f32 v[16:17], v[16:17], v[132:133]
	v_pk_mul_f32 v[12:13], v[12:13], v[136:137]
	v_pk_mul_f32 v[8:9], v[8:9], v[140:141]
	s_waitcnt lgkmcnt(0)
	v_pk_mul_f32 v[4:5], v[4:5], v[144:145]
	v_pk_mul_f32 v[2:3], v[2:3], v[142:143]
	v_pk_mul_f32 v[62:63], v[62:63], v[130:131]
	v_pk_mul_f32 v[58:59], v[58:59], v[134:135]
	v_pk_mul_f32 v[54:55], v[54:55], v[138:139]
	v_pk_mul_f32 v[64:65], v[64:65], v[132:133]
	v_pk_mul_f32 v[60:61], v[60:61], v[136:137]
	v_pk_mul_f32 v[56:57], v[56:57], v[140:141]
	v_pk_mul_f32 v[52:53], v[52:53], v[144:145]
	v_pk_mul_f32 v[50:51], v[50:51], v[142:143]
	v_pk_mul_f32 v[46:47], v[46:47], v[130:131]
	v_pk_mul_f32 v[42:43], v[42:43], v[134:135]
	v_pk_mul_f32 v[38:39], v[38:39], v[138:139]
	v_pk_mul_f32 v[48:49], v[48:49], v[132:133]
	v_pk_mul_f32 v[44:45], v[44:45], v[136:137]
	v_pk_mul_f32 v[40:41], v[40:41], v[140:141]
	v_pk_mul_f32 v[36:37], v[36:37], v[144:145]
	v_pk_mul_f32 v[34:35], v[34:35], v[142:143]
	v_pk_mul_f32 v[30:31], v[30:31], v[130:131]
	v_pk_mul_f32 v[26:27], v[26:27], v[134:135]
	v_pk_mul_f32 v[22:23], v[22:23], v[138:139]
	v_pk_mul_f32 v[32:33], v[32:33], v[132:133]
	v_pk_mul_f32 v[28:29], v[28:29], v[136:137]
	v_pk_mul_f32 v[24:25], v[24:25], v[140:141]
	v_pk_mul_f32 v[20:21], v[20:21], v[144:145]
	v_pk_mul_f32 v[18:19], v[18:19], v[142:143]
.LBB0_813:
	v_cndmask_b32_e64 v208, v151, v208, s[10:11]
	v_mul_f32_e32 v134, 0xbfb8aa3b, v208
	v_mov_b32_e32 v135, v134
	v_pk_fma_f32 v[142:143], v[66:67], s[84:85], v[134:135] op_sel_hi:[1,0,0]
	v_add_f32_e32 v66, v210, v211
	v_fmac_f32_e32 v66, v207, v167
	v_add_f32_e32 v167, v229, v230
	v_pk_fma_f32 v[140:141], v[68:69], s[84:85], v[134:135] op_sel_hi:[1,0,0]
	v_pk_fma_f32 v[136:137], v[70:71], s[84:85], v[134:135] op_sel_hi:[1,0,0]
	v_pk_fma_f32 v[132:133], v[72:73], s[84:85], v[134:135] op_sel_hi:[1,0,0]
	v_fmac_f32_e32 v167, v66, v212
	ds_read_b128 v[66:69], v172 offset:57344
	ds_read_b128 v[70:73], v204 offset:57344
	v_pk_fma_f32 v[130:131], v[74:75], s[84:85], v[134:135] op_sel_hi:[1,0,0]
	v_pk_fma_f32 v[144:145], v[76:77], s[84:85], v[134:135] op_sel_hi:[1,0,0]
	v_pk_fma_f32 v[138:139], v[78:79], s[84:85], v[134:135] op_sel_hi:[1,0,0]
	v_fmamk_f32 v82, v82, 0x3fb8aa3b, v134
	v_fmamk_f32 v83, v83, 0x3fb8aa3b, v134
	v_fmamk_f32 v84, v84, 0x3fb8aa3b, v134
	v_fmamk_f32 v85, v85, 0x3fb8aa3b, v134
	v_fmamk_f32 v86, v86, 0x3fb8aa3b, v134
	v_fmamk_f32 v87, v87, 0x3fb8aa3b, v134
	v_fmamk_f32 v88, v88, 0x3fb8aa3b, v134
	v_fmamk_f32 v89, v89, 0x3fb8aa3b, v134
	v_fmamk_f32 v90, v90, 0x3fb8aa3b, v134
	v_fmamk_f32 v91, v91, 0x3fb8aa3b, v134
	v_fmamk_f32 v92, v92, 0x3fb8aa3b, v134
	v_fmamk_f32 v93, v93, 0x3fb8aa3b, v134
	v_fmamk_f32 v94, v94, 0x3fb8aa3b, v134
	v_fmamk_f32 v95, v95, 0x3fb8aa3b, v134
	v_fmamk_f32 v96, v96, 0x3fb8aa3b, v134
	v_fmac_f32_e32 v135, 0x3fb8aa3b, v97
	v_exp_f32_e32 v215, v82
	v_exp_f32_e32 v217, v83
	v_exp_f32_e32 v151, v84
	v_exp_f32_e32 v216, v85
	v_exp_f32_e32 v152, v86
	v_exp_f32_e32 v214, v87
	v_exp_f32_e32 v153, v88
	v_exp_f32_e32 v213, v89
	v_exp_f32_e32 v161, v90
	v_exp_f32_e32 v163, v91
	v_exp_f32_e32 v160, v92
	v_exp_f32_e32 v162, v93
	v_exp_f32_e32 v147, v94
	v_exp_f32_e32 v149, v95
	v_exp_f32_e32 v146, v96
	v_exp_f32_e32 v148, v135
	v_pk_fma_f32 v[134:135], v[80:81], s[84:85], v[134:135] op_sel_hi:[1,0,0]
	s_add_i32 s13, s13, 2
	v_lshl_add_u64 v[156:157], v[156:157], 0, s[40:41]
	s_cmpk_gt_u32 s13, 0xfc
	v_lshl_add_u64 v[158:159], v[158:159], 0, s[42:43]
	s_cbranch_scc1 .LBB0_815
	v_mov_b32_e32 v207, v150
	s_branch .LBB0_805
.LBB0_815:
	s_waitcnt lgkmcnt(1)
	v_mfma_f32_32x32x16_bf16 v[82:97], v[66:69], v[126:129], 0
	s_waitcnt lgkmcnt(0)
	v_mfma_f32_32x32x16_bf16 v[66:81], v[70:73], v[126:129], 0
	ds_read_b128 v[126:129], v176 offset:57344
	ds_read_b128 v[156:159], v206 offset:57344
	s_waitcnt lgkmcnt(1)
	v_mfma_f32_32x32x16_bf16 v[82:97], v[126:129], v[122:125], v[82:97]
	s_waitcnt lgkmcnt(0)
	v_mfma_f32_32x32x16_bf16 v[66:81], v[156:159], v[122:125], v[66:81]
	ds_read_b128 v[122:125], v177 offset:57344
	ds_read_b128 v[126:129], v205 offset:57344
	s_waitcnt lgkmcnt(1)
	v_mfma_f32_32x32x16_bf16 v[82:97], v[122:125], v[118:121], v[82:97]
	s_waitcnt lgkmcnt(0)
	v_mfma_f32_32x32x16_bf16 v[66:81], v[126:129], v[118:121], v[66:81]
	ds_read_b128 v[118:121], v178 offset:57344
	ds_read_b128 v[122:125], v203 offset:57344
	s_waitcnt lgkmcnt(1)
	v_mfma_f32_32x32x16_bf16 v[82:97], v[118:121], v[114:117], v[82:97]
	s_waitcnt lgkmcnt(0)
	v_mfma_f32_32x32x16_bf16 v[66:81], v[122:125], v[114:117], v[66:81]
	ds_read_b128 v[114:117], v181 offset:57344
	ds_read_b128 v[118:121], v202 offset:57344
	v_exp_f32_e32 v122, v134
	v_exp_f32_e32 v123, v135
	s_waitcnt lgkmcnt(1)
	v_mfma_f32_32x32x16_bf16 v[82:97], v[114:117], v[110:113], v[82:97]
	s_waitcnt lgkmcnt(0)
	v_mfma_f32_32x32x16_bf16 v[66:81], v[118:121], v[110:113], v[66:81]
	ds_read_b128 v[110:113], v185 offset:57344
	ds_read_b128 v[114:117], v201 offset:57344
	v_exp_f32_e32 v118, v144
	v_exp_f32_e32 v119, v145
	v_exp_f32_e32 v120, v138
	v_exp_f32_e32 v121, v139
	s_waitcnt lgkmcnt(1)
; #define SCHEDB() __builtin_amdgcn_sched_barrier(0)
; __device__ __forceinline__ void finishSM(f32x16& p0, f32x16& p1, float alpha, float& l_reg, bf16x8& pa0, bf16x8& pa1, bf16x8& pa2, bf16x8& pa3) {
; #pragma unroll
;   for (int r = 0; r < 16; ++r) p1[r] = __builtin_amdgcn_exp2f(p1[r]);
;   float ps = 0;
; #pragma unroll
;   for (int r = 0; r < 16; ++r) ps += p0[r];
; #pragma unroll
;   for (int r = 0; r < 16; ++r) ps += p1[r];
;   { auto rr = __builtin_amdgcn_permlane32_swap(__float_as_uint(ps), __float_as_uint(ps), false, false);
;     ps = __uint_as_float(rr[0]) + __uint_as_float(rr[1]); }
;   l_reg = l_reg * alpha + ps;
;     ...
;   PK4(p0, 0, pa0); PK4(p0, 8, pa1); PK4(p1, 0, pa2); PK4(p1, 8, pa3);
; __device__ __forceinline__ void attn_body(const bfr* __restrict__ Qb, const bfr* __restrict__ Kh, const bfr* __restrict__ Vh, bfr* __restrict__ Ob, int seq) {
;     ...
;   SCHEDB(); qkt(pB0, pB1, K_lds + A_SHM_K, qr, qpe, r32, hi);
;   finishSM(pA0, pA1, alA, l_reg, pa0, pa1, pa2, pa3); SCHEDB();
;   pv_d0(o, vb0, pa0, pa1, pa2, pa3); partialSM(pB0, pB1, m_reg, mnB, alB);
	v_mfma_f32_32x32x16_bf16 v[82:97], v[110:113], v[106:109], v[82:97]
	s_waitcnt lgkmcnt(0)
	v_mfma_f32_32x32x16_bf16 v[66:81], v[114:117], v[106:109], v[66:81]
	ds_read_b128 v[106:109], v179 offset:57344
	ds_read_b128 v[110:113], v200 offset:57344
	v_exp_f32_e32 v114, v132
	v_exp_f32_e32 v115, v133
	v_exp_f32_e32 v116, v130
	v_exp_f32_e32 v117, v131
	s_waitcnt lgkmcnt(1)
	v_mfma_f32_32x32x16_bf16 v[82:97], v[106:109], v[102:105], v[82:97]
	s_waitcnt lgkmcnt(0)
	v_mfma_f32_32x32x16_bf16 v[66:81], v[110:113], v[102:105], v[66:81]
	ds_read_b128 v[102:105], v180 offset:57344
	ds_read_b128 v[106:109], v199 offset:57344
	v_exp_f32_e32 v110, v140
	v_exp_f32_e32 v111, v141
	v_exp_f32_e32 v112, v136
	v_exp_f32_e32 v113, v137
	s_waitcnt lgkmcnt(1)
	v_mfma_f32_32x32x16_bf16 v[82:97], v[102:105], v[98:101], v[82:97]
	s_waitcnt lgkmcnt(0)
	v_mfma_f32_32x32x16_bf16 v[66:81], v[106:109], v[98:101], v[66:81]
	ds_read_b128 v[98:101], v188 offset:57344
	ds_read_b128 v[102:105], v198 offset:57344
	ds_read_b128 v[106:109], v209
	s_waitcnt lgkmcnt(0)
	v_mfma_f32_32x32x16_bf16 v[82:97], v[98:101], v[106:109], v[82:97]
	v_mfma_f32_32x32x16_bf16 v[66:81], v[102:105], v[106:109], v[66:81]
	ds_read_b128 v[98:101], v192 offset:57344
	ds_read_b128 v[102:105], v197 offset:57344
	ds_read_b128 v[106:109], v209 offset:1024
	s_waitcnt lgkmcnt(0)
	v_mfma_f32_32x32x16_bf16 v[82:97], v[98:101], v[106:109], v[82:97]
	v_mfma_f32_32x32x16_bf16 v[66:81], v[102:105], v[106:109], v[66:81]
	ds_read_b128 v[98:101], v193 offset:57344
	ds_read_b128 v[102:105], v196 offset:57344
	ds_read_b128 v[106:109], v209 offset:2048
	s_waitcnt lgkmcnt(0)
	v_mfma_f32_32x32x16_bf16 v[82:97], v[98:101], v[106:109], v[82:97]
	v_mfma_f32_32x32x16_bf16 v[66:81], v[102:105], v[106:109], v[66:81]
	ds_read_b128 v[98:101], v195 offset:57344
	ds_read_b128 v[102:105], v194 offset:57344
	ds_read_b128 v[106:109], v209 offset:3072
	s_waitcnt lgkmcnt(0)
	v_mfma_f32_32x32x16_bf16 v[82:97], v[98:101], v[106:109], v[82:97]
	v_add_f32_e32 v98, 0, v215
	v_add_f32_e32 v98, v217, v98
	v_add_f32_e32 v98, v151, v98
	v_add_f32_e32 v98, v216, v98
	v_add_f32_e32 v98, v152, v98
	v_add_f32_e32 v98, v214, v98
	v_add_f32_e32 v98, v153, v98
	v_add_f32_e32 v98, v213, v98
	v_add_f32_e32 v98, v161, v98
	v_add_f32_e32 v98, v163, v98
	v_add_f32_e32 v98, v160, v98
	v_add_f32_e32 v98, v162, v98
	v_mfma_f32_32x32x16_bf16 v[66:81], v[102:105], v[106:109], v[66:81]
	v_exp_f32_e32 v108, v142
	v_add_f32_e32 v98, v147, v98
	v_exp_f32_e32 v109, v143
	v_add_f32_e32 v98, v149, v98
	v_add_f32_e32 v98, v146, v98
	v_add_f32_e32 v98, v148, v98
	v_add_f32_e32 v98, v108, v98
	v_add_f32_e32 v98, v109, v98
	v_add_f32_e32 v98, v110, v98
	v_add_f32_e32 v98, v111, v98
	v_add_f32_e32 v98, v112, v98
	v_add_f32_e32 v98, v113, v98
	v_add_f32_e32 v98, v114, v98
	v_add_f32_e32 v98, v115, v98
	v_add_f32_e32 v98, v116, v98
	v_add_f32_e32 v98, v117, v98
	v_add_f32_e32 v98, v118, v98
	v_add_f32_e32 v98, v119, v98
	v_add_f32_e32 v98, v120, v98
	v_add_f32_e32 v98, v121, v98
	v_add_f32_e32 v98, v122, v98
	v_add_f32_e32 v98, v123, v98
	v_mov_b32_e32 v99, v98
	v_cvt_pk_bf16_f32 v100, v215, v217
	v_cvt_pk_bf16_f32 v101, v151, v216
	v_cvt_pk_bf16_f32 v102, v152, v214
	v_cvt_pk_bf16_f32 v103, v153, v213
	s_nop 1
	v_permlane32_swap_b32_e32 v98, v99
	v_permlane32_swap_b32_e32 v100, v102
	v_permlane32_swap_b32_e32 v101, v103
	v_cvt_pk_bf16_f32 v104, v161, v163
	v_cvt_pk_bf16_f32 v105, v160, v162
	v_cvt_pk_bf16_f32 v106, v147, v149
	v_cvt_pk_bf16_f32 v107, v146, v148
	v_cvt_pk_bf16_f32 v108, v108, v109
	v_cvt_pk_bf16_f32 v109, v110, v111
	v_cvt_pk_bf16_f32 v110, v112, v113
	v_cvt_pk_bf16_f32 v111, v114, v115
	v_cvt_pk_bf16_f32 v112, v116, v117
	v_cvt_pk_bf16_f32 v113, v118, v119
	v_cvt_pk_bf16_f32 v114, v120, v121
	v_cvt_pk_bf16_f32 v115, v122, v123
	s_nop 0
	v_permlane32_swap_b32_e32 v104, v106
	v_permlane32_swap_b32_e32 v105, v107
	v_permlane32_swap_b32_e32 v108, v110
	v_permlane32_swap_b32_e32 v109, v111
	v_permlane32_swap_b32_e32 v112, v114
	v_permlane32_swap_b32_e32 v113, v115
	ds_read_b64_tr_b16 v[116:117], v169 offset:0
	ds_read_b64_tr_b16 v[118:119], v169 offset:0x800
	ds_read_b64_tr_b16 v[120:121], v169 offset:0x1000
	ds_read_b64_tr_b16 v[122:123], v169 offset:0x1800
	ds_read_b64_tr_b16 v[124:125], v169 offset:0x2000
	ds_read_b64_tr_b16 v[126:127], v169 offset:0x2800
	ds_read_b64_tr_b16 v[128:129], v169 offset:0x3000
	ds_read_b64_tr_b16 v[130:131], v169 offset:0x3800
	s_waitcnt lgkmcnt(0)
	s_nop 0
	v_mfma_f32_32x32x16_bf16 v[2:17], v[100:103], v[116:119], v[2:17]
	ds_read_b64_tr_b16 v[116:117], v169 offset:0x200
	ds_read_b64_tr_b16 v[118:119], v169 offset:0xa00
	v_mfma_f32_32x32x16_bf16 v[2:17], v[104:107], v[120:123], v[2:17]
	ds_read_b64_tr_b16 v[120:121], v169 offset:0x1200
	ds_read_b64_tr_b16 v[122:123], v169 offset:0x1a00
	v_mfma_f32_32x32x16_bf16 v[2:17], v[108:111], v[124:127], v[2:17]
	ds_read_b64_tr_b16 v[124:125], v169 offset:0x2200
	ds_read_b64_tr_b16 v[126:127], v169 offset:0x2a00
	v_mfma_f32_32x32x16_bf16 v[2:17], v[112:115], v[128:131], v[2:17]
	ds_read_b64_tr_b16 v[128:129], v169 offset:0x3200
	ds_read_b64_tr_b16 v[130:131], v169 offset:0x3a00
	s_waitcnt lgkmcnt(0)
; #define SCHEDB() __builtin_amdgcn_sched_barrier(0)
; #define RESC(a) do { if (__any((a) < 1.f)) { if (hi == 0) al_l[r32] = (a); asm volatile("s_waitcnt lgkmcnt(0)" ::: "memory"); \
;     _Pragma("unroll") for (int d = 0; d < 4; ++d) _Pragma("unroll") for (int r = 0; r < 16; ++r) o[d][r] *= al_l[crow(r, hi)]; } } while (0)
; template <int D0> __device__ __forceinline__ void pv_one(f32x16& od, int vb, bf16x8 pa0, bf16x8 pa1, bf16x8 pa2, bf16x8 pa3) {
;   const s16x4 l0 = tr_read<v_rd_off(D0, 0, 0)>(vb), h0 = tr_read<v_rd_off(D0, 0, 1)>(vb), l1 = tr_read<v_rd_off(D0, 1, 0)>(vb), h1 = tr_read<v_rd_off(D0, 1, 1)>(vb);
;   const s16x4 l2 = tr_read<v_rd_off(D0, 2, 0)>(vb), h2 = tr_read<v_rd_off(D0, 2, 1)>(vb), l3 = tr_read<v_rd_off(D0, 3, 0)>(vb), h3 = tr_read<v_rd_off(D0, 3, 1)>(vb);
;   asm volatile("s_waitcnt lgkmcnt(0)" ::: "memory"); SCHEDB();
;     ...
;   od = __builtin_amdgcn_mfma_f32_32x32x16_bf16(pa0, PKV(l0, h0), od, 0, 0, 0);
;   od = __builtin_amdgcn_mfma_f32_32x32x16_bf16(pa1, PKV(l1, h1), od, 0, 0, 0);
;   od = __builtin_amdgcn_mfma_f32_32x32x16_bf16(pa2, PKV(l2, h2), od, 0, 0, 0);
;   od = __builtin_amdgcn_mfma_f32_32x32x16_bf16(pa3, PKV(l3, h3), od, 0, 0, 0);
;     ...
; }
; __device__ __forceinline__ void pv_d0(f32x16* o, int vb, bf16x8 pa0, bf16x8 pa1, bf16x8 pa2, bf16x8 pa3) {
;   pv_one<0>(o[0], vb, pa0, pa1, pa2, pa3); pv_one<1>(o[1], vb, pa0, pa1, pa2, pa3); pv_one<2>(o[2], vb, pa0, pa1, pa2, pa3); pv_one<3>(o[3], vb, pa0, pa1, pa2, pa3);
; __device__ __forceinline__ void attn_body(const bfr* __restrict__ Qb, const bfr* __restrict__ Kh, const bfr* __restrict__ Vh, bfr* __restrict__ Ob, int seq) {
;     ...
;   pv_d0(o, vb0, pa0, pa1, pa2, pa3); partialSM(pB0, pB1, m_reg, mnB, alB);
;   __syncthreads(); RESC(alB);
	v_mfma_f32_32x32x16_bf16 v[50:65], v[100:103], v[116:119], v[50:65]
	ds_read_b64_tr_b16 v[116:117], v169 offset:0x400
	ds_read_b64_tr_b16 v[118:119], v169 offset:0xc00
	v_mfma_f32_32x32x16_bf16 v[50:65], v[104:107], v[120:123], v[50:65]
	ds_read_b64_tr_b16 v[120:121], v169 offset:0x1400
	ds_read_b64_tr_b16 v[122:123], v169 offset:0x1c00
	v_mfma_f32_32x32x16_bf16 v[50:65], v[108:111], v[124:127], v[50:65]
	ds_read_b64_tr_b16 v[124:125], v169 offset:0x2400
	ds_read_b64_tr_b16 v[126:127], v169 offset:0x2c00
	v_mfma_f32_32x32x16_bf16 v[50:65], v[112:115], v[128:131], v[50:65]
	ds_read_b64_tr_b16 v[128:129], v169 offset:0x3400
	ds_read_b64_tr_b16 v[130:131], v169 offset:0x3c00
	s_waitcnt lgkmcnt(0)
	v_mfma_f32_32x32x16_bf16 v[34:49], v[100:103], v[116:119], v[34:49]
	ds_read_b64_tr_b16 v[116:117], v169 offset:0x600
	ds_read_b64_tr_b16 v[118:119], v169 offset:0xe00
	v_mfma_f32_32x32x16_bf16 v[34:49], v[104:107], v[120:123], v[34:49]
	ds_read_b64_tr_b16 v[120:121], v169 offset:0x1600
	ds_read_b64_tr_b16 v[122:123], v169 offset:0x1e00
	v_mfma_f32_32x32x16_bf16 v[34:49], v[108:111], v[124:127], v[34:49]
	ds_read_b64_tr_b16 v[124:125], v169 offset:0x2600
	ds_read_b64_tr_b16 v[126:127], v169 offset:0x2e00
	v_mfma_f32_32x32x16_bf16 v[34:49], v[112:115], v[128:131], v[34:49]
	ds_read_b64_tr_b16 v[128:129], v169 offset:0x3600
	ds_read_b64_tr_b16 v[130:131], v169 offset:0x3e00
	s_waitcnt lgkmcnt(0)
	v_mfma_f32_32x32x16_bf16 v[18:33], v[100:103], v[116:119], v[18:33]
	v_max_f32_e32 v100, v83, v83
	v_max_f32_e32 v101, v82, v82
	v_max_f32_e32 v100, v101, v100
	v_max3_f32 v100, v100, v84, v85
	v_max3_f32 v100, v100, v86, v87
	v_max3_f32 v100, v100, v88, v89
	v_max3_f32 v100, v100, v90, v91
	v_max3_f32 v100, v100, v92, v93
	v_max3_f32 v100, v100, v94, v95
	v_mfma_f32_32x32x16_bf16 v[18:33], v[104:107], v[120:123], v[18:33]
	v_max3_f32 v100, v100, v96, v97
	v_max3_f32 v100, v100, v66, v67
	v_max3_f32 v100, v100, v68, v69
	v_max3_f32 v100, v100, v70, v71
	v_max3_f32 v100, v100, v72, v73
	v_max3_f32 v100, v100, v74, v75
	v_max3_f32 v100, v100, v76, v77
	v_max3_f32 v100, v100, v78, v79
	v_mfma_f32_32x32x16_bf16 v[18:33], v[108:111], v[124:127], v[18:33]
	v_max3_f32 v100, v100, v80, v81
	v_mov_b32_e32 v101, v100
	s_nop 1
	v_permlane32_swap_b32_e32 v100, v101
	v_max_f32_e32 v101, v101, v101
	v_max_f32_e32 v100, v100, v100
	v_max_f32_e32 v100, v100, v101
	v_sub_f32_e32 v101, v100, v208
	v_cmp_ge_f32_e32 vcc, s2, v101
	v_max_f32_e32 v101, v208, v208
	v_max_f32_e32 v101, v101, v100
	v_mfma_f32_32x32x16_bf16 v[18:33], v[112:115], v[128:131], v[18:33]
	v_sub_f32_e32 v100, v208, v101
	v_mul_f32_e32 v100, 0x3fb8aa3b, v100
	v_exp_f32_e32 v100, v100
	s_cmp_eq_u64 vcc, exec
	s_cselect_b64 s[10:11], -1, 0
	v_cndmask_b32_e64 v100, v100, 1.0, s[10:11]
	v_cmp_gt_f32_e32 vcc, 1.0, v100
	s_barrier
	s_cbranch_vccz .LBB0_819
	s_and_saveexec_b64 s[14:15], s[8:9]
	ds_write_b32 v166, v100 offset:128
	s_or_b64 exec, exec, s[14:15]
	s_waitcnt lgkmcnt(0)
	v_add_u32_e32 v114, v155, v0
	ds_read_b128 v[102:105], v114 offset:224
	ds_read_b128 v[106:109], v114 offset:192
	ds_read_b128 v[110:113], v114 offset:160
	ds_read_b128 v[114:117], v114 offset:128
	s_waitcnt lgkmcnt(3)
	v_pk_mul_f32 v[14:15], v[14:15], v[102:103]
	s_waitcnt lgkmcnt(2)
	v_pk_mul_f32 v[10:11], v[10:11], v[106:107]
	s_waitcnt lgkmcnt(1)
	v_pk_mul_f32 v[6:7], v[6:7], v[110:111]
	v_pk_mul_f32 v[16:17], v[16:17], v[104:105]
	v_pk_mul_f32 v[12:13], v[12:13], v[108:109]
	v_pk_mul_f32 v[8:9], v[8:9], v[112:113]
	s_waitcnt lgkmcnt(0)
	v_pk_mul_f32 v[4:5], v[4:5], v[116:117]
	v_pk_mul_f32 v[2:3], v[2:3], v[114:115]
	v_pk_mul_f32 v[62:63], v[62:63], v[102:103]
	v_pk_mul_f32 v[58:59], v[58:59], v[106:107]
	v_pk_mul_f32 v[54:55], v[54:55], v[110:111]
	v_pk_mul_f32 v[64:65], v[64:65], v[104:105]
	v_pk_mul_f32 v[60:61], v[60:61], v[108:109]
	v_pk_mul_f32 v[56:57], v[56:57], v[112:113]
	v_pk_mul_f32 v[52:53], v[52:53], v[116:117]
	v_pk_mul_f32 v[50:51], v[50:51], v[114:115]
	v_pk_mul_f32 v[46:47], v[46:47], v[102:103]
	v_pk_mul_f32 v[42:43], v[42:43], v[106:107]
	v_pk_mul_f32 v[38:39], v[38:39], v[110:111]
	v_pk_mul_f32 v[48:49], v[48:49], v[104:105]
	v_pk_mul_f32 v[44:45], v[44:45], v[108:109]
	v_pk_mul_f32 v[40:41], v[40:41], v[112:113]
	v_pk_mul_f32 v[36:37], v[36:37], v[116:117]
	v_pk_mul_f32 v[34:35], v[34:35], v[114:115]
	v_pk_mul_f32 v[30:31], v[30:31], v[102:103]
	v_pk_mul_f32 v[26:27], v[26:27], v[106:107]
	v_pk_mul_f32 v[22:23], v[22:23], v[110:111]
	v_pk_mul_f32 v[32:33], v[32:33], v[104:105]
	v_pk_mul_f32 v[28:29], v[28:29], v[108:109]
	v_pk_mul_f32 v[24:25], v[24:25], v[112:113]
	v_pk_mul_f32 v[20:21], v[20:21], v[116:117]
	v_pk_mul_f32 v[18:19], v[18:19], v[114:115]

.LBB0_1433:
	v_readlane_b32 s20, v255, 15
	v_readlane_b32 s21, v255, 16
	s_load_dwordx2 s[20:21], s[20:21], 0x80
	s_ashr_i32 s22, s39, 2
	s_ashr_i32 s23, s22, 31
	s_lshl_b64 s[40:41], s[22:23], 19
	v_lshl_add_u64 v[136:137], v[206:207], 0, s[40:41]
	s_waitcnt lgkmcnt(0)
	s_add_u32 s2, s20, s31
	s_addc_u32 s19, s21, 0
	s_lshl_b32 s20, s39, 8
	s_and_b32 s20, s20, 0x300
	v_add_u32_e32 v14, s20, v230
	s_lshl_b32 s21, s22, 4
	v_lshl_or_b32 v138, v14, 4, v229
	s_and_b32 s21, s21, 0x3f0
	v_ashrrev_i32_e32 v139, 31, v138
	v_lshlrev_b64 v[14:15], 5, v[138:139]
	s_lshl_b32 s22, s21, 2
	v_lshl_add_u64 v[14:15], v[136:137], 0, v[14:15]
	s_add_u32 s22, s2, s22
	v_mov_b64_e32 v[180:181], v[14:15]
	s_addc_u32 s23, s19, 0
	global_load_dwordx4 v[14:17], v246, s[22:23]
	global_load_dwordx2 v[152:153], v[180:181], off
	global_load_dwordx2 v[154:155], v[180:181], off offset:32
	global_load_dwordx2 v[156:157], v[180:181], off offset:64
	global_load_dwordx2 v[158:159], v[180:181], off offset:96
	v_add_co_u32_e32 v180, vcc, 0x2000, v180
	s_nop 1
	v_addc_co_u32_e32 v181, vcc, 0, v181, vcc
	global_load_dwordx2 v[160:161], v[180:181], off
	global_load_dwordx2 v[162:163], v[180:181], off offset:32
	global_load_dwordx2 v[164:165], v[180:181], off offset:64
	global_load_dwordx2 v[166:167], v[180:181], off offset:96
	v_add_co_u32_e32 v180, vcc, 0x2000, v180
	s_nop 1
	v_addc_co_u32_e32 v181, vcc, 0, v181, vcc
	global_load_dwordx2 v[168:169], v[180:181], off
	global_load_dwordx2 v[170:171], v[180:181], off offset:32
	global_load_dwordx2 v[172:173], v[180:181], off offset:64
	global_load_dwordx2 v[174:175], v[180:181], off offset:96
	v_add_co_u32_e32 v180, vcc, 0x2000, v180
	s_nop 1
	v_addc_co_u32_e32 v181, vcc, 0, v181, vcc
	global_load_dwordx2 v[176:177], v[180:181], off
	global_load_dwordx2 v[178:179], v[180:181], off offset:32
	v_or_b32_e32 v142, 1, v138
	v_ashrrev_i32_e32 v143, 31, v142
	v_lshlrev_b64 v[146:147], 5, v[142:143]
	s_lshl_b32 s2, s39, 6
	s_and_b32 s19, s2, 0xffffc000
	v_add_u32_e32 v144, s19, v138
	s_lshl_b32 s68, s21, 1
	v_ashrrev_i32_e32 v145, 31, v144
	v_lshl_add_u64 v[134:135], v[208:209], 0, s[68:69]
	v_lshlrev_b64 v[144:145], 11, v[144:145]
	v_lshl_add_u64 v[144:145], v[134:135], 0, v[144:145]
	v_lshl_add_u64 v[146:147], v[136:137], 0, v[146:147]
	s_waitcnt vmcnt(13)
	v_mov_b64_e32 v[140:141], v[152:153]
	global_load_dwordx2 v[152:153], v[180:181], off offset:64
	v_lshlrev_b32_e32 v139, 16, v140
	v_and_b32_e32 v140, 0xffff0000, v140
	v_lshlrev_b32_e32 v143, 16, v141
	v_and_b32_e32 v141, 0xffff0000, v141
	v_fmac_f32_e32 v130, v14, v139
	v_fmac_f32_e32 v131, v15, v140
	v_fmac_f32_e32 v132, v16, v143
	v_fmac_f32_e32 v133, v17, v141
	v_mul_f32_e32 v139, 0x3d372713, v130
	v_mul_f32_e32 v141, 0x3d372713, v131
	v_mul_f32_e32 v148, 0x3d372713, v132
	v_mul_f32_e32 v150, 0x3d372713, v133
	v_mul_f32_e32 v139, v130, v139
	v_mul_f32_e32 v141, v131, v141
	v_mul_f32_e32 v140, 0.5, v130
	v_mul_f32_e32 v143, 0.5, v131
	v_mul_f32_e32 v148, v132, v148
	v_mul_f32_e32 v150, v133, v150
	v_fma_f32 v130, v130, v139, v130
	v_fma_f32 v131, v131, v141, v131
	v_mul_f32_e32 v149, 0.5, v132
	v_mul_f32_e32 v151, 0.5, v133
	v_fma_f32 v132, v132, v148, v132
	v_fma_f32 v133, v133, v150, v133
	v_mul_f32_e32 v130, 0x3f4c422a, v130
	v_mul_f32_e32 v131, 0x3f4c422a, v131
	v_mul_f32_e32 v132, 0x3f4c422a, v132
	v_mul_f32_e32 v133, 0x3f4c422a, v133
	v_add_f32_e32 v130, v130, v130
	v_add_f32_e32 v131, v131, v131
	v_add_f32_e32 v132, v132, v132
	v_add_f32_e32 v133, v133, v133
	v_mul_f32_e32 v130, 0x3fb8aa3b, v130
	v_mul_f32_e32 v131, 0x3fb8aa3b, v131
	v_mul_f32_e32 v132, 0x3fb8aa3b, v132
	v_mul_f32_e32 v133, 0x3fb8aa3b, v133
	v_exp_f32_e32 v130, v130
	v_exp_f32_e32 v131, v131
	v_exp_f32_e32 v132, v132
	v_exp_f32_e32 v133, v133
	v_add_f32_e32 v130, 1.0, v130
	v_add_f32_e32 v131, 1.0, v131
	v_add_f32_e32 v132, 1.0, v132
	v_add_f32_e32 v133, 1.0, v133
	v_rcp_f32_e32 v130, v130
	v_rcp_f32_e32 v131, v131
	v_rcp_f32_e32 v132, v132
	v_rcp_f32_e32 v133, v133
	v_fma_f32 v130, v130, -2.0, 1.0
	v_fma_f32 v131, v131, -2.0, 1.0
	v_fma_f32 v132, v132, -2.0, 1.0
	v_fma_f32 v133, v133, -2.0, 1.0
	v_add_f32_e32 v130, 1.0, v130
	v_add_f32_e32 v131, 1.0, v131
	v_add_f32_e32 v132, 1.0, v132
	v_add_f32_e32 v133, 1.0, v133
	v_mul_f32_e32 v130, v140, v130
	v_mul_f32_e32 v131, v143, v131
	v_mul_f32_e32 v132, v149, v132
	v_mul_f32_e32 v133, v151, v133
	v_cvt_pk_bf16_f32 v130, v130, v131
	v_cvt_pk_bf16_f32 v131, v132, v133
	global_store_dwordx2 v[144:145], v[130:131], off
	s_waitcnt vmcnt(14)
	v_mov_b64_e32 v[130:131], v[154:155]
	global_load_dwordx2 v[154:155], v[180:181], off offset:96
	v_add_co_u32_e32 v180, vcc, 0x2000, v180
	s_nop 1
	v_addc_co_u32_e32 v181, vcc, 0, v181, vcc
	v_or_b32_e32 v132, 2, v138
	v_ashrrev_i32_e32 v133, 31, v132
	v_add_u32_e32 v140, s19, v142
	v_lshlrev_b64 v[142:143], 5, v[132:133]
	v_ashrrev_i32_e32 v141, 31, v140
	v_lshlrev_b64 v[140:141], 11, v[140:141]
	v_lshl_add_u64 v[140:141], v[134:135], 0, v[140:141]
	v_lshl_add_u64 v[142:143], v[136:137], 0, v[142:143]
	v_lshlrev_b32_e32 v133, 16, v130
	v_and_b32_e32 v130, 0xffff0000, v130
	v_lshlrev_b32_e32 v139, 16, v131
	v_and_b32_e32 v131, 0xffff0000, v131
	v_fmac_f32_e32 v126, v14, v133
	v_fmac_f32_e32 v127, v15, v130
	v_fmac_f32_e32 v128, v16, v139
	v_fmac_f32_e32 v129, v17, v131
	v_mul_f32_e32 v130, 0x3d372713, v126
	v_mul_f32_e32 v133, 0x3d372713, v127
	v_mul_f32_e32 v144, 0x3d372713, v128
	v_mul_f32_e32 v146, 0x3d372713, v129
	v_mul_f32_e32 v130, v126, v130
	v_mul_f32_e32 v133, v127, v133
	v_mul_f32_e32 v131, 0.5, v126
	v_mul_f32_e32 v139, 0.5, v127
	v_mul_f32_e32 v144, v128, v144
	v_mul_f32_e32 v146, v129, v146
	v_fma_f32 v126, v126, v130, v126
	v_fma_f32 v127, v127, v133, v127
	v_mul_f32_e32 v145, 0.5, v128
	v_mul_f32_e32 v147, 0.5, v129
	v_fma_f32 v128, v128, v144, v128
	v_fma_f32 v129, v129, v146, v129
	v_mul_f32_e32 v126, 0x3f4c422a, v126
	v_mul_f32_e32 v127, 0x3f4c422a, v127
	v_mul_f32_e32 v128, 0x3f4c422a, v128
	v_mul_f32_e32 v129, 0x3f4c422a, v129
	v_add_f32_e32 v126, v126, v126
	v_add_f32_e32 v127, v127, v127
	v_add_f32_e32 v128, v128, v128
	v_add_f32_e32 v129, v129, v129
	v_mul_f32_e32 v126, 0x3fb8aa3b, v126
	v_mul_f32_e32 v127, 0x3fb8aa3b, v127
	v_mul_f32_e32 v128, 0x3fb8aa3b, v128
	v_mul_f32_e32 v129, 0x3fb8aa3b, v129
	v_exp_f32_e32 v126, v126
	v_exp_f32_e32 v127, v127
	v_exp_f32_e32 v128, v128
	v_exp_f32_e32 v129, v129
	v_add_f32_e32 v126, 1.0, v126
	v_add_f32_e32 v127, 1.0, v127
	v_add_f32_e32 v128, 1.0, v128
	v_add_f32_e32 v129, 1.0, v129
	v_rcp_f32_e32 v126, v126
	v_rcp_f32_e32 v127, v127
	v_rcp_f32_e32 v128, v128
	v_rcp_f32_e32 v129, v129
	v_fma_f32 v126, v126, -2.0, 1.0
	v_fma_f32 v127, v127, -2.0, 1.0
	v_fma_f32 v128, v128, -2.0, 1.0
	v_fma_f32 v129, v129, -2.0, 1.0
	v_add_f32_e32 v126, 1.0, v126
	v_add_f32_e32 v127, 1.0, v127
	v_add_f32_e32 v128, 1.0, v128
	v_add_f32_e32 v129, 1.0, v129
	v_mul_f32_e32 v126, v131, v126
	v_mul_f32_e32 v127, v139, v127
	v_mul_f32_e32 v128, v145, v128
	v_mul_f32_e32 v129, v147, v129
	v_cvt_pk_bf16_f32 v126, v126, v127
	v_cvt_pk_bf16_f32 v127, v128, v129
	global_store_dwordx2 v[140:141], v[126:127], off
	s_waitcnt vmcnt(15)
	v_mov_b64_e32 v[126:127], v[156:157]
	global_load_dwordx2 v[156:157], v[180:181], off
	v_or_b32_e32 v128, 3, v138
	v_ashrrev_i32_e32 v129, 31, v128
	v_add_u32_e32 v130, s19, v132
	v_lshlrev_b64 v[132:133], 5, v[128:129]
	v_ashrrev_i32_e32 v131, 31, v130
	v_lshlrev_b64 v[130:131], 11, v[130:131]
	v_lshl_add_u64 v[130:131], v[134:135], 0, v[130:131]
	v_lshl_add_u64 v[132:133], v[136:137], 0, v[132:133]
	v_lshlrev_b32_e32 v129, 16, v126
	v_and_b32_e32 v126, 0xffff0000, v126
	v_lshlrev_b32_e32 v138, 16, v127
	v_and_b32_e32 v127, 0xffff0000, v127
	v_fmac_f32_e32 v122, v14, v129
	v_fmac_f32_e32 v123, v15, v126
	v_fmac_f32_e32 v124, v16, v138
	v_fmac_f32_e32 v125, v17, v127
	v_mul_f32_e32 v126, 0x3d372713, v122
	v_mul_f32_e32 v129, 0x3d372713, v123
	v_mul_f32_e32 v139, 0x3d372713, v124
	v_mul_f32_e32 v141, 0x3d372713, v125
	v_mul_f32_e32 v126, v122, v126
	v_mul_f32_e32 v129, v123, v129
	v_mul_f32_e32 v127, 0.5, v122
	v_mul_f32_e32 v138, 0.5, v123
	v_mul_f32_e32 v139, v124, v139
	v_mul_f32_e32 v141, v125, v141
	v_fma_f32 v122, v122, v126, v122
	v_fma_f32 v123, v123, v129, v123
	v_mul_f32_e32 v140, 0.5, v124
	v_mul_f32_e32 v142, 0.5, v125
	v_fma_f32 v124, v124, v139, v124
	v_fma_f32 v125, v125, v141, v125
	v_mul_f32_e32 v122, 0x3f4c422a, v122
	v_mul_f32_e32 v123, 0x3f4c422a, v123
	v_mul_f32_e32 v124, 0x3f4c422a, v124
	v_mul_f32_e32 v125, 0x3f4c422a, v125
	v_add_f32_e32 v122, v122, v122
	v_add_f32_e32 v123, v123, v123
	v_add_f32_e32 v124, v124, v124
	v_add_f32_e32 v125, v125, v125
	v_mul_f32_e32 v122, 0x3fb8aa3b, v122
	v_mul_f32_e32 v123, 0x3fb8aa3b, v123
	v_mul_f32_e32 v124, 0x3fb8aa3b, v124
	v_mul_f32_e32 v125, 0x3fb8aa3b, v125
	v_exp_f32_e32 v122, v122
	v_exp_f32_e32 v123, v123
	v_exp_f32_e32 v124, v124
	v_exp_f32_e32 v125, v125
	v_add_f32_e32 v122, 1.0, v122
	v_add_f32_e32 v123, 1.0, v123
	v_add_f32_e32 v124, 1.0, v124
	v_add_f32_e32 v125, 1.0, v125
	v_rcp_f32_e32 v122, v122
	v_rcp_f32_e32 v123, v123
	v_rcp_f32_e32 v124, v124
	v_rcp_f32_e32 v125, v125
	v_fma_f32 v122, v122, -2.0, 1.0
	v_fma_f32 v123, v123, -2.0, 1.0
	v_fma_f32 v124, v124, -2.0, 1.0
	v_fma_f32 v125, v125, -2.0, 1.0
	v_add_f32_e32 v122, 1.0, v122
	v_add_f32_e32 v123, 1.0, v123
	v_add_f32_e32 v124, 1.0, v124
	v_add_f32_e32 v125, 1.0, v125
	v_mul_f32_e32 v122, v127, v122
	v_mul_f32_e32 v123, v138, v123
	v_mul_f32_e32 v124, v140, v124
	v_mul_f32_e32 v125, v142, v125
	v_cvt_pk_bf16_f32 v122, v122, v123
	v_cvt_pk_bf16_f32 v123, v124, v125
	global_store_dwordx2 v[130:131], v[122:123], off
	s_waitcnt vmcnt(16)
	v_mov_b64_e32 v[122:123], v[158:159]
	global_load_dwordx2 v[158:159], v[180:181], off offset:32
	v_add_u32_e32 v124, s19, v128
	v_ashrrev_i32_e32 v125, 31, v124
	v_lshlrev_b64 v[124:125], 11, v[124:125]
	v_lshlrev_b32_e32 v126, 16, v122
	v_and_b32_e32 v122, 0xffff0000, v122
	v_lshlrev_b32_e32 v127, 16, v123
	v_and_b32_e32 v123, 0xffff0000, v123
	v_fmac_f32_e32 v118, v14, v126
	v_fmac_f32_e32 v119, v15, v122
	v_fmac_f32_e32 v120, v16, v127
	v_fmac_f32_e32 v121, v17, v123
	v_mul_f32_e32 v122, 0x3d372713, v118
	v_mul_f32_e32 v126, 0x3d372713, v119
	v_mul_f32_e32 v128, 0x3d372713, v120
	v_mul_f32_e32 v130, 0x3d372713, v121
	v_mul_f32_e32 v122, v118, v122
	v_mul_f32_e32 v126, v119, v126
	v_mul_f32_e32 v128, v120, v128
	v_mul_f32_e32 v130, v121, v130
	v_mul_f32_e32 v123, 0.5, v118
	v_mul_f32_e32 v127, 0.5, v119
	v_mul_f32_e32 v129, 0.5, v120
	v_mul_f32_e32 v131, 0.5, v121
	v_fma_f32 v118, v118, v122, v118
	v_fma_f32 v119, v119, v126, v119
	v_fma_f32 v120, v120, v128, v120
	v_fma_f32 v121, v121, v130, v121
	v_mul_f32_e32 v118, 0x3f4c422a, v118
	v_mul_f32_e32 v119, 0x3f4c422a, v119
	v_mul_f32_e32 v120, 0x3f4c422a, v120
	v_mul_f32_e32 v121, 0x3f4c422a, v121
	v_add_f32_e32 v118, v118, v118
	v_add_f32_e32 v119, v119, v119
	v_add_f32_e32 v120, v120, v120
	v_add_f32_e32 v121, v121, v121
	v_mul_f32_e32 v118, 0x3fb8aa3b, v118
	v_mul_f32_e32 v119, 0x3fb8aa3b, v119
	v_mul_f32_e32 v120, 0x3fb8aa3b, v120
	v_mul_f32_e32 v121, 0x3fb8aa3b, v121
	v_exp_f32_e32 v118, v118
	v_exp_f32_e32 v119, v119
	v_exp_f32_e32 v120, v120
	v_exp_f32_e32 v121, v121
	v_add_f32_e32 v118, 1.0, v118
	v_add_f32_e32 v119, 1.0, v119
	v_add_f32_e32 v120, 1.0, v120
	v_add_f32_e32 v121, 1.0, v121
	v_rcp_f32_e32 v118, v118
	v_rcp_f32_e32 v119, v119
	v_rcp_f32_e32 v120, v120
	v_rcp_f32_e32 v121, v121
	v_fma_f32 v118, v118, -2.0, 1.0
	v_fma_f32 v119, v119, -2.0, 1.0
	v_fma_f32 v120, v120, -2.0, 1.0
	v_fma_f32 v121, v121, -2.0, 1.0
	v_add_f32_e32 v118, 1.0, v118
	v_add_f32_e32 v119, 1.0, v119
	v_add_f32_e32 v120, 1.0, v120
	v_add_f32_e32 v121, 1.0, v121
	v_mul_f32_e32 v118, v123, v118
	v_mul_f32_e32 v119, v127, v119
	v_mul_f32_e32 v120, v129, v120
	v_mul_f32_e32 v121, v131, v121
	v_cvt_pk_bf16_f32 v118, v118, v119
	v_cvt_pk_bf16_f32 v119, v120, v121
	v_lshl_add_u64 v[120:121], v[134:135], 0, v[124:125]
	global_store_dwordx2 v[120:121], v[118:119], off
	v_or_b32_e32 v118, 16, v230
	v_add_u32_e32 v118, s20, v118
	v_lshl_or_b32 v118, v118, 4, v229
	v_ashrrev_i32_e32 v119, 31, v118
	v_lshlrev_b64 v[120:121], 5, v[118:119]
	v_lshl_add_u64 v[120:121], v[136:137], 0, v[120:121]
	s_waitcnt vmcnt(17)
	v_mov_b64_e32 v[120:121], v[160:161]
	global_load_dwordx2 v[160:161], v[180:181], off offset:64
	v_lshlrev_b32_e32 v119, 16, v120
	v_fmac_f32_e32 v114, v14, v119
	v_mul_f32_e32 v119, 0x3d372713, v114
	v_mul_f32_e32 v119, v114, v119
	v_fma_f32 v119, v114, v119, v114
	v_mul_f32_e32 v119, 0x3f4c422a, v119
	v_add_f32_e32 v119, v119, v119
	v_mul_f32_e32 v119, 0x3fb8aa3b, v119
	v_exp_f32_e32 v119, v119
	v_mul_f32_e32 v114, 0.5, v114
	v_add_f32_e32 v119, 1.0, v119
	v_rcp_f32_e32 v119, v119
	s_nop 0
	v_fma_f32 v119, v119, -2.0, 1.0
	v_add_f32_e32 v119, 1.0, v119
	v_mul_f32_e32 v114, v114, v119
	v_and_b32_e32 v119, 0xffff0000, v120
	v_fmac_f32_e32 v115, v15, v119
	v_mul_f32_e32 v119, 0x3d372713, v115
	v_mul_f32_e32 v119, v115, v119
	v_fma_f32 v119, v115, v119, v115
	v_mul_f32_e32 v119, 0x3f4c422a, v119
	v_add_f32_e32 v119, v119, v119
	v_mul_f32_e32 v119, 0x3fb8aa3b, v119
	v_exp_f32_e32 v119, v119
	v_mul_f32_e32 v115, 0.5, v115
	v_add_f32_e32 v119, 1.0, v119
	v_rcp_f32_e32 v119, v119
	s_nop 0
	v_fma_f32 v119, v119, -2.0, 1.0
	v_add_f32_e32 v119, 1.0, v119
	v_mul_f32_e32 v115, v115, v119
	v_lshlrev_b32_e32 v119, 16, v121
	v_fmac_f32_e32 v116, v16, v119
	v_mul_f32_e32 v119, 0x3d372713, v116
	v_mul_f32_e32 v119, v116, v119
	v_fma_f32 v119, v116, v119, v116
	v_mul_f32_e32 v119, 0x3f4c422a, v119
	v_add_f32_e32 v119, v119, v119
	v_mul_f32_e32 v119, 0x3fb8aa3b, v119
	v_exp_f32_e32 v119, v119
	v_mul_f32_e32 v116, 0.5, v116
	v_cvt_pk_bf16_f32 v114, v114, v115
	v_add_f32_e32 v119, 1.0, v119
	v_rcp_f32_e32 v119, v119
	s_nop 0
	v_fma_f32 v119, v119, -2.0, 1.0
	v_add_f32_e32 v119, 1.0, v119
	v_mul_f32_e32 v116, v116, v119
	v_and_b32_e32 v119, 0xffff0000, v121
	v_fmac_f32_e32 v117, v17, v119
	v_mul_f32_e32 v119, 0x3d372713, v117
	v_mul_f32_e32 v119, v117, v119
	v_fma_f32 v119, v117, v119, v117
	v_mul_f32_e32 v119, 0x3f4c422a, v119
	v_add_f32_e32 v119, v119, v119
	v_mul_f32_e32 v119, 0x3fb8aa3b, v119
	v_exp_f32_e32 v119, v119
	v_mul_f32_e32 v117, 0.5, v117
	v_add_f32_e32 v119, 1.0, v119
	v_rcp_f32_e32 v119, v119
	s_nop 0
	v_fma_f32 v119, v119, -2.0, 1.0
	v_add_f32_e32 v119, 1.0, v119
	v_mul_f32_e32 v117, v117, v119
	v_cvt_pk_bf16_f32 v115, v116, v117
	v_add_u32_e32 v116, s19, v118
	v_ashrrev_i32_e32 v117, 31, v116
	v_lshlrev_b64 v[116:117], 11, v[116:117]
	v_lshl_add_u64 v[116:117], v[134:135], 0, v[116:117]
	global_store_dwordx2 v[116:117], v[114:115], off
	v_or_b32_e32 v114, 1, v118
	v_ashrrev_i32_e32 v115, 31, v114
	v_lshlrev_b64 v[116:117], 5, v[114:115]
	v_lshl_add_u64 v[116:117], v[136:137], 0, v[116:117]
	s_waitcnt vmcnt(18)
	v_mov_b64_e32 v[116:117], v[162:163]
	global_load_dwordx2 v[162:163], v[180:181], off offset:96
	v_add_co_u32_e32 v180, vcc, 0x2000, v180
	s_nop 1
	v_addc_co_u32_e32 v181, vcc, 0, v181, vcc
	v_lshlrev_b32_e32 v115, 16, v116
	v_fmac_f32_e32 v110, v14, v115
	v_mul_f32_e32 v115, 0x3d372713, v110
	v_mul_f32_e32 v115, v110, v115
	v_fma_f32 v115, v110, v115, v110
	v_mul_f32_e32 v115, 0x3f4c422a, v115
	v_add_f32_e32 v115, v115, v115
	v_mul_f32_e32 v115, 0x3fb8aa3b, v115
	v_exp_f32_e32 v115, v115
	v_mul_f32_e32 v110, 0.5, v110
	v_add_f32_e32 v115, 1.0, v115
	v_rcp_f32_e32 v115, v115
	s_nop 0
	v_fma_f32 v115, v115, -2.0, 1.0
	v_add_f32_e32 v115, 1.0, v115
	v_mul_f32_e32 v110, v110, v115
	v_and_b32_e32 v115, 0xffff0000, v116
	v_fmac_f32_e32 v111, v15, v115
	v_mul_f32_e32 v115, 0x3d372713, v111
	v_mul_f32_e32 v115, v111, v115
	v_fma_f32 v115, v111, v115, v111
	v_mul_f32_e32 v115, 0x3f4c422a, v115
	v_add_f32_e32 v115, v115, v115
	v_mul_f32_e32 v115, 0x3fb8aa3b, v115
	v_exp_f32_e32 v115, v115
	v_mul_f32_e32 v111, 0.5, v111
	v_add_f32_e32 v115, 1.0, v115
	v_rcp_f32_e32 v115, v115
	s_nop 0
	v_fma_f32 v115, v115, -2.0, 1.0
	v_add_f32_e32 v115, 1.0, v115
	v_mul_f32_e32 v111, v111, v115
	v_lshlrev_b32_e32 v115, 16, v117
	v_fmac_f32_e32 v112, v16, v115
	v_mul_f32_e32 v115, 0x3d372713, v112
	v_mul_f32_e32 v115, v112, v115
	v_fma_f32 v115, v112, v115, v112
	v_mul_f32_e32 v115, 0x3f4c422a, v115
	v_add_f32_e32 v115, v115, v115
	v_mul_f32_e32 v115, 0x3fb8aa3b, v115
	v_exp_f32_e32 v115, v115
	v_mul_f32_e32 v112, 0.5, v112
	v_cvt_pk_bf16_f32 v110, v110, v111
	v_add_f32_e32 v115, 1.0, v115
	v_rcp_f32_e32 v115, v115
	s_nop 0
	v_fma_f32 v115, v115, -2.0, 1.0
	v_add_f32_e32 v115, 1.0, v115
	v_mul_f32_e32 v112, v112, v115
	v_and_b32_e32 v115, 0xffff0000, v117
	v_fmac_f32_e32 v113, v17, v115
	v_mul_f32_e32 v115, 0x3d372713, v113
	v_mul_f32_e32 v115, v113, v115
	v_fma_f32 v115, v113, v115, v113
	v_mul_f32_e32 v115, 0x3f4c422a, v115
	v_add_f32_e32 v115, v115, v115
	v_mul_f32_e32 v115, 0x3fb8aa3b, v115
	v_exp_f32_e32 v115, v115
	v_mul_f32_e32 v113, 0.5, v113
	v_add_f32_e32 v115, 1.0, v115
	v_rcp_f32_e32 v115, v115
	s_nop 0
	v_fma_f32 v115, v115, -2.0, 1.0
	v_add_f32_e32 v115, 1.0, v115
	v_mul_f32_e32 v113, v113, v115
	v_cvt_pk_bf16_f32 v111, v112, v113
	v_add_u32_e32 v112, s19, v114
	v_ashrrev_i32_e32 v113, 31, v112
	v_lshlrev_b64 v[112:113], 11, v[112:113]
	v_lshl_add_u64 v[112:113], v[134:135], 0, v[112:113]
	global_store_dwordx2 v[112:113], v[110:111], off
	v_or_b32_e32 v110, 2, v118
	v_ashrrev_i32_e32 v111, 31, v110
	v_lshlrev_b64 v[112:113], 5, v[110:111]
	v_lshl_add_u64 v[112:113], v[136:137], 0, v[112:113]
	s_waitcnt vmcnt(19)
	v_mov_b64_e32 v[112:113], v[164:165]
	global_load_dwordx2 v[164:165], v[180:181], off
	v_lshlrev_b32_e32 v111, 16, v112
	v_fmac_f32_e32 v106, v14, v111
	v_mul_f32_e32 v111, 0x3d372713, v106
	v_mul_f32_e32 v111, v106, v111
	v_fma_f32 v111, v106, v111, v106
	v_mul_f32_e32 v111, 0x3f4c422a, v111
	v_add_f32_e32 v111, v111, v111
	v_mul_f32_e32 v111, 0x3fb8aa3b, v111
	v_exp_f32_e32 v111, v111
	v_mul_f32_e32 v106, 0.5, v106
	v_add_f32_e32 v111, 1.0, v111
	v_rcp_f32_e32 v111, v111
	s_nop 0
	v_fma_f32 v111, v111, -2.0, 1.0
	v_add_f32_e32 v111, 1.0, v111
	v_mul_f32_e32 v106, v106, v111
	v_and_b32_e32 v111, 0xffff0000, v112
	v_fmac_f32_e32 v107, v15, v111
	v_mul_f32_e32 v111, 0x3d372713, v107
	v_mul_f32_e32 v111, v107, v111
	v_fma_f32 v111, v107, v111, v107
	v_mul_f32_e32 v111, 0x3f4c422a, v111
	v_add_f32_e32 v111, v111, v111
	v_mul_f32_e32 v111, 0x3fb8aa3b, v111
	v_exp_f32_e32 v111, v111
	v_mul_f32_e32 v107, 0.5, v107
	v_add_f32_e32 v111, 1.0, v111
	v_rcp_f32_e32 v111, v111
	s_nop 0
	v_fma_f32 v111, v111, -2.0, 1.0
	v_add_f32_e32 v111, 1.0, v111
	v_mul_f32_e32 v107, v107, v111
	v_lshlrev_b32_e32 v111, 16, v113
	v_fmac_f32_e32 v108, v16, v111
	v_mul_f32_e32 v111, 0x3d372713, v108
	v_mul_f32_e32 v111, v108, v111
	v_fma_f32 v111, v108, v111, v108
	v_mul_f32_e32 v111, 0x3f4c422a, v111
	v_add_f32_e32 v111, v111, v111
	v_mul_f32_e32 v111, 0x3fb8aa3b, v111
	v_exp_f32_e32 v111, v111
	v_mul_f32_e32 v108, 0.5, v108
	v_cvt_pk_bf16_f32 v106, v106, v107
	v_add_f32_e32 v111, 1.0, v111
	v_rcp_f32_e32 v111, v111
	s_nop 0
	v_fma_f32 v111, v111, -2.0, 1.0
	v_add_f32_e32 v111, 1.0, v111
	v_mul_f32_e32 v108, v108, v111
	v_and_b32_e32 v111, 0xffff0000, v113
	v_fmac_f32_e32 v109, v17, v111
	v_mul_f32_e32 v111, 0x3d372713, v109
	v_mul_f32_e32 v111, v109, v111
	v_fma_f32 v111, v109, v111, v109
	v_mul_f32_e32 v111, 0x3f4c422a, v111
	v_add_f32_e32 v111, v111, v111
	v_mul_f32_e32 v111, 0x3fb8aa3b, v111
	v_exp_f32_e32 v111, v111
	v_mul_f32_e32 v109, 0.5, v109
	v_add_f32_e32 v111, 1.0, v111
	v_rcp_f32_e32 v111, v111
	s_nop 0
	v_fma_f32 v111, v111, -2.0, 1.0
	v_add_f32_e32 v111, 1.0, v111
	v_mul_f32_e32 v109, v109, v111
	v_cvt_pk_bf16_f32 v107, v108, v109
	v_add_u32_e32 v108, s19, v110
	v_ashrrev_i32_e32 v109, 31, v108
	v_lshlrev_b64 v[108:109], 11, v[108:109]
	v_lshl_add_u64 v[108:109], v[134:135], 0, v[108:109]
	global_store_dwordx2 v[108:109], v[106:107], off
	v_or_b32_e32 v106, 3, v118
	v_ashrrev_i32_e32 v107, 31, v106
	v_lshlrev_b64 v[108:109], 5, v[106:107]
	v_lshl_add_u64 v[108:109], v[136:137], 0, v[108:109]
	s_waitcnt vmcnt(20)
	v_mov_b64_e32 v[108:109], v[166:167]
	global_load_dwordx2 v[166:167], v[180:181], off offset:32
	v_lshlrev_b32_e32 v107, 16, v108
	v_fmac_f32_e32 v102, v14, v107
	v_mul_f32_e32 v107, 0x3d372713, v102
	v_mul_f32_e32 v107, v102, v107
	v_fma_f32 v107, v102, v107, v102
	v_mul_f32_e32 v107, 0x3f4c422a, v107
	v_add_f32_e32 v107, v107, v107
	v_mul_f32_e32 v107, 0x3fb8aa3b, v107
	v_exp_f32_e32 v107, v107
	v_mul_f32_e32 v102, 0.5, v102
	v_add_f32_e32 v107, 1.0, v107
	v_rcp_f32_e32 v107, v107
	s_nop 0
	v_fma_f32 v107, v107, -2.0, 1.0
	v_add_f32_e32 v107, 1.0, v107
	v_mul_f32_e32 v102, v102, v107
	v_and_b32_e32 v107, 0xffff0000, v108
	v_fmac_f32_e32 v103, v15, v107
	v_mul_f32_e32 v107, 0x3d372713, v103
	v_mul_f32_e32 v107, v103, v107
	v_fma_f32 v107, v103, v107, v103
	v_mul_f32_e32 v107, 0x3f4c422a, v107
	v_add_f32_e32 v107, v107, v107
	v_mul_f32_e32 v107, 0x3fb8aa3b, v107
	v_exp_f32_e32 v107, v107
	v_mul_f32_e32 v103, 0.5, v103
	v_add_f32_e32 v107, 1.0, v107
	v_rcp_f32_e32 v107, v107
	s_nop 0
	v_fma_f32 v107, v107, -2.0, 1.0
	v_add_f32_e32 v107, 1.0, v107
	v_mul_f32_e32 v103, v103, v107
	v_lshlrev_b32_e32 v107, 16, v109
	v_fmac_f32_e32 v104, v16, v107
	v_mul_f32_e32 v107, 0x3d372713, v104
	v_mul_f32_e32 v107, v104, v107
	v_fma_f32 v107, v104, v107, v104
	v_mul_f32_e32 v107, 0x3f4c422a, v107
	v_add_f32_e32 v107, v107, v107
	v_mul_f32_e32 v107, 0x3fb8aa3b, v107
	v_exp_f32_e32 v107, v107
	v_mul_f32_e32 v104, 0.5, v104
	v_cvt_pk_bf16_f32 v102, v102, v103
	v_add_f32_e32 v107, 1.0, v107
	v_rcp_f32_e32 v107, v107
	s_nop 0
	v_fma_f32 v107, v107, -2.0, 1.0
	v_add_f32_e32 v107, 1.0, v107
	v_mul_f32_e32 v104, v104, v107
	v_and_b32_e32 v107, 0xffff0000, v109
	v_fmac_f32_e32 v105, v17, v107
	v_mul_f32_e32 v107, 0x3d372713, v105
	v_mul_f32_e32 v107, v105, v107
	v_fma_f32 v107, v105, v107, v105
	v_mul_f32_e32 v107, 0x3f4c422a, v107
	v_add_f32_e32 v107, v107, v107
	v_mul_f32_e32 v107, 0x3fb8aa3b, v107
	v_exp_f32_e32 v107, v107
	v_mul_f32_e32 v105, 0.5, v105
	v_add_f32_e32 v107, 1.0, v107
	v_rcp_f32_e32 v107, v107
	s_nop 0
	v_fma_f32 v107, v107, -2.0, 1.0
	v_add_f32_e32 v107, 1.0, v107
	v_mul_f32_e32 v105, v105, v107
	v_cvt_pk_bf16_f32 v103, v104, v105
	v_add_u32_e32 v104, s19, v106
	v_ashrrev_i32_e32 v105, 31, v104
	v_lshlrev_b64 v[104:105], 11, v[104:105]
	v_lshl_add_u64 v[104:105], v[134:135], 0, v[104:105]
	global_store_dwordx2 v[104:105], v[102:103], off
	v_add_u32_e32 v102, s20, v231
	v_lshl_or_b32 v102, v102, 4, v229
	v_ashrrev_i32_e32 v103, 31, v102
	v_lshlrev_b64 v[104:105], 5, v[102:103]
	v_lshl_add_u64 v[104:105], v[136:137], 0, v[104:105]
	s_waitcnt vmcnt(21)
	v_mov_b64_e32 v[104:105], v[168:169]
	global_load_dwordx2 v[168:169], v[180:181], off offset:64
	v_lshlrev_b32_e32 v103, 16, v104
	v_fmac_f32_e32 v98, v14, v103
	v_mul_f32_e32 v103, 0x3d372713, v98
	v_mul_f32_e32 v103, v98, v103
	v_fma_f32 v103, v98, v103, v98
	v_mul_f32_e32 v103, 0x3f4c422a, v103
	v_add_f32_e32 v103, v103, v103
	v_mul_f32_e32 v103, 0x3fb8aa3b, v103
	v_exp_f32_e32 v103, v103
	v_mul_f32_e32 v98, 0.5, v98
	v_add_f32_e32 v103, 1.0, v103
	v_rcp_f32_e32 v103, v103
	s_nop 0
	v_fma_f32 v103, v103, -2.0, 1.0
	v_add_f32_e32 v103, 1.0, v103
	v_mul_f32_e32 v98, v98, v103
	v_and_b32_e32 v103, 0xffff0000, v104
	v_fmac_f32_e32 v99, v15, v103
	v_mul_f32_e32 v103, 0x3d372713, v99
	v_mul_f32_e32 v103, v99, v103
	v_fma_f32 v103, v99, v103, v99
	v_mul_f32_e32 v103, 0x3f4c422a, v103
	v_add_f32_e32 v103, v103, v103
	v_mul_f32_e32 v103, 0x3fb8aa3b, v103
	v_exp_f32_e32 v103, v103
	v_mul_f32_e32 v99, 0.5, v99
	v_add_f32_e32 v103, 1.0, v103
	v_rcp_f32_e32 v103, v103
	s_nop 0
	v_fma_f32 v103, v103, -2.0, 1.0
	v_add_f32_e32 v103, 1.0, v103
	v_mul_f32_e32 v99, v99, v103
	v_lshlrev_b32_e32 v103, 16, v105
	v_fmac_f32_e32 v100, v16, v103
	v_mul_f32_e32 v103, 0x3d372713, v100
	v_mul_f32_e32 v103, v100, v103
	v_fma_f32 v103, v100, v103, v100
	v_mul_f32_e32 v103, 0x3f4c422a, v103
	v_add_f32_e32 v103, v103, v103
	v_mul_f32_e32 v103, 0x3fb8aa3b, v103
	v_exp_f32_e32 v103, v103
	v_mul_f32_e32 v100, 0.5, v100
	v_cvt_pk_bf16_f32 v98, v98, v99
	v_add_f32_e32 v103, 1.0, v103
	v_rcp_f32_e32 v103, v103
	s_nop 0
	v_fma_f32 v103, v103, -2.0, 1.0
	v_add_f32_e32 v103, 1.0, v103
	v_mul_f32_e32 v100, v100, v103
	v_and_b32_e32 v103, 0xffff0000, v105
	v_fmac_f32_e32 v101, v17, v103
	v_mul_f32_e32 v103, 0x3d372713, v101
	v_mul_f32_e32 v103, v101, v103
	v_fma_f32 v103, v101, v103, v101
	v_mul_f32_e32 v103, 0x3f4c422a, v103
	v_add_f32_e32 v103, v103, v103
	v_mul_f32_e32 v103, 0x3fb8aa3b, v103
	v_exp_f32_e32 v103, v103
	v_mul_f32_e32 v101, 0.5, v101
	v_add_f32_e32 v103, 1.0, v103
	v_rcp_f32_e32 v103, v103
	s_nop 0
	v_fma_f32 v103, v103, -2.0, 1.0
	v_add_f32_e32 v103, 1.0, v103
	v_mul_f32_e32 v101, v101, v103
	v_cvt_pk_bf16_f32 v99, v100, v101
	v_add_u32_e32 v100, s19, v102
	v_ashrrev_i32_e32 v101, 31, v100
	v_lshlrev_b64 v[100:101], 11, v[100:101]
	v_lshl_add_u64 v[100:101], v[134:135], 0, v[100:101]
	global_store_dwordx2 v[100:101], v[98:99], off
	v_or_b32_e32 v98, 1, v102
	v_ashrrev_i32_e32 v99, 31, v98
	v_lshlrev_b64 v[100:101], 5, v[98:99]
	v_lshl_add_u64 v[100:101], v[136:137], 0, v[100:101]
	s_waitcnt vmcnt(22)
	v_mov_b64_e32 v[100:101], v[170:171]
	global_load_dwordx2 v[170:171], v[180:181], off offset:96
	v_add_co_u32_e32 v180, vcc, 0x2000, v180
	s_nop 1
	v_addc_co_u32_e32 v181, vcc, 0, v181, vcc
	v_lshlrev_b32_e32 v99, 16, v100
	v_fmac_f32_e32 v94, v14, v99
	v_mul_f32_e32 v99, 0x3d372713, v94
	v_mul_f32_e32 v99, v94, v99
	v_fma_f32 v99, v94, v99, v94
	v_mul_f32_e32 v99, 0x3f4c422a, v99
	v_add_f32_e32 v99, v99, v99
	v_mul_f32_e32 v99, 0x3fb8aa3b, v99
	v_exp_f32_e32 v99, v99
	v_mul_f32_e32 v94, 0.5, v94
	v_add_f32_e32 v99, 1.0, v99
	v_rcp_f32_e32 v99, v99
	s_nop 0
	v_fma_f32 v99, v99, -2.0, 1.0
	v_add_f32_e32 v99, 1.0, v99
	v_mul_f32_e32 v94, v94, v99
	v_and_b32_e32 v99, 0xffff0000, v100
	v_fmac_f32_e32 v95, v15, v99
	v_mul_f32_e32 v99, 0x3d372713, v95
	v_mul_f32_e32 v99, v95, v99
	v_fma_f32 v99, v95, v99, v95
	v_mul_f32_e32 v99, 0x3f4c422a, v99
	v_add_f32_e32 v99, v99, v99
	v_mul_f32_e32 v99, 0x3fb8aa3b, v99
	v_exp_f32_e32 v99, v99
	v_mul_f32_e32 v95, 0.5, v95
	v_add_f32_e32 v99, 1.0, v99
	v_rcp_f32_e32 v99, v99
	s_nop 0
	v_fma_f32 v99, v99, -2.0, 1.0
	v_add_f32_e32 v99, 1.0, v99
	v_mul_f32_e32 v95, v95, v99
	v_lshlrev_b32_e32 v99, 16, v101
	v_fmac_f32_e32 v96, v16, v99
	v_mul_f32_e32 v99, 0x3d372713, v96
	v_mul_f32_e32 v99, v96, v99
	v_fma_f32 v99, v96, v99, v96
	v_mul_f32_e32 v99, 0x3f4c422a, v99
	v_add_f32_e32 v99, v99, v99
	v_mul_f32_e32 v99, 0x3fb8aa3b, v99
	v_exp_f32_e32 v99, v99
	v_mul_f32_e32 v96, 0.5, v96
	v_cvt_pk_bf16_f32 v94, v94, v95
	v_add_f32_e32 v99, 1.0, v99
	v_rcp_f32_e32 v99, v99
	s_nop 0
	v_fma_f32 v99, v99, -2.0, 1.0
	v_add_f32_e32 v99, 1.0, v99
	v_mul_f32_e32 v96, v96, v99
	v_and_b32_e32 v99, 0xffff0000, v101
	v_fmac_f32_e32 v97, v17, v99
	v_mul_f32_e32 v99, 0x3d372713, v97
	v_mul_f32_e32 v99, v97, v99
	v_fma_f32 v99, v97, v99, v97
	v_mul_f32_e32 v99, 0x3f4c422a, v99
	v_add_f32_e32 v99, v99, v99
	v_mul_f32_e32 v99, 0x3fb8aa3b, v99
	v_exp_f32_e32 v99, v99
	v_mul_f32_e32 v97, 0.5, v97
	v_add_f32_e32 v99, 1.0, v99
	v_rcp_f32_e32 v99, v99
	s_nop 0
	v_fma_f32 v99, v99, -2.0, 1.0
	v_add_f32_e32 v99, 1.0, v99
	v_mul_f32_e32 v97, v97, v99
	v_cvt_pk_bf16_f32 v95, v96, v97
	v_add_u32_e32 v96, s19, v98
	v_ashrrev_i32_e32 v97, 31, v96
	v_lshlrev_b64 v[96:97], 11, v[96:97]
	v_lshl_add_u64 v[96:97], v[134:135], 0, v[96:97]
	global_store_dwordx2 v[96:97], v[94:95], off
	v_or_b32_e32 v94, 2, v102
	v_ashrrev_i32_e32 v95, 31, v94
	v_lshlrev_b64 v[96:97], 5, v[94:95]
	v_lshl_add_u64 v[96:97], v[136:137], 0, v[96:97]
	s_waitcnt vmcnt(23)
	v_mov_b64_e32 v[96:97], v[172:173]
	global_load_dwordx2 v[172:173], v[180:181], off
	v_lshlrev_b32_e32 v95, 16, v96
	v_fmac_f32_e32 v90, v14, v95
	v_mul_f32_e32 v95, 0x3d372713, v90
	v_mul_f32_e32 v95, v90, v95
	v_fma_f32 v95, v90, v95, v90
	v_mul_f32_e32 v95, 0x3f4c422a, v95
	v_add_f32_e32 v95, v95, v95
	v_mul_f32_e32 v95, 0x3fb8aa3b, v95
	v_exp_f32_e32 v95, v95
	v_mul_f32_e32 v90, 0.5, v90
	v_add_f32_e32 v95, 1.0, v95
	v_rcp_f32_e32 v95, v95
	s_nop 0
	v_fma_f32 v95, v95, -2.0, 1.0
	v_add_f32_e32 v95, 1.0, v95
	v_mul_f32_e32 v90, v90, v95
	v_and_b32_e32 v95, 0xffff0000, v96
	v_fmac_f32_e32 v91, v15, v95
	v_mul_f32_e32 v95, 0x3d372713, v91
	v_mul_f32_e32 v95, v91, v95
	v_fma_f32 v95, v91, v95, v91
	v_mul_f32_e32 v95, 0x3f4c422a, v95
	v_add_f32_e32 v95, v95, v95
	v_mul_f32_e32 v95, 0x3fb8aa3b, v95
	v_exp_f32_e32 v95, v95
	v_mul_f32_e32 v91, 0.5, v91
	v_add_f32_e32 v95, 1.0, v95
	v_rcp_f32_e32 v95, v95
	s_nop 0
	v_fma_f32 v95, v95, -2.0, 1.0
	v_add_f32_e32 v95, 1.0, v95
	v_mul_f32_e32 v91, v91, v95
	v_lshlrev_b32_e32 v95, 16, v97
	v_fmac_f32_e32 v92, v16, v95
	v_mul_f32_e32 v95, 0x3d372713, v92
	v_mul_f32_e32 v95, v92, v95
	v_fma_f32 v95, v92, v95, v92
	v_mul_f32_e32 v95, 0x3f4c422a, v95
	v_add_f32_e32 v95, v95, v95
	v_mul_f32_e32 v95, 0x3fb8aa3b, v95
	v_exp_f32_e32 v95, v95
	v_mul_f32_e32 v92, 0.5, v92
	v_cvt_pk_bf16_f32 v90, v90, v91
	v_add_f32_e32 v95, 1.0, v95
	v_rcp_f32_e32 v95, v95
	s_nop 0
	v_fma_f32 v95, v95, -2.0, 1.0
	v_add_f32_e32 v95, 1.0, v95
	v_mul_f32_e32 v92, v92, v95
	v_and_b32_e32 v95, 0xffff0000, v97
	v_fmac_f32_e32 v93, v17, v95
	v_mul_f32_e32 v95, 0x3d372713, v93
	v_mul_f32_e32 v95, v93, v95
	v_fma_f32 v95, v93, v95, v93
	v_mul_f32_e32 v95, 0x3f4c422a, v95
	v_add_f32_e32 v95, v95, v95
	v_mul_f32_e32 v95, 0x3fb8aa3b, v95
	v_exp_f32_e32 v95, v95
	v_mul_f32_e32 v93, 0.5, v93
	v_add_f32_e32 v95, 1.0, v95
	v_rcp_f32_e32 v95, v95
	s_nop 0
	v_fma_f32 v95, v95, -2.0, 1.0
	v_add_f32_e32 v95, 1.0, v95
	v_mul_f32_e32 v93, v93, v95
	v_cvt_pk_bf16_f32 v91, v92, v93
	v_add_u32_e32 v92, s19, v94
	v_ashrrev_i32_e32 v93, 31, v92
	v_lshlrev_b64 v[92:93], 11, v[92:93]
	v_lshl_add_u64 v[92:93], v[134:135], 0, v[92:93]
	global_store_dwordx2 v[92:93], v[90:91], off
	v_or_b32_e32 v90, 3, v102
	v_ashrrev_i32_e32 v91, 31, v90
	v_lshlrev_b64 v[92:93], 5, v[90:91]
	v_lshl_add_u64 v[92:93], v[136:137], 0, v[92:93]
	s_waitcnt vmcnt(24)
	v_mov_b64_e32 v[92:93], v[174:175]
	global_load_dwordx2 v[174:175], v[180:181], off offset:32
	v_lshlrev_b32_e32 v91, 16, v92
	v_fmac_f32_e32 v86, v14, v91
	v_mul_f32_e32 v91, 0x3d372713, v86
	v_mul_f32_e32 v91, v86, v91
	v_fma_f32 v91, v86, v91, v86
	v_mul_f32_e32 v91, 0x3f4c422a, v91
	v_add_f32_e32 v91, v91, v91
	v_mul_f32_e32 v91, 0x3fb8aa3b, v91
	v_exp_f32_e32 v91, v91
	v_mul_f32_e32 v86, 0.5, v86
	v_add_f32_e32 v91, 1.0, v91
	v_rcp_f32_e32 v91, v91
	s_nop 0
	v_fma_f32 v91, v91, -2.0, 1.0
	v_add_f32_e32 v91, 1.0, v91
	v_mul_f32_e32 v86, v86, v91
	v_and_b32_e32 v91, 0xffff0000, v92
	v_fmac_f32_e32 v87, v15, v91
	v_mul_f32_e32 v91, 0x3d372713, v87
	v_mul_f32_e32 v91, v87, v91
	v_fma_f32 v91, v87, v91, v87
	v_mul_f32_e32 v91, 0x3f4c422a, v91
	v_add_f32_e32 v91, v91, v91
	v_mul_f32_e32 v91, 0x3fb8aa3b, v91
	v_exp_f32_e32 v91, v91
	v_mul_f32_e32 v87, 0.5, v87
	v_add_f32_e32 v91, 1.0, v91
	v_rcp_f32_e32 v91, v91
	s_nop 0
	v_fma_f32 v91, v91, -2.0, 1.0
	v_add_f32_e32 v91, 1.0, v91
	v_mul_f32_e32 v87, v87, v91
	v_lshlrev_b32_e32 v91, 16, v93
	v_fmac_f32_e32 v88, v16, v91
	v_mul_f32_e32 v91, 0x3d372713, v88
	v_mul_f32_e32 v91, v88, v91
	v_fma_f32 v91, v88, v91, v88
	v_mul_f32_e32 v91, 0x3f4c422a, v91
	v_add_f32_e32 v91, v91, v91
	v_mul_f32_e32 v91, 0x3fb8aa3b, v91
	v_exp_f32_e32 v91, v91
	v_mul_f32_e32 v88, 0.5, v88
	v_cvt_pk_bf16_f32 v86, v86, v87
	v_add_f32_e32 v91, 1.0, v91
	v_rcp_f32_e32 v91, v91
	s_nop 0
	v_fma_f32 v91, v91, -2.0, 1.0
	v_add_f32_e32 v91, 1.0, v91
	v_mul_f32_e32 v88, v88, v91
	v_and_b32_e32 v91, 0xffff0000, v93
	v_fmac_f32_e32 v89, v17, v91
	v_mul_f32_e32 v91, 0x3d372713, v89
	v_mul_f32_e32 v91, v89, v91
	v_fma_f32 v91, v89, v91, v89
	v_mul_f32_e32 v91, 0x3f4c422a, v91
	v_add_f32_e32 v91, v91, v91
	v_mul_f32_e32 v91, 0x3fb8aa3b, v91
	v_exp_f32_e32 v91, v91
	v_mul_f32_e32 v89, 0.5, v89
	v_add_f32_e32 v91, 1.0, v91
	v_rcp_f32_e32 v91, v91
	s_nop 0
	v_fma_f32 v91, v91, -2.0, 1.0
	v_add_f32_e32 v91, 1.0, v91
	v_mul_f32_e32 v89, v89, v91
	v_cvt_pk_bf16_f32 v87, v88, v89
	v_add_u32_e32 v88, s19, v90
	v_ashrrev_i32_e32 v89, 31, v88
	v_lshlrev_b64 v[88:89], 11, v[88:89]
	v_lshl_add_u64 v[88:89], v[134:135], 0, v[88:89]
	global_store_dwordx2 v[88:89], v[86:87], off
	v_add_u32_e32 v86, s20, v232
	v_lshl_or_b32 v86, v86, 4, v229
	v_ashrrev_i32_e32 v87, 31, v86
	v_lshlrev_b64 v[88:89], 5, v[86:87]
	v_lshl_add_u64 v[88:89], v[136:137], 0, v[88:89]
	s_waitcnt vmcnt(25)
	v_mov_b64_e32 v[88:89], v[176:177]
	global_load_dwordx2 v[176:177], v[180:181], off offset:64
	v_lshlrev_b32_e32 v87, 16, v88
	v_fmac_f32_e32 v82, v14, v87
	v_mul_f32_e32 v87, 0x3d372713, v82
	v_mul_f32_e32 v87, v82, v87
	v_fma_f32 v87, v82, v87, v82
	v_mul_f32_e32 v87, 0x3f4c422a, v87
	v_add_f32_e32 v87, v87, v87
	v_mul_f32_e32 v87, 0x3fb8aa3b, v87
	v_exp_f32_e32 v87, v87
	v_mul_f32_e32 v82, 0.5, v82
	v_add_f32_e32 v87, 1.0, v87
	v_rcp_f32_e32 v87, v87
	s_nop 0
	v_fma_f32 v87, v87, -2.0, 1.0
	v_add_f32_e32 v87, 1.0, v87
	v_mul_f32_e32 v82, v82, v87
	v_and_b32_e32 v87, 0xffff0000, v88
	v_fmac_f32_e32 v83, v15, v87
	v_mul_f32_e32 v87, 0x3d372713, v83
	v_mul_f32_e32 v87, v83, v87
	v_fma_f32 v87, v83, v87, v83
	v_mul_f32_e32 v87, 0x3f4c422a, v87
	v_add_f32_e32 v87, v87, v87
	v_mul_f32_e32 v87, 0x3fb8aa3b, v87
	v_exp_f32_e32 v87, v87
	v_mul_f32_e32 v83, 0.5, v83
	v_add_f32_e32 v87, 1.0, v87
	v_rcp_f32_e32 v87, v87
	s_nop 0
	v_fma_f32 v87, v87, -2.0, 1.0
	v_add_f32_e32 v87, 1.0, v87
	v_mul_f32_e32 v83, v83, v87
	v_lshlrev_b32_e32 v87, 16, v89
	v_fmac_f32_e32 v84, v16, v87
	v_mul_f32_e32 v87, 0x3d372713, v84
	v_mul_f32_e32 v87, v84, v87
	v_fma_f32 v87, v84, v87, v84
	v_mul_f32_e32 v87, 0x3f4c422a, v87
	v_add_f32_e32 v87, v87, v87
	v_mul_f32_e32 v87, 0x3fb8aa3b, v87
	v_exp_f32_e32 v87, v87
	v_mul_f32_e32 v84, 0.5, v84
	v_cvt_pk_bf16_f32 v82, v82, v83
	v_add_f32_e32 v87, 1.0, v87
	v_rcp_f32_e32 v87, v87
	s_nop 0
	v_fma_f32 v87, v87, -2.0, 1.0
	v_add_f32_e32 v87, 1.0, v87
	v_mul_f32_e32 v84, v84, v87
	v_and_b32_e32 v87, 0xffff0000, v89
	v_fmac_f32_e32 v85, v17, v87
	v_mul_f32_e32 v87, 0x3d372713, v85
	v_mul_f32_e32 v87, v85, v87
	v_fma_f32 v87, v85, v87, v85
	v_mul_f32_e32 v87, 0x3f4c422a, v87
	v_add_f32_e32 v87, v87, v87
	v_mul_f32_e32 v87, 0x3fb8aa3b, v87
	v_exp_f32_e32 v87, v87
	v_mul_f32_e32 v85, 0.5, v85
	v_add_f32_e32 v87, 1.0, v87
	v_rcp_f32_e32 v87, v87
	s_nop 0
	v_fma_f32 v87, v87, -2.0, 1.0
	v_add_f32_e32 v87, 1.0, v87
	v_mul_f32_e32 v85, v85, v87
	v_cvt_pk_bf16_f32 v83, v84, v85
	v_add_u32_e32 v84, s19, v86
	v_ashrrev_i32_e32 v85, 31, v84
	v_lshlrev_b64 v[84:85], 11, v[84:85]
	v_lshl_add_u64 v[84:85], v[134:135], 0, v[84:85]
	global_store_dwordx2 v[84:85], v[82:83], off
	v_or_b32_e32 v82, 1, v86
	v_ashrrev_i32_e32 v83, 31, v82
	v_lshlrev_b64 v[84:85], 5, v[82:83]
	v_lshl_add_u64 v[84:85], v[136:137], 0, v[84:85]
	s_waitcnt vmcnt(26)
	v_mov_b64_e32 v[84:85], v[178:179]
	global_load_dwordx2 v[178:179], v[180:181], off offset:96
	v_add_co_u32_e32 v180, vcc, 0x2000, v180
	s_nop 1
	v_addc_co_u32_e32 v181, vcc, 0, v181, vcc
	v_lshlrev_b32_e32 v83, 16, v84
	v_fmac_f32_e32 v78, v14, v83
	v_mul_f32_e32 v83, 0x3d372713, v78
	v_mul_f32_e32 v83, v78, v83
	v_fma_f32 v83, v78, v83, v78
	v_mul_f32_e32 v83, 0x3f4c422a, v83
	v_add_f32_e32 v83, v83, v83
	v_mul_f32_e32 v83, 0x3fb8aa3b, v83
	v_exp_f32_e32 v83, v83
	v_mul_f32_e32 v78, 0.5, v78
	v_add_f32_e32 v83, 1.0, v83
	v_rcp_f32_e32 v83, v83
	s_nop 0
	v_fma_f32 v83, v83, -2.0, 1.0
	v_add_f32_e32 v83, 1.0, v83
	v_mul_f32_e32 v78, v78, v83
	v_and_b32_e32 v83, 0xffff0000, v84
	v_fmac_f32_e32 v79, v15, v83
	v_mul_f32_e32 v83, 0x3d372713, v79
	v_mul_f32_e32 v83, v79, v83
	v_fma_f32 v83, v79, v83, v79
	v_mul_f32_e32 v83, 0x3f4c422a, v83
	v_add_f32_e32 v83, v83, v83
	v_mul_f32_e32 v83, 0x3fb8aa3b, v83
	v_exp_f32_e32 v83, v83
	v_mul_f32_e32 v79, 0.5, v79
	v_add_f32_e32 v83, 1.0, v83
	v_rcp_f32_e32 v83, v83
	s_nop 0
	v_fma_f32 v83, v83, -2.0, 1.0
	v_add_f32_e32 v83, 1.0, v83
	v_mul_f32_e32 v79, v79, v83
	v_lshlrev_b32_e32 v83, 16, v85
	v_fmac_f32_e32 v80, v16, v83
	v_mul_f32_e32 v83, 0x3d372713, v80
	v_mul_f32_e32 v83, v80, v83
	v_fma_f32 v83, v80, v83, v80
	v_mul_f32_e32 v83, 0x3f4c422a, v83
	v_add_f32_e32 v83, v83, v83
	v_mul_f32_e32 v83, 0x3fb8aa3b, v83
	v_exp_f32_e32 v83, v83
	v_mul_f32_e32 v80, 0.5, v80
	v_cvt_pk_bf16_f32 v78, v78, v79
	v_add_f32_e32 v83, 1.0, v83
	v_rcp_f32_e32 v83, v83
	s_nop 0
	v_fma_f32 v83, v83, -2.0, 1.0
	v_add_f32_e32 v83, 1.0, v83
	v_mul_f32_e32 v80, v80, v83
	v_and_b32_e32 v83, 0xffff0000, v85
	v_fmac_f32_e32 v81, v17, v83
	v_mul_f32_e32 v83, 0x3d372713, v81
	v_mul_f32_e32 v83, v81, v83
	v_fma_f32 v83, v81, v83, v81
	v_mul_f32_e32 v83, 0x3f4c422a, v83
	v_add_f32_e32 v83, v83, v83
	v_mul_f32_e32 v83, 0x3fb8aa3b, v83
	v_exp_f32_e32 v83, v83
	v_mul_f32_e32 v81, 0.5, v81
	v_add_f32_e32 v83, 1.0, v83
	v_rcp_f32_e32 v83, v83
	s_nop 0
	v_fma_f32 v83, v83, -2.0, 1.0
	v_add_f32_e32 v83, 1.0, v83
	v_mul_f32_e32 v81, v81, v83
	v_cvt_pk_bf16_f32 v79, v80, v81
	v_add_u32_e32 v80, s19, v82
	v_ashrrev_i32_e32 v81, 31, v80
	v_lshlrev_b64 v[80:81], 11, v[80:81]
	v_lshl_add_u64 v[80:81], v[134:135], 0, v[80:81]
	global_store_dwordx2 v[80:81], v[78:79], off
	v_or_b32_e32 v78, 2, v86
	v_ashrrev_i32_e32 v79, 31, v78
	v_lshlrev_b64 v[80:81], 5, v[78:79]
	v_lshl_add_u64 v[80:81], v[136:137], 0, v[80:81]
	s_waitcnt vmcnt(27)
	v_mov_b64_e32 v[80:81], v[152:153]
	global_load_dwordx2 v[152:153], v[180:181], off
	v_lshlrev_b32_e32 v79, 16, v80
	v_fmac_f32_e32 v74, v14, v79
	v_mul_f32_e32 v79, 0x3d372713, v74
	v_mul_f32_e32 v79, v74, v79
	v_fma_f32 v79, v74, v79, v74
	v_mul_f32_e32 v79, 0x3f4c422a, v79
	v_add_f32_e32 v79, v79, v79
	v_mul_f32_e32 v79, 0x3fb8aa3b, v79
	v_exp_f32_e32 v79, v79
	v_mul_f32_e32 v74, 0.5, v74
	v_add_f32_e32 v79, 1.0, v79
	v_rcp_f32_e32 v79, v79
	s_nop 0
	v_fma_f32 v79, v79, -2.0, 1.0
	v_add_f32_e32 v79, 1.0, v79
	v_mul_f32_e32 v74, v74, v79
	v_and_b32_e32 v79, 0xffff0000, v80
	v_fmac_f32_e32 v75, v15, v79
	v_mul_f32_e32 v79, 0x3d372713, v75
	v_mul_f32_e32 v79, v75, v79
	v_fma_f32 v79, v75, v79, v75
	v_mul_f32_e32 v79, 0x3f4c422a, v79
	v_add_f32_e32 v79, v79, v79
	v_mul_f32_e32 v79, 0x3fb8aa3b, v79
	v_exp_f32_e32 v79, v79
	v_mul_f32_e32 v75, 0.5, v75
	v_add_f32_e32 v79, 1.0, v79
	v_rcp_f32_e32 v79, v79
	s_nop 0
	v_fma_f32 v79, v79, -2.0, 1.0
	v_add_f32_e32 v79, 1.0, v79
	v_mul_f32_e32 v75, v75, v79
	v_lshlrev_b32_e32 v79, 16, v81
	v_fmac_f32_e32 v76, v16, v79
	v_mul_f32_e32 v79, 0x3d372713, v76
	v_mul_f32_e32 v79, v76, v79
	v_fma_f32 v79, v76, v79, v76
	v_mul_f32_e32 v79, 0x3f4c422a, v79
	v_add_f32_e32 v79, v79, v79
	v_mul_f32_e32 v79, 0x3fb8aa3b, v79
	v_exp_f32_e32 v79, v79
	v_mul_f32_e32 v76, 0.5, v76
	v_cvt_pk_bf16_f32 v74, v74, v75
	v_add_f32_e32 v79, 1.0, v79
	v_rcp_f32_e32 v79, v79
	s_nop 0
	v_fma_f32 v79, v79, -2.0, 1.0
	v_add_f32_e32 v79, 1.0, v79
	v_mul_f32_e32 v76, v76, v79
	v_and_b32_e32 v79, 0xffff0000, v81
	v_fmac_f32_e32 v77, v17, v79
	v_mul_f32_e32 v79, 0x3d372713, v77
	v_mul_f32_e32 v79, v77, v79
	v_fma_f32 v79, v77, v79, v77
	v_mul_f32_e32 v79, 0x3f4c422a, v79
	v_add_f32_e32 v79, v79, v79
	v_mul_f32_e32 v79, 0x3fb8aa3b, v79
	v_exp_f32_e32 v79, v79
	v_mul_f32_e32 v77, 0.5, v77
	v_add_f32_e32 v79, 1.0, v79
	v_rcp_f32_e32 v79, v79
	s_nop 0
	v_fma_f32 v79, v79, -2.0, 1.0
	v_add_f32_e32 v79, 1.0, v79
	v_mul_f32_e32 v77, v77, v79
	v_cvt_pk_bf16_f32 v75, v76, v77
	v_add_u32_e32 v76, s19, v78
	v_ashrrev_i32_e32 v77, 31, v76
	v_lshlrev_b64 v[76:77], 11, v[76:77]
	v_lshl_add_u64 v[76:77], v[134:135], 0, v[76:77]
	global_store_dwordx2 v[76:77], v[74:75], off
	v_or_b32_e32 v74, 3, v86
	v_ashrrev_i32_e32 v75, 31, v74
	v_lshlrev_b64 v[76:77], 5, v[74:75]
	v_lshl_add_u64 v[76:77], v[136:137], 0, v[76:77]
	s_waitcnt vmcnt(27)
	v_mov_b64_e32 v[76:77], v[154:155]
	global_load_dwordx2 v[154:155], v[180:181], off offset:32
	v_lshlrev_b32_e32 v75, 16, v76
	v_fmac_f32_e32 v70, v14, v75
	v_mul_f32_e32 v75, 0x3d372713, v70
	v_mul_f32_e32 v75, v70, v75
	v_fma_f32 v75, v70, v75, v70
	v_mul_f32_e32 v75, 0x3f4c422a, v75
	v_add_f32_e32 v75, v75, v75
	v_mul_f32_e32 v75, 0x3fb8aa3b, v75
	v_exp_f32_e32 v75, v75
	v_mul_f32_e32 v70, 0.5, v70
	v_add_f32_e32 v75, 1.0, v75
	v_rcp_f32_e32 v75, v75
	s_nop 0
	v_fma_f32 v75, v75, -2.0, 1.0
	v_add_f32_e32 v75, 1.0, v75
	v_mul_f32_e32 v70, v70, v75
	v_and_b32_e32 v75, 0xffff0000, v76
	v_fmac_f32_e32 v71, v15, v75
	v_mul_f32_e32 v75, 0x3d372713, v71
	v_mul_f32_e32 v75, v71, v75
	v_fma_f32 v75, v71, v75, v71
	v_mul_f32_e32 v75, 0x3f4c422a, v75
	v_add_f32_e32 v75, v75, v75
	v_mul_f32_e32 v75, 0x3fb8aa3b, v75
	v_exp_f32_e32 v75, v75
	v_mul_f32_e32 v71, 0.5, v71
	v_add_f32_e32 v75, 1.0, v75
	v_rcp_f32_e32 v75, v75
	s_nop 0
	v_fma_f32 v75, v75, -2.0, 1.0
	v_add_f32_e32 v75, 1.0, v75
	v_mul_f32_e32 v71, v71, v75
	v_lshlrev_b32_e32 v75, 16, v77
	v_fmac_f32_e32 v72, v16, v75
	v_mul_f32_e32 v75, 0x3d372713, v72
	v_mul_f32_e32 v75, v72, v75
	v_fma_f32 v75, v72, v75, v72
	v_mul_f32_e32 v75, 0x3f4c422a, v75
	v_add_f32_e32 v75, v75, v75
	v_mul_f32_e32 v75, 0x3fb8aa3b, v75
	v_exp_f32_e32 v75, v75
	v_mul_f32_e32 v72, 0.5, v72
	v_cvt_pk_bf16_f32 v70, v70, v71
	v_add_f32_e32 v75, 1.0, v75
	v_rcp_f32_e32 v75, v75
	s_nop 0
	v_fma_f32 v75, v75, -2.0, 1.0
	v_add_f32_e32 v75, 1.0, v75
	v_mul_f32_e32 v72, v72, v75
	v_and_b32_e32 v75, 0xffff0000, v77
	v_fmac_f32_e32 v73, v17, v75
	v_mul_f32_e32 v75, 0x3d372713, v73
	v_mul_f32_e32 v75, v73, v75
	v_fma_f32 v75, v73, v75, v73
	v_mul_f32_e32 v75, 0x3f4c422a, v75
	v_add_f32_e32 v75, v75, v75
	v_mul_f32_e32 v75, 0x3fb8aa3b, v75
	v_exp_f32_e32 v75, v75
	v_mul_f32_e32 v73, 0.5, v73
	v_add_f32_e32 v75, 1.0, v75
	v_rcp_f32_e32 v75, v75
	s_nop 0
	v_fma_f32 v75, v75, -2.0, 1.0
	v_add_f32_e32 v75, 1.0, v75
	v_mul_f32_e32 v73, v73, v75
	v_cvt_pk_bf16_f32 v71, v72, v73
	v_add_u32_e32 v72, s19, v74
	v_ashrrev_i32_e32 v73, 31, v72
	v_lshlrev_b64 v[72:73], 11, v[72:73]
	v_lshl_add_u64 v[72:73], v[134:135], 0, v[72:73]
	global_store_dwordx2 v[72:73], v[70:71], off
	v_add_u32_e32 v70, s20, v233
	v_lshl_or_b32 v70, v70, 4, v229
	v_ashrrev_i32_e32 v71, 31, v70
	v_lshlrev_b64 v[72:73], 5, v[70:71]
	v_lshl_add_u64 v[72:73], v[136:137], 0, v[72:73]
	s_waitcnt vmcnt(27)
	v_mov_b64_e32 v[72:73], v[156:157]
	global_load_dwordx2 v[156:157], v[180:181], off offset:64
	v_lshlrev_b32_e32 v71, 16, v72
	v_fmac_f32_e32 v66, v14, v71
	v_mul_f32_e32 v71, 0x3d372713, v66
	v_mul_f32_e32 v71, v66, v71
	v_fma_f32 v71, v66, v71, v66
	v_mul_f32_e32 v71, 0x3f4c422a, v71
	v_add_f32_e32 v71, v71, v71
	v_mul_f32_e32 v71, 0x3fb8aa3b, v71
	v_exp_f32_e32 v71, v71
	v_mul_f32_e32 v66, 0.5, v66
	v_add_f32_e32 v71, 1.0, v71
	v_rcp_f32_e32 v71, v71
	s_nop 0
	v_fma_f32 v71, v71, -2.0, 1.0
	v_add_f32_e32 v71, 1.0, v71
	v_mul_f32_e32 v66, v66, v71
	v_and_b32_e32 v71, 0xffff0000, v72
	v_fmac_f32_e32 v67, v15, v71
	v_mul_f32_e32 v71, 0x3d372713, v67
	v_mul_f32_e32 v71, v67, v71
	v_fma_f32 v71, v67, v71, v67
	v_mul_f32_e32 v71, 0x3f4c422a, v71
	v_add_f32_e32 v71, v71, v71
	v_mul_f32_e32 v71, 0x3fb8aa3b, v71
	v_exp_f32_e32 v71, v71
	v_mul_f32_e32 v67, 0.5, v67
	v_add_f32_e32 v71, 1.0, v71
	v_rcp_f32_e32 v71, v71
	s_nop 0
	v_fma_f32 v71, v71, -2.0, 1.0
	v_add_f32_e32 v71, 1.0, v71
	v_mul_f32_e32 v67, v67, v71
	v_lshlrev_b32_e32 v71, 16, v73
	v_fmac_f32_e32 v68, v16, v71
	v_mul_f32_e32 v71, 0x3d372713, v68
	v_mul_f32_e32 v71, v68, v71
	v_fma_f32 v71, v68, v71, v68
	v_mul_f32_e32 v71, 0x3f4c422a, v71
	v_add_f32_e32 v71, v71, v71
	v_mul_f32_e32 v71, 0x3fb8aa3b, v71
	v_exp_f32_e32 v71, v71
	v_mul_f32_e32 v68, 0.5, v68
	v_cvt_pk_bf16_f32 v66, v66, v67
	v_add_f32_e32 v71, 1.0, v71
	v_rcp_f32_e32 v71, v71
	s_nop 0
	v_fma_f32 v71, v71, -2.0, 1.0
	v_add_f32_e32 v71, 1.0, v71
	v_mul_f32_e32 v68, v68, v71
	v_and_b32_e32 v71, 0xffff0000, v73
	v_fmac_f32_e32 v69, v17, v71
	v_mul_f32_e32 v71, 0x3d372713, v69
	v_mul_f32_e32 v71, v69, v71
	v_fma_f32 v71, v69, v71, v69
	v_mul_f32_e32 v71, 0x3f4c422a, v71
	v_add_f32_e32 v71, v71, v71
	v_mul_f32_e32 v71, 0x3fb8aa3b, v71
	v_exp_f32_e32 v71, v71
	v_mul_f32_e32 v69, 0.5, v69
	v_add_f32_e32 v71, 1.0, v71
	v_rcp_f32_e32 v71, v71
	s_nop 0
	v_fma_f32 v71, v71, -2.0, 1.0
	v_add_f32_e32 v71, 1.0, v71
	v_mul_f32_e32 v69, v69, v71
	v_cvt_pk_bf16_f32 v67, v68, v69
	v_add_u32_e32 v68, s19, v70
	v_ashrrev_i32_e32 v69, 31, v68
	v_lshlrev_b64 v[68:69], 11, v[68:69]
	v_lshl_add_u64 v[68:69], v[134:135], 0, v[68:69]
	global_store_dwordx2 v[68:69], v[66:67], off
	v_or_b32_e32 v66, 1, v70
	v_ashrrev_i32_e32 v67, 31, v66
	v_lshlrev_b64 v[68:69], 5, v[66:67]
	v_lshl_add_u64 v[68:69], v[136:137], 0, v[68:69]
	s_waitcnt vmcnt(27)
	v_mov_b64_e32 v[68:69], v[158:159]
	global_load_dwordx2 v[158:159], v[180:181], off offset:96
	v_lshlrev_b32_e32 v67, 16, v68
	v_fmac_f32_e32 v62, v14, v67
	v_mul_f32_e32 v67, 0x3d372713, v62
	v_mul_f32_e32 v67, v62, v67
	v_fma_f32 v67, v62, v67, v62
	v_mul_f32_e32 v67, 0x3f4c422a, v67
	v_add_f32_e32 v67, v67, v67
	v_mul_f32_e32 v67, 0x3fb8aa3b, v67
	v_exp_f32_e32 v67, v67
	v_mul_f32_e32 v62, 0.5, v62
	v_add_f32_e32 v67, 1.0, v67
	v_rcp_f32_e32 v67, v67
	s_nop 0
	v_fma_f32 v67, v67, -2.0, 1.0
	v_add_f32_e32 v67, 1.0, v67
	v_mul_f32_e32 v62, v62, v67
	v_and_b32_e32 v67, 0xffff0000, v68
	v_fmac_f32_e32 v63, v15, v67
	v_mul_f32_e32 v67, 0x3d372713, v63
	v_mul_f32_e32 v67, v63, v67
	v_fma_f32 v67, v63, v67, v63
	v_mul_f32_e32 v67, 0x3f4c422a, v67
	v_add_f32_e32 v67, v67, v67
	v_mul_f32_e32 v67, 0x3fb8aa3b, v67
	v_exp_f32_e32 v67, v67
	v_mul_f32_e32 v63, 0.5, v63
	v_add_f32_e32 v67, 1.0, v67
	v_rcp_f32_e32 v67, v67
	s_nop 0
	v_fma_f32 v67, v67, -2.0, 1.0
	v_add_f32_e32 v67, 1.0, v67
	v_mul_f32_e32 v63, v63, v67
	v_lshlrev_b32_e32 v67, 16, v69
	v_fmac_f32_e32 v64, v16, v67
	v_mul_f32_e32 v67, 0x3d372713, v64
	v_mul_f32_e32 v67, v64, v67
	v_fma_f32 v67, v64, v67, v64
	v_mul_f32_e32 v67, 0x3f4c422a, v67
	v_add_f32_e32 v67, v67, v67
	v_mul_f32_e32 v67, 0x3fb8aa3b, v67
	v_exp_f32_e32 v67, v67
	v_mul_f32_e32 v64, 0.5, v64
	v_cvt_pk_bf16_f32 v62, v62, v63
	v_add_f32_e32 v67, 1.0, v67
	v_rcp_f32_e32 v67, v67
	s_nop 0
	v_fma_f32 v67, v67, -2.0, 1.0
	v_add_f32_e32 v67, 1.0, v67
	v_mul_f32_e32 v64, v64, v67
	v_and_b32_e32 v67, 0xffff0000, v69
	v_fmac_f32_e32 v65, v17, v67
	v_mul_f32_e32 v67, 0x3d372713, v65
	v_mul_f32_e32 v67, v65, v67
	v_fma_f32 v67, v65, v67, v65
	v_mul_f32_e32 v67, 0x3f4c422a, v67
	v_add_f32_e32 v67, v67, v67
	v_mul_f32_e32 v67, 0x3fb8aa3b, v67
	v_exp_f32_e32 v67, v67
	v_mul_f32_e32 v65, 0.5, v65
	v_add_f32_e32 v67, 1.0, v67
	v_rcp_f32_e32 v67, v67
	s_nop 0
	v_fma_f32 v67, v67, -2.0, 1.0
	v_add_f32_e32 v67, 1.0, v67
	v_mul_f32_e32 v65, v65, v67
	v_cvt_pk_bf16_f32 v63, v64, v65
	v_add_u32_e32 v64, s19, v66
	v_ashrrev_i32_e32 v65, 31, v64
	v_lshlrev_b64 v[64:65], 11, v[64:65]
	v_lshl_add_u64 v[64:65], v[134:135], 0, v[64:65]
	global_store_dwordx2 v[64:65], v[62:63], off
	v_or_b32_e32 v62, 2, v70
	v_ashrrev_i32_e32 v63, 31, v62
	v_lshlrev_b64 v[64:65], 5, v[62:63]
	v_lshl_add_u64 v[64:65], v[136:137], 0, v[64:65]
	s_waitcnt vmcnt(27)
	v_mov_b64_e32 v[64:65], v[160:161]
	v_lshlrev_b32_e32 v63, 16, v64
	v_fmac_f32_e32 v58, v14, v63
	v_mul_f32_e32 v63, 0x3d372713, v58
	v_mul_f32_e32 v63, v58, v63
	v_fma_f32 v63, v58, v63, v58
	v_mul_f32_e32 v63, 0x3f4c422a, v63
	v_add_f32_e32 v63, v63, v63
	v_mul_f32_e32 v63, 0x3fb8aa3b, v63
	v_exp_f32_e32 v63, v63
	v_mul_f32_e32 v58, 0.5, v58
	v_add_f32_e32 v63, 1.0, v63
	v_rcp_f32_e32 v63, v63
	s_nop 0
	v_fma_f32 v63, v63, -2.0, 1.0
	v_add_f32_e32 v63, 1.0, v63
	v_mul_f32_e32 v58, v58, v63
	v_and_b32_e32 v63, 0xffff0000, v64
	v_fmac_f32_e32 v59, v15, v63
	v_mul_f32_e32 v63, 0x3d372713, v59
	v_mul_f32_e32 v63, v59, v63
	v_fma_f32 v63, v59, v63, v59
	v_mul_f32_e32 v63, 0x3f4c422a, v63
	v_add_f32_e32 v63, v63, v63
	v_mul_f32_e32 v63, 0x3fb8aa3b, v63
	v_exp_f32_e32 v63, v63
	v_mul_f32_e32 v59, 0.5, v59
	v_add_f32_e32 v63, 1.0, v63
	v_rcp_f32_e32 v63, v63
	s_nop 0
	v_fma_f32 v63, v63, -2.0, 1.0
	v_add_f32_e32 v63, 1.0, v63
	v_mul_f32_e32 v59, v59, v63
	v_lshlrev_b32_e32 v63, 16, v65
	v_fmac_f32_e32 v60, v16, v63
	v_mul_f32_e32 v63, 0x3d372713, v60
	v_mul_f32_e32 v63, v60, v63
	v_fma_f32 v63, v60, v63, v60
	v_mul_f32_e32 v63, 0x3f4c422a, v63
	v_add_f32_e32 v63, v63, v63
	v_mul_f32_e32 v63, 0x3fb8aa3b, v63
	v_exp_f32_e32 v63, v63
	v_mul_f32_e32 v60, 0.5, v60
	v_cvt_pk_bf16_f32 v58, v58, v59
	v_add_f32_e32 v63, 1.0, v63
	v_rcp_f32_e32 v63, v63
	s_nop 0
	v_fma_f32 v63, v63, -2.0, 1.0
	v_add_f32_e32 v63, 1.0, v63
	v_mul_f32_e32 v60, v60, v63
	v_and_b32_e32 v63, 0xffff0000, v65
	v_fmac_f32_e32 v61, v17, v63
	v_mul_f32_e32 v63, 0x3d372713, v61
	v_mul_f32_e32 v63, v61, v63
	v_fma_f32 v63, v61, v63, v61
	v_mul_f32_e32 v63, 0x3f4c422a, v63
	v_add_f32_e32 v63, v63, v63
	v_mul_f32_e32 v63, 0x3fb8aa3b, v63
	v_exp_f32_e32 v63, v63
	v_mul_f32_e32 v61, 0.5, v61
	v_add_f32_e32 v63, 1.0, v63
	v_rcp_f32_e32 v63, v63
	s_nop 0
	v_fma_f32 v63, v63, -2.0, 1.0
	v_add_f32_e32 v63, 1.0, v63
	v_mul_f32_e32 v61, v61, v63
	v_cvt_pk_bf16_f32 v59, v60, v61
	v_add_u32_e32 v60, s19, v62
	v_ashrrev_i32_e32 v61, 31, v60
	v_lshlrev_b64 v[60:61], 11, v[60:61]
	v_lshl_add_u64 v[60:61], v[134:135], 0, v[60:61]
	global_store_dwordx2 v[60:61], v[58:59], off
	v_or_b32_e32 v58, 3, v70
	v_ashrrev_i32_e32 v59, 31, v58
	v_lshlrev_b64 v[60:61], 5, v[58:59]
	v_lshl_add_u64 v[60:61], v[136:137], 0, v[60:61]
	s_waitcnt vmcnt(26)
	v_mov_b64_e32 v[60:61], v[162:163]
	v_lshlrev_b32_e32 v59, 16, v60
	v_fmac_f32_e32 v54, v14, v59
	v_mul_f32_e32 v59, 0x3d372713, v54
	v_mul_f32_e32 v59, v54, v59
	v_fma_f32 v59, v54, v59, v54
	v_mul_f32_e32 v59, 0x3f4c422a, v59
	v_add_f32_e32 v59, v59, v59
	v_mul_f32_e32 v59, 0x3fb8aa3b, v59
	v_exp_f32_e32 v59, v59
	v_mul_f32_e32 v54, 0.5, v54
	v_add_f32_e32 v59, 1.0, v59
	v_rcp_f32_e32 v59, v59
	s_nop 0
	v_fma_f32 v59, v59, -2.0, 1.0
	v_add_f32_e32 v59, 1.0, v59
	v_mul_f32_e32 v54, v54, v59
	v_and_b32_e32 v59, 0xffff0000, v60
	v_fmac_f32_e32 v55, v15, v59
	v_mul_f32_e32 v59, 0x3d372713, v55
	v_mul_f32_e32 v59, v55, v59
	v_fma_f32 v59, v55, v59, v55
	v_mul_f32_e32 v59, 0x3f4c422a, v59
	v_add_f32_e32 v59, v59, v59
	v_mul_f32_e32 v59, 0x3fb8aa3b, v59
	v_exp_f32_e32 v59, v59
	v_mul_f32_e32 v55, 0.5, v55
	v_add_f32_e32 v59, 1.0, v59
	v_rcp_f32_e32 v59, v59
	s_nop 0
	v_fma_f32 v59, v59, -2.0, 1.0
	v_add_f32_e32 v59, 1.0, v59
	v_mul_f32_e32 v55, v55, v59
	v_lshlrev_b32_e32 v59, 16, v61
	v_fmac_f32_e32 v56, v16, v59
	v_mul_f32_e32 v59, 0x3d372713, v56
	v_mul_f32_e32 v59, v56, v59
	v_fma_f32 v59, v56, v59, v56
	v_mul_f32_e32 v59, 0x3f4c422a, v59
	v_add_f32_e32 v59, v59, v59
	v_mul_f32_e32 v59, 0x3fb8aa3b, v59
	v_exp_f32_e32 v59, v59
	v_mul_f32_e32 v56, 0.5, v56
	v_cvt_pk_bf16_f32 v54, v54, v55
	v_add_f32_e32 v59, 1.0, v59
	v_rcp_f32_e32 v59, v59
	s_nop 0
	v_fma_f32 v59, v59, -2.0, 1.0
	v_add_f32_e32 v59, 1.0, v59
	v_mul_f32_e32 v56, v56, v59
	v_and_b32_e32 v59, 0xffff0000, v61
	v_fmac_f32_e32 v57, v17, v59
	v_mul_f32_e32 v59, 0x3d372713, v57
	v_mul_f32_e32 v59, v57, v59
	v_fma_f32 v59, v57, v59, v57
	v_mul_f32_e32 v59, 0x3f4c422a, v59
	v_add_f32_e32 v59, v59, v59
	v_mul_f32_e32 v59, 0x3fb8aa3b, v59
	v_exp_f32_e32 v59, v59
	v_mul_f32_e32 v57, 0.5, v57
	v_add_f32_e32 v59, 1.0, v59
	v_rcp_f32_e32 v59, v59
	s_nop 0
	v_fma_f32 v59, v59, -2.0, 1.0
	v_add_f32_e32 v59, 1.0, v59
	v_mul_f32_e32 v57, v57, v59
	v_cvt_pk_bf16_f32 v55, v56, v57
	v_add_u32_e32 v56, s19, v58
	v_ashrrev_i32_e32 v57, 31, v56
	v_lshlrev_b64 v[56:57], 11, v[56:57]
	v_lshl_add_u64 v[56:57], v[134:135], 0, v[56:57]
	global_store_dwordx2 v[56:57], v[54:55], off
	v_add_u32_e32 v54, s20, v234
	v_lshl_or_b32 v54, v54, 4, v229
	v_ashrrev_i32_e32 v55, 31, v54
	v_lshlrev_b64 v[56:57], 5, v[54:55]
	v_lshl_add_u64 v[56:57], v[136:137], 0, v[56:57]
	s_waitcnt vmcnt(25)
	v_mov_b64_e32 v[56:57], v[164:165]
	v_lshlrev_b32_e32 v55, 16, v56
	v_fmac_f32_e32 v50, v14, v55
	v_mul_f32_e32 v55, 0x3d372713, v50
	v_mul_f32_e32 v55, v50, v55
	v_fma_f32 v55, v50, v55, v50
	v_mul_f32_e32 v55, 0x3f4c422a, v55
	v_add_f32_e32 v55, v55, v55
	v_mul_f32_e32 v55, 0x3fb8aa3b, v55
	v_exp_f32_e32 v55, v55
	v_mul_f32_e32 v50, 0.5, v50
	v_add_f32_e32 v55, 1.0, v55
	v_rcp_f32_e32 v55, v55
	s_nop 0
	v_fma_f32 v55, v55, -2.0, 1.0
	v_add_f32_e32 v55, 1.0, v55
	v_mul_f32_e32 v50, v50, v55
	v_and_b32_e32 v55, 0xffff0000, v56
	v_fmac_f32_e32 v51, v15, v55
	v_mul_f32_e32 v55, 0x3d372713, v51
	v_mul_f32_e32 v55, v51, v55
	v_fma_f32 v55, v51, v55, v51
	v_mul_f32_e32 v55, 0x3f4c422a, v55
	v_add_f32_e32 v55, v55, v55
	v_mul_f32_e32 v55, 0x3fb8aa3b, v55
	v_exp_f32_e32 v55, v55
	v_mul_f32_e32 v51, 0.5, v51
	v_add_f32_e32 v55, 1.0, v55
	v_rcp_f32_e32 v55, v55
	s_nop 0
	v_fma_f32 v55, v55, -2.0, 1.0
	v_add_f32_e32 v55, 1.0, v55
	v_mul_f32_e32 v51, v51, v55
	v_lshlrev_b32_e32 v55, 16, v57
	v_fmac_f32_e32 v52, v16, v55
	v_mul_f32_e32 v55, 0x3d372713, v52
	v_mul_f32_e32 v55, v52, v55
	v_fma_f32 v55, v52, v55, v52
	v_mul_f32_e32 v55, 0x3f4c422a, v55
	v_add_f32_e32 v55, v55, v55
	v_mul_f32_e32 v55, 0x3fb8aa3b, v55
	v_exp_f32_e32 v55, v55
	v_mul_f32_e32 v52, 0.5, v52
	v_cvt_pk_bf16_f32 v50, v50, v51
	v_add_f32_e32 v55, 1.0, v55
	v_rcp_f32_e32 v55, v55
	s_nop 0
	v_fma_f32 v55, v55, -2.0, 1.0
	v_add_f32_e32 v55, 1.0, v55
	v_mul_f32_e32 v52, v52, v55
	v_and_b32_e32 v55, 0xffff0000, v57
	v_fmac_f32_e32 v53, v17, v55
	v_mul_f32_e32 v55, 0x3d372713, v53
	v_mul_f32_e32 v55, v53, v55
	v_fma_f32 v55, v53, v55, v53
	v_mul_f32_e32 v55, 0x3f4c422a, v55
	v_add_f32_e32 v55, v55, v55
	v_mul_f32_e32 v55, 0x3fb8aa3b, v55
	v_exp_f32_e32 v55, v55
	v_mul_f32_e32 v53, 0.5, v53
	v_add_f32_e32 v55, 1.0, v55
	v_rcp_f32_e32 v55, v55
	s_nop 0
	v_fma_f32 v55, v55, -2.0, 1.0
	v_add_f32_e32 v55, 1.0, v55
	v_mul_f32_e32 v53, v53, v55
	v_cvt_pk_bf16_f32 v51, v52, v53
	v_add_u32_e32 v52, s19, v54
	v_ashrrev_i32_e32 v53, 31, v52
	v_lshlrev_b64 v[52:53], 11, v[52:53]
	v_lshl_add_u64 v[52:53], v[134:135], 0, v[52:53]
	global_store_dwordx2 v[52:53], v[50:51], off
	v_or_b32_e32 v50, 1, v54
	v_ashrrev_i32_e32 v51, 31, v50
	v_lshlrev_b64 v[52:53], 5, v[50:51]
	v_lshl_add_u64 v[52:53], v[136:137], 0, v[52:53]
	s_waitcnt vmcnt(24)
	v_mov_b64_e32 v[52:53], v[166:167]
	v_lshlrev_b32_e32 v51, 16, v52
	v_fmac_f32_e32 v46, v14, v51
	v_mul_f32_e32 v51, 0x3d372713, v46
	v_mul_f32_e32 v51, v46, v51
	v_fma_f32 v51, v46, v51, v46
	v_mul_f32_e32 v51, 0x3f4c422a, v51
	v_add_f32_e32 v51, v51, v51
	v_mul_f32_e32 v51, 0x3fb8aa3b, v51
	v_exp_f32_e32 v51, v51
	v_mul_f32_e32 v46, 0.5, v46
	v_add_f32_e32 v51, 1.0, v51
	v_rcp_f32_e32 v51, v51
	s_nop 0
	v_fma_f32 v51, v51, -2.0, 1.0
	v_add_f32_e32 v51, 1.0, v51
	v_mul_f32_e32 v46, v46, v51
	v_and_b32_e32 v51, 0xffff0000, v52
	v_fmac_f32_e32 v47, v15, v51
	v_mul_f32_e32 v51, 0x3d372713, v47
	v_mul_f32_e32 v51, v47, v51
	v_fma_f32 v51, v47, v51, v47
	v_mul_f32_e32 v51, 0x3f4c422a, v51
	v_add_f32_e32 v51, v51, v51
	v_mul_f32_e32 v51, 0x3fb8aa3b, v51
	v_exp_f32_e32 v51, v51
	v_mul_f32_e32 v47, 0.5, v47
	v_add_f32_e32 v51, 1.0, v51
	v_rcp_f32_e32 v51, v51
	s_nop 0
	v_fma_f32 v51, v51, -2.0, 1.0
	v_add_f32_e32 v51, 1.0, v51
	v_mul_f32_e32 v47, v47, v51
	v_lshlrev_b32_e32 v51, 16, v53
	v_fmac_f32_e32 v48, v16, v51
	v_mul_f32_e32 v51, 0x3d372713, v48
	v_mul_f32_e32 v51, v48, v51
	v_fma_f32 v51, v48, v51, v48
	v_mul_f32_e32 v51, 0x3f4c422a, v51
	v_add_f32_e32 v51, v51, v51
	v_mul_f32_e32 v51, 0x3fb8aa3b, v51
	v_exp_f32_e32 v51, v51
	v_mul_f32_e32 v48, 0.5, v48
	v_cvt_pk_bf16_f32 v46, v46, v47
	v_add_f32_e32 v51, 1.0, v51
	v_rcp_f32_e32 v51, v51
	s_nop 0
	v_fma_f32 v51, v51, -2.0, 1.0
	v_add_f32_e32 v51, 1.0, v51
	v_mul_f32_e32 v48, v48, v51
	v_and_b32_e32 v51, 0xffff0000, v53
	v_fmac_f32_e32 v49, v17, v51
	v_mul_f32_e32 v51, 0x3d372713, v49
	v_mul_f32_e32 v51, v49, v51
	v_fma_f32 v51, v49, v51, v49
	v_mul_f32_e32 v51, 0x3f4c422a, v51
	v_add_f32_e32 v51, v51, v51
	v_mul_f32_e32 v51, 0x3fb8aa3b, v51
	v_exp_f32_e32 v51, v51
	v_mul_f32_e32 v49, 0.5, v49
	v_add_f32_e32 v51, 1.0, v51
	v_rcp_f32_e32 v51, v51
	s_nop 0
	v_fma_f32 v51, v51, -2.0, 1.0
	v_add_f32_e32 v51, 1.0, v51
	v_mul_f32_e32 v49, v49, v51
	v_cvt_pk_bf16_f32 v47, v48, v49
	v_add_u32_e32 v48, s19, v50
	v_ashrrev_i32_e32 v49, 31, v48
	v_lshlrev_b64 v[48:49], 11, v[48:49]
	v_lshl_add_u64 v[48:49], v[134:135], 0, v[48:49]
	global_store_dwordx2 v[48:49], v[46:47], off
	v_or_b32_e32 v46, 2, v54
	v_ashrrev_i32_e32 v47, 31, v46
	v_lshlrev_b64 v[48:49], 5, v[46:47]
	v_lshl_add_u64 v[48:49], v[136:137], 0, v[48:49]
	s_waitcnt vmcnt(23)
	v_mov_b64_e32 v[48:49], v[168:169]
	v_lshlrev_b32_e32 v47, 16, v48
	v_fmac_f32_e32 v42, v14, v47
	v_mul_f32_e32 v47, 0x3d372713, v42
	v_mul_f32_e32 v47, v42, v47
	v_fma_f32 v47, v42, v47, v42
	v_mul_f32_e32 v47, 0x3f4c422a, v47
	v_add_f32_e32 v47, v47, v47
	v_mul_f32_e32 v47, 0x3fb8aa3b, v47
	v_exp_f32_e32 v47, v47
	v_mul_f32_e32 v42, 0.5, v42
	v_add_f32_e32 v47, 1.0, v47
	v_rcp_f32_e32 v47, v47
	s_nop 0
	v_fma_f32 v47, v47, -2.0, 1.0
	v_add_f32_e32 v47, 1.0, v47
	v_mul_f32_e32 v42, v42, v47
	v_and_b32_e32 v47, 0xffff0000, v48
	v_fmac_f32_e32 v43, v15, v47
	v_mul_f32_e32 v47, 0x3d372713, v43
	v_mul_f32_e32 v47, v43, v47
	v_fma_f32 v47, v43, v47, v43
	v_mul_f32_e32 v47, 0x3f4c422a, v47
	v_add_f32_e32 v47, v47, v47
	v_mul_f32_e32 v47, 0x3fb8aa3b, v47
	v_exp_f32_e32 v47, v47
	v_mul_f32_e32 v43, 0.5, v43
	v_add_f32_e32 v47, 1.0, v47
	v_rcp_f32_e32 v47, v47
	s_nop 0
	v_fma_f32 v47, v47, -2.0, 1.0
	v_add_f32_e32 v47, 1.0, v47
	v_mul_f32_e32 v43, v43, v47
	v_lshlrev_b32_e32 v47, 16, v49
	v_fmac_f32_e32 v44, v16, v47
	v_mul_f32_e32 v47, 0x3d372713, v44
	v_mul_f32_e32 v47, v44, v47
	v_fma_f32 v47, v44, v47, v44
	v_mul_f32_e32 v47, 0x3f4c422a, v47
	v_add_f32_e32 v47, v47, v47
	v_mul_f32_e32 v47, 0x3fb8aa3b, v47
	v_exp_f32_e32 v47, v47
	v_mul_f32_e32 v44, 0.5, v44
	v_cvt_pk_bf16_f32 v42, v42, v43
	v_add_f32_e32 v47, 1.0, v47
	v_rcp_f32_e32 v47, v47
	s_nop 0
	v_fma_f32 v47, v47, -2.0, 1.0
	v_add_f32_e32 v47, 1.0, v47
	v_mul_f32_e32 v44, v44, v47
	v_and_b32_e32 v47, 0xffff0000, v49
	v_fmac_f32_e32 v45, v17, v47
	v_mul_f32_e32 v47, 0x3d372713, v45
	v_mul_f32_e32 v47, v45, v47
	v_fma_f32 v47, v45, v47, v45
	v_mul_f32_e32 v47, 0x3f4c422a, v47
	v_add_f32_e32 v47, v47, v47
	v_mul_f32_e32 v47, 0x3fb8aa3b, v47
	v_exp_f32_e32 v47, v47
	v_mul_f32_e32 v45, 0.5, v45
	v_add_f32_e32 v47, 1.0, v47
	v_rcp_f32_e32 v47, v47
	s_nop 0
	v_fma_f32 v47, v47, -2.0, 1.0
	v_add_f32_e32 v47, 1.0, v47
	v_mul_f32_e32 v45, v45, v47
	v_cvt_pk_bf16_f32 v43, v44, v45
	v_add_u32_e32 v44, s19, v46
	v_ashrrev_i32_e32 v45, 31, v44
	v_lshlrev_b64 v[44:45], 11, v[44:45]
	v_lshl_add_u64 v[44:45], v[134:135], 0, v[44:45]
	global_store_dwordx2 v[44:45], v[42:43], off
	v_or_b32_e32 v42, 3, v54
	v_ashrrev_i32_e32 v43, 31, v42
	v_lshlrev_b64 v[44:45], 5, v[42:43]
	v_lshl_add_u64 v[44:45], v[136:137], 0, v[44:45]
	s_waitcnt vmcnt(22)
	v_mov_b64_e32 v[44:45], v[170:171]
	v_lshlrev_b32_e32 v43, 16, v44
	v_fmac_f32_e32 v38, v14, v43
	v_mul_f32_e32 v43, 0x3d372713, v38
	v_mul_f32_e32 v43, v38, v43
	v_fma_f32 v43, v38, v43, v38
	v_mul_f32_e32 v43, 0x3f4c422a, v43
	v_add_f32_e32 v43, v43, v43
	v_mul_f32_e32 v43, 0x3fb8aa3b, v43
	v_exp_f32_e32 v43, v43
	v_mul_f32_e32 v38, 0.5, v38
	v_add_f32_e32 v43, 1.0, v43
	v_rcp_f32_e32 v43, v43
	s_nop 0
	v_fma_f32 v43, v43, -2.0, 1.0
	v_add_f32_e32 v43, 1.0, v43
	v_mul_f32_e32 v38, v38, v43
	v_and_b32_e32 v43, 0xffff0000, v44
	v_fmac_f32_e32 v39, v15, v43
	v_mul_f32_e32 v43, 0x3d372713, v39
	v_mul_f32_e32 v43, v39, v43
	v_fma_f32 v43, v39, v43, v39
	v_mul_f32_e32 v43, 0x3f4c422a, v43
	v_add_f32_e32 v43, v43, v43
	v_mul_f32_e32 v43, 0x3fb8aa3b, v43
	v_exp_f32_e32 v43, v43
	v_mul_f32_e32 v39, 0.5, v39
	v_add_f32_e32 v43, 1.0, v43
	v_rcp_f32_e32 v43, v43
	s_nop 0
	v_fma_f32 v43, v43, -2.0, 1.0
	v_add_f32_e32 v43, 1.0, v43
	v_mul_f32_e32 v39, v39, v43
	v_lshlrev_b32_e32 v43, 16, v45
	v_fmac_f32_e32 v40, v16, v43
	v_mul_f32_e32 v43, 0x3d372713, v40
	v_mul_f32_e32 v43, v40, v43
	v_fma_f32 v43, v40, v43, v40
	v_mul_f32_e32 v43, 0x3f4c422a, v43
	v_add_f32_e32 v43, v43, v43
	v_mul_f32_e32 v43, 0x3fb8aa3b, v43
	v_exp_f32_e32 v43, v43
	v_mul_f32_e32 v40, 0.5, v40
	v_cvt_pk_bf16_f32 v38, v38, v39
	v_add_f32_e32 v43, 1.0, v43
	v_rcp_f32_e32 v43, v43
	s_nop 0
	v_fma_f32 v43, v43, -2.0, 1.0
	v_add_f32_e32 v43, 1.0, v43
	v_mul_f32_e32 v40, v40, v43
	v_and_b32_e32 v43, 0xffff0000, v45
	v_fmac_f32_e32 v41, v17, v43
	v_mul_f32_e32 v43, 0x3d372713, v41
	v_mul_f32_e32 v43, v41, v43
	v_fma_f32 v43, v41, v43, v41
	v_mul_f32_e32 v43, 0x3f4c422a, v43
	v_add_f32_e32 v43, v43, v43
	v_mul_f32_e32 v43, 0x3fb8aa3b, v43
	v_exp_f32_e32 v43, v43
	v_mul_f32_e32 v41, 0.5, v41
	v_add_f32_e32 v43, 1.0, v43
	v_rcp_f32_e32 v43, v43
	s_nop 0
	v_fma_f32 v43, v43, -2.0, 1.0
	v_add_f32_e32 v43, 1.0, v43
	v_mul_f32_e32 v41, v41, v43
	v_cvt_pk_bf16_f32 v39, v40, v41
	v_add_u32_e32 v40, s19, v42
	v_ashrrev_i32_e32 v41, 31, v40
	v_lshlrev_b64 v[40:41], 11, v[40:41]
	v_lshl_add_u64 v[40:41], v[134:135], 0, v[40:41]
	global_store_dwordx2 v[40:41], v[38:39], off
	v_add_u32_e32 v38, s20, v235
	v_lshl_or_b32 v38, v38, 4, v229
	v_ashrrev_i32_e32 v39, 31, v38
	v_lshlrev_b64 v[40:41], 5, v[38:39]
	v_lshl_add_u64 v[40:41], v[136:137], 0, v[40:41]
	s_waitcnt vmcnt(21)
	v_mov_b64_e32 v[40:41], v[172:173]
	v_lshlrev_b32_e32 v39, 16, v40
	v_fmac_f32_e32 v34, v14, v39
	v_mul_f32_e32 v39, 0x3d372713, v34
	v_mul_f32_e32 v39, v34, v39
	v_fma_f32 v39, v34, v39, v34
	v_mul_f32_e32 v39, 0x3f4c422a, v39
	v_add_f32_e32 v39, v39, v39
	v_mul_f32_e32 v39, 0x3fb8aa3b, v39
	v_exp_f32_e32 v39, v39
	v_mul_f32_e32 v34, 0.5, v34
	v_add_f32_e32 v39, 1.0, v39
	v_rcp_f32_e32 v39, v39
	s_nop 0
	v_fma_f32 v39, v39, -2.0, 1.0
	v_add_f32_e32 v39, 1.0, v39
	v_mul_f32_e32 v34, v34, v39
	v_and_b32_e32 v39, 0xffff0000, v40
	v_fmac_f32_e32 v35, v15, v39
	v_mul_f32_e32 v39, 0x3d372713, v35
	v_mul_f32_e32 v39, v35, v39
	v_fma_f32 v39, v35, v39, v35
	v_mul_f32_e32 v39, 0x3f4c422a, v39
	v_add_f32_e32 v39, v39, v39
	v_mul_f32_e32 v39, 0x3fb8aa3b, v39
	v_exp_f32_e32 v39, v39
	v_mul_f32_e32 v35, 0.5, v35
	v_add_f32_e32 v39, 1.0, v39
	v_rcp_f32_e32 v39, v39
	s_nop 0
	v_fma_f32 v39, v39, -2.0, 1.0
	v_add_f32_e32 v39, 1.0, v39
	v_mul_f32_e32 v35, v35, v39
	v_lshlrev_b32_e32 v39, 16, v41
	v_fmac_f32_e32 v36, v16, v39
	v_mul_f32_e32 v39, 0x3d372713, v36
	v_mul_f32_e32 v39, v36, v39
	v_fma_f32 v39, v36, v39, v36
	v_mul_f32_e32 v39, 0x3f4c422a, v39
	v_add_f32_e32 v39, v39, v39
	v_mul_f32_e32 v39, 0x3fb8aa3b, v39
	v_exp_f32_e32 v39, v39
	v_mul_f32_e32 v36, 0.5, v36
	v_cvt_pk_bf16_f32 v34, v34, v35
	v_add_f32_e32 v39, 1.0, v39
	v_rcp_f32_e32 v39, v39
	s_nop 0
	v_fma_f32 v39, v39, -2.0, 1.0
	v_add_f32_e32 v39, 1.0, v39
	v_mul_f32_e32 v36, v36, v39
	v_and_b32_e32 v39, 0xffff0000, v41
	v_fmac_f32_e32 v37, v17, v39
	v_mul_f32_e32 v39, 0x3d372713, v37
	v_mul_f32_e32 v39, v37, v39
	v_fma_f32 v39, v37, v39, v37
	v_mul_f32_e32 v39, 0x3f4c422a, v39
	v_add_f32_e32 v39, v39, v39
	v_mul_f32_e32 v39, 0x3fb8aa3b, v39
	v_exp_f32_e32 v39, v39
	v_mul_f32_e32 v37, 0.5, v37
	v_add_f32_e32 v39, 1.0, v39
	v_rcp_f32_e32 v39, v39
	s_nop 0
	v_fma_f32 v39, v39, -2.0, 1.0
	v_add_f32_e32 v39, 1.0, v39
	v_mul_f32_e32 v37, v37, v39
	v_cvt_pk_bf16_f32 v35, v36, v37
	v_add_u32_e32 v36, s19, v38
	v_ashrrev_i32_e32 v37, 31, v36
	v_lshlrev_b64 v[36:37], 11, v[36:37]
	v_lshl_add_u64 v[36:37], v[134:135], 0, v[36:37]
	global_store_dwordx2 v[36:37], v[34:35], off
	v_or_b32_e32 v34, 1, v38
	v_ashrrev_i32_e32 v35, 31, v34
	v_lshlrev_b64 v[36:37], 5, v[34:35]
	v_lshl_add_u64 v[36:37], v[136:137], 0, v[36:37]
	s_waitcnt vmcnt(20)
	v_mov_b64_e32 v[36:37], v[174:175]
	v_lshlrev_b32_e32 v35, 16, v36
	v_fmac_f32_e32 v30, v14, v35
	v_mul_f32_e32 v35, 0x3d372713, v30
	v_mul_f32_e32 v35, v30, v35
	v_fma_f32 v35, v30, v35, v30
	v_mul_f32_e32 v35, 0x3f4c422a, v35
	v_add_f32_e32 v35, v35, v35
	v_mul_f32_e32 v35, 0x3fb8aa3b, v35
	v_exp_f32_e32 v35, v35
	v_mul_f32_e32 v30, 0.5, v30
	v_add_f32_e32 v35, 1.0, v35
	v_rcp_f32_e32 v35, v35
	s_nop 0
	v_fma_f32 v35, v35, -2.0, 1.0
	v_add_f32_e32 v35, 1.0, v35
	v_mul_f32_e32 v30, v30, v35
	v_and_b32_e32 v35, 0xffff0000, v36
	v_fmac_f32_e32 v31, v15, v35
	v_mul_f32_e32 v35, 0x3d372713, v31
	v_mul_f32_e32 v35, v31, v35
	v_fma_f32 v35, v31, v35, v31
	v_mul_f32_e32 v35, 0x3f4c422a, v35
	v_add_f32_e32 v35, v35, v35
	v_mul_f32_e32 v35, 0x3fb8aa3b, v35
	v_exp_f32_e32 v35, v35
	v_mul_f32_e32 v31, 0.5, v31
	v_add_f32_e32 v35, 1.0, v35
	v_rcp_f32_e32 v35, v35
	s_nop 0
	v_fma_f32 v35, v35, -2.0, 1.0
	v_add_f32_e32 v35, 1.0, v35
	v_mul_f32_e32 v31, v31, v35
	v_lshlrev_b32_e32 v35, 16, v37
	v_fmac_f32_e32 v32, v16, v35
	v_mul_f32_e32 v35, 0x3d372713, v32
	v_mul_f32_e32 v35, v32, v35
	v_fma_f32 v35, v32, v35, v32
	v_mul_f32_e32 v35, 0x3f4c422a, v35
	v_add_f32_e32 v35, v35, v35
	v_mul_f32_e32 v35, 0x3fb8aa3b, v35
	v_exp_f32_e32 v35, v35
	v_mul_f32_e32 v32, 0.5, v32
	v_cvt_pk_bf16_f32 v30, v30, v31
	v_add_f32_e32 v35, 1.0, v35
	v_rcp_f32_e32 v35, v35
	s_nop 0
	v_fma_f32 v35, v35, -2.0, 1.0
	v_add_f32_e32 v35, 1.0, v35
	v_mul_f32_e32 v32, v32, v35
	v_and_b32_e32 v35, 0xffff0000, v37
	v_fmac_f32_e32 v33, v17, v35
	v_mul_f32_e32 v35, 0x3d372713, v33
	v_mul_f32_e32 v35, v33, v35
	v_fma_f32 v35, v33, v35, v33
	v_mul_f32_e32 v35, 0x3f4c422a, v35
	v_add_f32_e32 v35, v35, v35
	v_mul_f32_e32 v35, 0x3fb8aa3b, v35
	v_exp_f32_e32 v35, v35
	v_mul_f32_e32 v33, 0.5, v33
	v_add_f32_e32 v35, 1.0, v35
	v_rcp_f32_e32 v35, v35
	s_nop 0
	v_fma_f32 v35, v35, -2.0, 1.0
	v_add_f32_e32 v35, 1.0, v35
	v_mul_f32_e32 v33, v33, v35
	v_cvt_pk_bf16_f32 v31, v32, v33
	v_add_u32_e32 v32, s19, v34
	v_ashrrev_i32_e32 v33, 31, v32
	v_lshlrev_b64 v[32:33], 11, v[32:33]
	v_lshl_add_u64 v[32:33], v[134:135], 0, v[32:33]
	global_store_dwordx2 v[32:33], v[30:31], off
	v_or_b32_e32 v30, 2, v38
	v_ashrrev_i32_e32 v31, 31, v30
	v_lshlrev_b64 v[32:33], 5, v[30:31]
	v_lshl_add_u64 v[32:33], v[136:137], 0, v[32:33]
	s_waitcnt vmcnt(19)
	v_mov_b64_e32 v[32:33], v[176:177]
	v_lshlrev_b32_e32 v31, 16, v32
	v_fmac_f32_e32 v26, v14, v31
	v_mul_f32_e32 v31, 0x3d372713, v26
	v_mul_f32_e32 v31, v26, v31
	v_fma_f32 v31, v26, v31, v26
	v_mul_f32_e32 v31, 0x3f4c422a, v31
	v_add_f32_e32 v31, v31, v31
	v_mul_f32_e32 v31, 0x3fb8aa3b, v31
	v_exp_f32_e32 v31, v31
	v_mul_f32_e32 v26, 0.5, v26
	v_add_f32_e32 v31, 1.0, v31
	v_rcp_f32_e32 v31, v31
	s_nop 0
	v_fma_f32 v31, v31, -2.0, 1.0
	v_add_f32_e32 v31, 1.0, v31
	v_mul_f32_e32 v26, v26, v31
	v_and_b32_e32 v31, 0xffff0000, v32
	v_fmac_f32_e32 v27, v15, v31
	v_mul_f32_e32 v31, 0x3d372713, v27
	v_mul_f32_e32 v31, v27, v31
	v_fma_f32 v31, v27, v31, v27
	v_mul_f32_e32 v31, 0x3f4c422a, v31
	v_add_f32_e32 v31, v31, v31
	v_mul_f32_e32 v31, 0x3fb8aa3b, v31
	v_exp_f32_e32 v31, v31
	v_mul_f32_e32 v27, 0.5, v27
	v_add_f32_e32 v31, 1.0, v31
	v_rcp_f32_e32 v31, v31
	s_nop 0
	v_fma_f32 v31, v31, -2.0, 1.0
	v_add_f32_e32 v31, 1.0, v31
	v_mul_f32_e32 v27, v27, v31
	v_lshlrev_b32_e32 v31, 16, v33
	v_fmac_f32_e32 v28, v16, v31
	v_mul_f32_e32 v31, 0x3d372713, v28
	v_mul_f32_e32 v31, v28, v31
	v_fma_f32 v31, v28, v31, v28
	v_mul_f32_e32 v31, 0x3f4c422a, v31
	v_add_f32_e32 v31, v31, v31
	v_mul_f32_e32 v31, 0x3fb8aa3b, v31
	v_exp_f32_e32 v31, v31
	v_mul_f32_e32 v28, 0.5, v28
	v_cvt_pk_bf16_f32 v26, v26, v27
	v_add_f32_e32 v31, 1.0, v31
	v_rcp_f32_e32 v31, v31
	s_nop 0
	v_fma_f32 v31, v31, -2.0, 1.0
	v_add_f32_e32 v31, 1.0, v31
	v_mul_f32_e32 v28, v28, v31
	v_and_b32_e32 v31, 0xffff0000, v33
	v_fmac_f32_e32 v29, v17, v31
	v_mul_f32_e32 v31, 0x3d372713, v29
	v_mul_f32_e32 v31, v29, v31
	v_fma_f32 v31, v29, v31, v29
	v_mul_f32_e32 v31, 0x3f4c422a, v31
	v_add_f32_e32 v31, v31, v31
	v_mul_f32_e32 v31, 0x3fb8aa3b, v31
	v_exp_f32_e32 v31, v31
	v_mul_f32_e32 v29, 0.5, v29
	v_add_f32_e32 v31, 1.0, v31
	v_rcp_f32_e32 v31, v31
	s_nop 0
	v_fma_f32 v31, v31, -2.0, 1.0
	v_add_f32_e32 v31, 1.0, v31
	v_mul_f32_e32 v29, v29, v31
	v_cvt_pk_bf16_f32 v27, v28, v29
	v_add_u32_e32 v28, s19, v30
	v_ashrrev_i32_e32 v29, 31, v28
	v_lshlrev_b64 v[28:29], 11, v[28:29]
	v_lshl_add_u64 v[28:29], v[134:135], 0, v[28:29]
	global_store_dwordx2 v[28:29], v[26:27], off
	v_or_b32_e32 v26, 3, v38
	v_ashrrev_i32_e32 v27, 31, v26
	v_lshlrev_b64 v[28:29], 5, v[26:27]
	v_lshl_add_u64 v[28:29], v[136:137], 0, v[28:29]
	s_waitcnt vmcnt(18)
	v_mov_b64_e32 v[28:29], v[178:179]
	v_lshlrev_b32_e32 v27, 16, v28
	v_fmac_f32_e32 v22, v14, v27
	v_mul_f32_e32 v27, 0x3d372713, v22
	v_mul_f32_e32 v27, v22, v27
	v_fma_f32 v27, v22, v27, v22
	v_mul_f32_e32 v27, 0x3f4c422a, v27
	v_add_f32_e32 v27, v27, v27
	v_mul_f32_e32 v27, 0x3fb8aa3b, v27
	v_exp_f32_e32 v27, v27
	v_mul_f32_e32 v22, 0.5, v22
	v_add_f32_e32 v27, 1.0, v27
	v_rcp_f32_e32 v27, v27
	s_nop 0
	v_fma_f32 v27, v27, -2.0, 1.0
	v_add_f32_e32 v27, 1.0, v27
	v_mul_f32_e32 v22, v22, v27
	v_and_b32_e32 v27, 0xffff0000, v28
	v_fmac_f32_e32 v23, v15, v27
	v_mul_f32_e32 v27, 0x3d372713, v23
	v_mul_f32_e32 v27, v23, v27
	v_fma_f32 v27, v23, v27, v23
	v_mul_f32_e32 v27, 0x3f4c422a, v27
	v_add_f32_e32 v27, v27, v27
	v_mul_f32_e32 v27, 0x3fb8aa3b, v27
	v_exp_f32_e32 v27, v27
	v_mul_f32_e32 v23, 0.5, v23
	v_add_f32_e32 v27, 1.0, v27
	v_rcp_f32_e32 v27, v27
	s_nop 0
	v_fma_f32 v27, v27, -2.0, 1.0
	v_add_f32_e32 v27, 1.0, v27
	v_mul_f32_e32 v23, v23, v27
	v_lshlrev_b32_e32 v27, 16, v29
	v_fmac_f32_e32 v24, v16, v27
	v_mul_f32_e32 v27, 0x3d372713, v24
	v_mul_f32_e32 v27, v24, v27
	v_fma_f32 v27, v24, v27, v24
	v_mul_f32_e32 v27, 0x3f4c422a, v27
	v_add_f32_e32 v27, v27, v27
	v_mul_f32_e32 v27, 0x3fb8aa3b, v27
	v_exp_f32_e32 v27, v27
	v_mul_f32_e32 v24, 0.5, v24
	v_cvt_pk_bf16_f32 v22, v22, v23
	v_add_f32_e32 v27, 1.0, v27
	v_rcp_f32_e32 v27, v27
	s_nop 0
	v_fma_f32 v27, v27, -2.0, 1.0
	v_add_f32_e32 v27, 1.0, v27
	v_mul_f32_e32 v24, v24, v27
	v_and_b32_e32 v27, 0xffff0000, v29
	v_fmac_f32_e32 v25, v17, v27
	v_mul_f32_e32 v27, 0x3d372713, v25
	v_mul_f32_e32 v27, v25, v27
	v_fma_f32 v27, v25, v27, v25
	v_mul_f32_e32 v27, 0x3f4c422a, v27
	v_add_f32_e32 v27, v27, v27
	v_mul_f32_e32 v27, 0x3fb8aa3b, v27
	v_exp_f32_e32 v27, v27
	v_mul_f32_e32 v25, 0.5, v25
	v_add_f32_e32 v27, 1.0, v27
	v_rcp_f32_e32 v27, v27
	s_nop 0
	v_fma_f32 v27, v27, -2.0, 1.0
	v_add_f32_e32 v27, 1.0, v27
	v_mul_f32_e32 v25, v25, v27
	v_cvt_pk_bf16_f32 v23, v24, v25
	v_add_u32_e32 v24, s19, v26
	v_ashrrev_i32_e32 v25, 31, v24
	v_lshlrev_b64 v[24:25], 11, v[24:25]
	v_lshl_add_u64 v[24:25], v[134:135], 0, v[24:25]
	global_store_dwordx2 v[24:25], v[22:23], off
	v_add_u32_e32 v22, s20, v236
	v_lshl_or_b32 v22, v22, 4, v229
	v_ashrrev_i32_e32 v23, 31, v22
	v_lshlrev_b64 v[24:25], 5, v[22:23]
	v_lshl_add_u64 v[24:25], v[136:137], 0, v[24:25]
	s_waitcnt vmcnt(17)
	v_mov_b64_e32 v[24:25], v[152:153]
	v_lshlrev_b32_e32 v23, 16, v24
	v_fmac_f32_e32 v18, v14, v23
	v_mul_f32_e32 v23, 0x3d372713, v18
	v_mul_f32_e32 v23, v18, v23
	v_fma_f32 v23, v18, v23, v18
	v_mul_f32_e32 v23, 0x3f4c422a, v23
	v_add_f32_e32 v23, v23, v23
	v_mul_f32_e32 v23, 0x3fb8aa3b, v23
	v_exp_f32_e32 v23, v23
	v_mul_f32_e32 v18, 0.5, v18
	v_add_f32_e32 v23, 1.0, v23
	v_rcp_f32_e32 v23, v23
	s_nop 0
	v_fma_f32 v23, v23, -2.0, 1.0
	v_add_f32_e32 v23, 1.0, v23
	v_mul_f32_e32 v18, v18, v23
	v_and_b32_e32 v23, 0xffff0000, v24
	v_fmac_f32_e32 v19, v15, v23
	v_mul_f32_e32 v23, 0x3d372713, v19
	v_mul_f32_e32 v23, v19, v23
	v_fma_f32 v23, v19, v23, v19
	v_mul_f32_e32 v23, 0x3f4c422a, v23
	v_add_f32_e32 v23, v23, v23
	v_mul_f32_e32 v23, 0x3fb8aa3b, v23
	v_exp_f32_e32 v23, v23
	v_mul_f32_e32 v19, 0.5, v19
	v_add_f32_e32 v23, 1.0, v23
	v_rcp_f32_e32 v23, v23
	s_nop 0
	v_fma_f32 v23, v23, -2.0, 1.0
	v_add_f32_e32 v23, 1.0, v23
	v_mul_f32_e32 v19, v19, v23
	v_lshlrev_b32_e32 v23, 16, v25
	v_fmac_f32_e32 v20, v16, v23
	v_mul_f32_e32 v23, 0x3d372713, v20
	v_mul_f32_e32 v23, v20, v23
	v_fma_f32 v23, v20, v23, v20
	v_mul_f32_e32 v23, 0x3f4c422a, v23
	v_add_f32_e32 v23, v23, v23
	v_mul_f32_e32 v23, 0x3fb8aa3b, v23
	v_exp_f32_e32 v23, v23
	v_mul_f32_e32 v20, 0.5, v20
	v_cvt_pk_bf16_f32 v18, v18, v19
	v_add_f32_e32 v23, 1.0, v23
	v_rcp_f32_e32 v23, v23
	s_nop 0
	v_fma_f32 v23, v23, -2.0, 1.0
	v_add_f32_e32 v23, 1.0, v23
	v_mul_f32_e32 v20, v20, v23
	v_and_b32_e32 v23, 0xffff0000, v25
	v_fmac_f32_e32 v21, v17, v23
	v_mul_f32_e32 v23, 0x3d372713, v21
	v_mul_f32_e32 v23, v21, v23
	v_fma_f32 v23, v21, v23, v21
	v_mul_f32_e32 v23, 0x3f4c422a, v23
	v_add_f32_e32 v23, v23, v23
	v_mul_f32_e32 v23, 0x3fb8aa3b, v23
	v_exp_f32_e32 v23, v23
	v_mul_f32_e32 v21, 0.5, v21
	v_add_f32_e32 v23, 1.0, v23
	v_rcp_f32_e32 v23, v23
	s_nop 0
	v_fma_f32 v23, v23, -2.0, 1.0
	v_add_f32_e32 v23, 1.0, v23
	v_mul_f32_e32 v21, v21, v23
	v_cvt_pk_bf16_f32 v19, v20, v21
	v_add_u32_e32 v20, s19, v22
	v_ashrrev_i32_e32 v21, 31, v20
	v_lshlrev_b64 v[20:21], 11, v[20:21]
	v_lshl_add_u64 v[20:21], v[134:135], 0, v[20:21]
	global_store_dwordx2 v[20:21], v[18:19], off
	v_or_b32_e32 v18, 1, v22
	v_ashrrev_i32_e32 v19, 31, v18
	v_lshlrev_b64 v[20:21], 5, v[18:19]
	v_lshl_add_u64 v[20:21], v[136:137], 0, v[20:21]
	s_waitcnt vmcnt(16)
; #define TILE_PMPN(t, pm, pn) do { int gid_ = (t) / nig, fm_ = gid_ * 8, gsz_ = min(nM - fm_, 8); pm = fm_ + (((t) % nig) % gsz_); pn = ((t) % nig) / gsz_; } while (0)
; #define GOFFS(D) do { _Pragma("unroll") for (int i = 0; i < 4; ++i) { int r_, c_; stage_rc2(wid * 1024 + i * 8192 + lane * 16, r_, c_); \
;     offA[i] = (unsigned)(r_ * D.ld1 + c_) * 2u; offB[i] = (unsigned)(r_ * D.K + c_) * 2u; } } while (0)
; template <class DescFn, class EpiFn>
; __device__ __forceinline__ void gemm_phase(int nM, int nN, DescFn dfn, EpiFn efn) {
;     ...
;     t += G;
;     const bool more = t < ntile;
;     if (more) { TILE_PMPN(t, pm, pn); D = dfn(pm, pn); GOFFS(D); GSTAGE(D, 0, 0); }
;     efn(cpm, cpn)(acc, wr, wc, fr, fq);
;     if (!more) break;
;     asm volatile("" : "+s"(D.ld1), "+s"(D.ld2), "+s"(D.K), "+s"(D.nk1));
;   }
	v_mov_b64_e32 v[20:21], v[154:155]
	v_lshlrev_b32_e32 v19, 16, v20
	v_fmac_f32_e32 v10, v14, v19
	v_mul_f32_e32 v19, 0x3d372713, v10
	v_mul_f32_e32 v19, v10, v19
	v_fma_f32 v19, v10, v19, v10
	v_mul_f32_e32 v19, 0x3f4c422a, v19
	v_add_f32_e32 v19, v19, v19
	v_mul_f32_e32 v19, 0x3fb8aa3b, v19
	v_exp_f32_e32 v19, v19
	v_mul_f32_e32 v10, 0.5, v10
	v_add_f32_e32 v19, 1.0, v19
	v_rcp_f32_e32 v19, v19
	s_nop 0
	v_fma_f32 v19, v19, -2.0, 1.0
	v_add_f32_e32 v19, 1.0, v19
	v_mul_f32_e32 v10, v10, v19
	v_and_b32_e32 v19, 0xffff0000, v20
	v_fmac_f32_e32 v11, v15, v19
	v_mul_f32_e32 v19, 0x3d372713, v11
	v_mul_f32_e32 v19, v11, v19
	v_fma_f32 v19, v11, v19, v11
	v_mul_f32_e32 v19, 0x3f4c422a, v19
	v_add_f32_e32 v19, v19, v19
	v_mul_f32_e32 v19, 0x3fb8aa3b, v19
	v_exp_f32_e32 v19, v19
	v_mul_f32_e32 v11, 0.5, v11
	v_add_f32_e32 v19, 1.0, v19
	v_rcp_f32_e32 v19, v19
	s_nop 0
	v_fma_f32 v19, v19, -2.0, 1.0
	v_add_f32_e32 v19, 1.0, v19
	v_mul_f32_e32 v11, v11, v19
	v_lshlrev_b32_e32 v19, 16, v21
	v_fmac_f32_e32 v12, v16, v19
	v_mul_f32_e32 v19, 0x3d372713, v12
	v_mul_f32_e32 v19, v12, v19
	v_fma_f32 v19, v12, v19, v12
	v_mul_f32_e32 v19, 0x3f4c422a, v19
	v_add_f32_e32 v19, v19, v19
	v_mul_f32_e32 v19, 0x3fb8aa3b, v19
	v_exp_f32_e32 v19, v19
	v_mul_f32_e32 v12, 0.5, v12
	v_cvt_pk_bf16_f32 v10, v10, v11
	v_add_f32_e32 v19, 1.0, v19
	v_rcp_f32_e32 v19, v19
	s_nop 0
	v_fma_f32 v19, v19, -2.0, 1.0
	v_add_f32_e32 v19, 1.0, v19
	v_mul_f32_e32 v12, v12, v19
	v_and_b32_e32 v19, 0xffff0000, v21
	v_fmac_f32_e32 v13, v17, v19
	v_mul_f32_e32 v19, 0x3d372713, v13
	v_mul_f32_e32 v19, v13, v19
	v_fma_f32 v19, v13, v19, v13
	v_mul_f32_e32 v19, 0x3f4c422a, v19
	v_add_f32_e32 v19, v19, v19
	v_mul_f32_e32 v19, 0x3fb8aa3b, v19
	v_exp_f32_e32 v19, v19
	v_mul_f32_e32 v13, 0.5, v13
	v_add_f32_e32 v19, 1.0, v19
	v_rcp_f32_e32 v19, v19
	s_nop 0
	v_fma_f32 v19, v19, -2.0, 1.0
	v_add_f32_e32 v19, 1.0, v19
	v_mul_f32_e32 v13, v13, v19
	v_cvt_pk_bf16_f32 v11, v12, v13
	v_add_u32_e32 v12, s19, v18
	v_ashrrev_i32_e32 v13, 31, v12
	v_lshlrev_b64 v[12:13], 11, v[12:13]
	v_lshl_add_u64 v[12:13], v[134:135], 0, v[12:13]
	global_store_dwordx2 v[12:13], v[10:11], off
	v_or_b32_e32 v10, 2, v22
	v_ashrrev_i32_e32 v11, 31, v10
	v_lshlrev_b64 v[12:13], 5, v[10:11]
	v_lshl_add_u64 v[12:13], v[136:137], 0, v[12:13]
	s_waitcnt vmcnt(15)
	v_mov_b64_e32 v[12:13], v[156:157]
	v_lshlrev_b32_e32 v11, 16, v12
	v_fmac_f32_e32 v6, v14, v11
	v_mul_f32_e32 v11, 0x3d372713, v6
	v_mul_f32_e32 v11, v6, v11
	v_fma_f32 v11, v6, v11, v6
	v_mul_f32_e32 v11, 0x3f4c422a, v11
	v_add_f32_e32 v11, v11, v11
	v_mul_f32_e32 v11, 0x3fb8aa3b, v11
	v_exp_f32_e32 v11, v11
	v_mul_f32_e32 v6, 0.5, v6
	v_add_f32_e32 v11, 1.0, v11
	v_rcp_f32_e32 v11, v11
	s_nop 0
	v_fma_f32 v11, v11, -2.0, 1.0
	v_add_f32_e32 v11, 1.0, v11
	v_mul_f32_e32 v6, v6, v11
	v_and_b32_e32 v11, 0xffff0000, v12
	v_fmac_f32_e32 v7, v15, v11
	v_mul_f32_e32 v11, 0x3d372713, v7
	v_mul_f32_e32 v11, v7, v11
	v_fma_f32 v11, v7, v11, v7
	v_mul_f32_e32 v11, 0x3f4c422a, v11
	v_add_f32_e32 v11, v11, v11
	v_mul_f32_e32 v11, 0x3fb8aa3b, v11
	v_exp_f32_e32 v11, v11
	v_mul_f32_e32 v7, 0.5, v7
	v_add_f32_e32 v11, 1.0, v11
	v_rcp_f32_e32 v11, v11
	s_nop 0
	v_fma_f32 v11, v11, -2.0, 1.0
	v_add_f32_e32 v11, 1.0, v11
	v_mul_f32_e32 v7, v7, v11
	v_lshlrev_b32_e32 v11, 16, v13
	v_fmac_f32_e32 v8, v16, v11
	v_mul_f32_e32 v11, 0x3d372713, v8
	v_mul_f32_e32 v11, v8, v11
	v_fma_f32 v11, v8, v11, v8
	v_mul_f32_e32 v11, 0x3f4c422a, v11
	v_add_f32_e32 v11, v11, v11
	v_mul_f32_e32 v11, 0x3fb8aa3b, v11
	v_exp_f32_e32 v11, v11
	v_mul_f32_e32 v8, 0.5, v8
	v_cvt_pk_bf16_f32 v6, v6, v7
	v_add_f32_e32 v11, 1.0, v11
	v_rcp_f32_e32 v11, v11
	s_nop 0
	v_fma_f32 v11, v11, -2.0, 1.0
	v_add_f32_e32 v11, 1.0, v11
	v_mul_f32_e32 v8, v8, v11
	v_and_b32_e32 v11, 0xffff0000, v13
	v_fmac_f32_e32 v9, v17, v11
	v_mul_f32_e32 v11, 0x3d372713, v9
	v_mul_f32_e32 v11, v9, v11
	v_fma_f32 v11, v9, v11, v9
	v_mul_f32_e32 v11, 0x3f4c422a, v11
	v_add_f32_e32 v11, v11, v11
	v_mul_f32_e32 v11, 0x3fb8aa3b, v11
	v_exp_f32_e32 v11, v11
	v_mul_f32_e32 v9, 0.5, v9
	v_add_f32_e32 v11, 1.0, v11
	v_rcp_f32_e32 v11, v11
	s_nop 0
	v_fma_f32 v11, v11, -2.0, 1.0
	v_add_f32_e32 v11, 1.0, v11
	v_mul_f32_e32 v9, v9, v11
	v_cvt_pk_bf16_f32 v7, v8, v9
	v_add_u32_e32 v8, s19, v10
	v_ashrrev_i32_e32 v9, 31, v8
	v_lshlrev_b64 v[8:9], 11, v[8:9]
	v_lshl_add_u64 v[8:9], v[134:135], 0, v[8:9]
	global_store_dwordx2 v[8:9], v[6:7], off
	v_or_b32_e32 v6, 3, v22
	v_ashrrev_i32_e32 v7, 31, v6
	v_lshlrev_b64 v[8:9], 5, v[6:7]
	v_lshl_add_u64 v[8:9], v[136:137], 0, v[8:9]
	s_waitcnt vmcnt(14)
	v_mov_b64_e32 v[8:9], v[158:159]
	v_lshlrev_b32_e32 v7, 16, v8
	v_fmac_f32_e32 v2, v14, v7
	v_mul_f32_e32 v7, 0x3d372713, v2
	v_mul_f32_e32 v7, v2, v7
	v_fma_f32 v7, v2, v7, v2
	v_mul_f32_e32 v7, 0x3f4c422a, v7
	v_add_f32_e32 v7, v7, v7
	v_mul_f32_e32 v7, 0x3fb8aa3b, v7
	v_exp_f32_e32 v7, v7
	v_mul_f32_e32 v2, 0.5, v2
	v_add_f32_e32 v7, 1.0, v7
	v_rcp_f32_e32 v7, v7
	s_nop 0
	v_fma_f32 v7, v7, -2.0, 1.0
	v_add_f32_e32 v7, 1.0, v7
	v_mul_f32_e32 v2, v2, v7
	v_and_b32_e32 v7, 0xffff0000, v8
	v_fmac_f32_e32 v3, v15, v7
	v_mul_f32_e32 v7, 0x3d372713, v3
	v_mul_f32_e32 v7, v3, v7
	v_fma_f32 v7, v3, v7, v3
	v_mul_f32_e32 v7, 0x3f4c422a, v7
	v_add_f32_e32 v7, v7, v7
	v_mul_f32_e32 v7, 0x3fb8aa3b, v7
	v_exp_f32_e32 v7, v7
	v_mul_f32_e32 v3, 0.5, v3
	v_add_f32_e32 v7, 1.0, v7
	v_rcp_f32_e32 v7, v7
	s_nop 0
	v_fma_f32 v7, v7, -2.0, 1.0
	v_add_f32_e32 v7, 1.0, v7
	v_mul_f32_e32 v3, v3, v7
	v_lshlrev_b32_e32 v7, 16, v9
	v_fmac_f32_e32 v4, v16, v7
	v_mul_f32_e32 v7, 0x3d372713, v4
	v_mul_f32_e32 v7, v4, v7
	v_fma_f32 v7, v4, v7, v4
	v_mul_f32_e32 v7, 0x3f4c422a, v7
	v_add_f32_e32 v7, v7, v7
	v_mul_f32_e32 v7, 0x3fb8aa3b, v7
	v_exp_f32_e32 v7, v7
	v_mul_f32_e32 v4, 0.5, v4
	v_cvt_pk_bf16_f32 v2, v2, v3
	v_add_f32_e32 v7, 1.0, v7
	v_rcp_f32_e32 v7, v7
	s_nop 0
	v_fma_f32 v7, v7, -2.0, 1.0
	v_add_f32_e32 v7, 1.0, v7
	v_mul_f32_e32 v4, v4, v7
	v_and_b32_e32 v7, 0xffff0000, v9
	v_fmac_f32_e32 v5, v17, v7
	v_mul_f32_e32 v7, 0x3d372713, v5
	v_mul_f32_e32 v7, v5, v7
	v_fma_f32 v7, v5, v7, v5
	v_mul_f32_e32 v7, 0x3f4c422a, v7
	v_add_f32_e32 v7, v7, v7
	v_mul_f32_e32 v7, 0x3fb8aa3b, v7
	v_exp_f32_e32 v7, v7
	v_mul_f32_e32 v5, 0.5, v5
	v_add_f32_e32 v7, 1.0, v7
	v_rcp_f32_e32 v7, v7
	s_nop 0
	v_fma_f32 v7, v7, -2.0, 1.0
	v_add_f32_e32 v7, 1.0, v7
	v_mul_f32_e32 v5, v5, v7
	v_cvt_pk_bf16_f32 v3, v4, v5
	v_add_u32_e32 v4, s19, v6
	v_ashrrev_i32_e32 v5, 31, v4
	v_lshlrev_b64 v[4:5], 11, v[4:5]
	v_lshl_add_u64 v[4:5], v[134:135], 0, v[4:5]
	global_store_dwordx2 v[4:5], v[2:3], off
	s_andn2_b64 vcc, exec, s[16:17]
	s_mov_b64 s[16:17], -1
	s_cbranch_vccnz .LBB0_1412
	s_mov_b64 s[16:17], 0
	s_branch .LBB0_1412

; __device__ __forceinline__ int otid() { int t = threadIdx.x; asm volatile("" : "+v"(t)); return t; }
; __device__ __forceinline__ int obid() { int t = blockIdx.x; asm volatile("" : "+s"(t)); return t; }
; __device__ __forceinline__ void ln_phase(const PRef& P, const float* __restrict__ gw, const float* __restrict__ bw, bool write_f32) {
;   float* H = P.out(); bfr* hb = (bfr*)(P.ws() + WS_HB); float2* st = (float2*)(P.ws() + WS_MISC + MS_STATS);
;   const int lane = otid() & 63, wv = obid() * 8 + (otid() >> 6), nw = gridDim.x * 8;
;   for (int row = wv; row < TT; row += 2 * nw) {
;     float4* hp0 = (float4*)(H + (long)row * DM); float4* hp1 = (float4*)(H + (long)(row + nw) * DM); float4 v[2][4]; float s0 = 0.f, s1 = 0.f;
; #pragma unroll
;     for (int i = 0; i < 4; ++i) { v[0][i] = hp0[lane + 64 * i]; v[1][i] = hp1[lane + 64 * i]; }
; #pragma unroll
;     for (int i = 0; i < 4; ++i) { s0 += v[0][i].x + v[0][i].y + v[0][i].z + v[0][i].w; s1 += v[1][i].x + v[1][i].y + v[1][i].z + v[1][i].w; }
; #pragma unroll
;     for (int o = 32; o > 0; o >>= 1) { s0 += __shfl_xor(s0, o); s1 += __shfl_xor(s1, o); }
;     const float mu0 = s0 * (1.f / DM), mu1 = s1 * (1.f / DM); float q0 = 0.f, q1 = 0.f;
.LBB0_1487:
	s_and_b64 vcc, exec, s[58:59]
	s_cbranch_vccz .LBB0_2495
	v_readlane_b32 s10, v255, 21
	v_readlane_b32 s11, v255, 22
	s_mov_b64 s[8:9], -1
	s_and_b64 vcc, exec, s[10:11]
	s_cbranch_vccz .LBB0_1503
	s_mov_b64 s[12:13], exec
	v_readlane_b32 s8, v255, 15
	v_readlane_b32 s9, v255, 16
	s_nop 0
	s_load_dwordx4 s[16:19], s[8:9], 0x20
	s_load_dwordx4 s[20:23], s[8:9], 0xf0
	v_readlane_b32 s2, v255, 13
	v_and_b32_e32 v2, 63, v182
	v_lshrrev_b32_e32 v3, 6, v182
	v_lshlrev_b32_e32 v4, 4, v2
	v_lshlrev_b32_e32 v5, 3, v2
	s_lshl_b32 s10, s2, 12
	s_cmp_eq_u32 s2, 3
	s_cselect_b32 s14, 1, 0
	v_readfirstlane_b32 s15, v3
	s_lshl_b32 s11, s94, 3
	s_waitcnt lgkmcnt(0)
	s_add_u32 s16, s16, s10
	s_addc_u32 s17, s17, 0
	s_add_u32 s18, s18, s10
	s_addc_u32 s19, s19, 0
	global_load_dwordx4 v[8:11], v4, s[16:17]
	global_load_dwordx4 v[24:27], v4, s[18:19]
	global_load_dwordx4 v[12:15], v4, s[16:17] offset:1024
	global_load_dwordx4 v[28:31], v4, s[18:19] offset:1024
	global_load_dwordx4 v[16:19], v4, s[16:17] offset:2048
	global_load_dwordx4 v[32:35], v4, s[18:19] offset:2048
	global_load_dwordx4 v[20:23], v4, s[16:17] offset:3072
	global_load_dwordx4 v[36:39], v4, s[18:19] offset:3072
	s_add_u32 s11, s11, s15
	s_lshl_b32 s15, s96, 3
	s_add_u32 s8, s22, 0x3000000
	s_addc_u32 s9, s23, 0
	s_add_u32 s22, s22, 0x1d980000
	s_addc_u32 s23, s23, 0
	s_cmpk_ge_u32 s11, 0x8000
	s_cbranch_scc1 .Llnb_done
	s_lshl_b32 s2, s11, 12
	s_add_u32 s16, s20, s2
	s_addc_u32 s17, s21, 0
	s_lshl_b32 s10, s15, 12
	s_add_u32 s18, s16, s10
	s_addc_u32 s19, s17, 0
	global_load_dwordx4 v[40:43], v4, s[16:17]
	global_load_dwordx4 v[44:47], v4, s[16:17] offset:1024
	global_load_dwordx4 v[48:51], v4, s[16:17] offset:2048
	global_load_dwordx4 v[52:55], v4, s[16:17] offset:3072
	global_load_dwordx4 v[56:59], v4, s[18:19]
	global_load_dwordx4 v[60:63], v4, s[18:19] offset:1024
	global_load_dwordx4 v[64:67], v4, s[18:19] offset:2048
	global_load_dwordx4 v[68:71], v4, s[18:19] offset:3072
	s_lshl_b32 s10, s15, 1
	s_add_u32 s10, s11, s10
	s_cmpk_lt_u32 s10, 0x8000
	s_cselect_b32 s10, s10, s11
	s_lshl_b32 s2, s10, 12
	s_add_u32 s16, s20, s2
	s_addc_u32 s17, s21, 0
	s_lshl_b32 s10, s15, 12
	s_add_u32 s18, s16, s10
	s_addc_u32 s19, s17, 0
	global_load_dwordx4 v[72:75], v4, s[16:17]
	global_load_dwordx4 v[76:79], v4, s[16:17] offset:1024
	global_load_dwordx4 v[80:83], v4, s[16:17] offset:2048
	global_load_dwordx4 v[84:87], v4, s[16:17] offset:3072
	global_load_dwordx4 v[88:91], v4, s[18:19]
	global_load_dwordx4 v[92:95], v4, s[18:19] offset:1024
	global_load_dwordx4 v[96:99], v4, s[18:19] offset:2048
	global_load_dwordx4 v[100:103], v4, s[18:19] offset:3072
	s_waitcnt vmcnt(8)
	v_add_f32_e32 v104, v40, v41
	v_add_f32_e32 v105, v56, v57
	v_add_f32_e32 v104, v104, v42
	v_add_f32_e32 v105, v105, v58
	v_add_f32_e32 v104, v104, v43
	v_add_f32_e32 v105, v105, v59
	v_add_f32_e32 v104, v104, v44
	v_add_f32_e32 v105, v105, v60
	v_add_f32_e32 v104, v104, v45
	v_add_f32_e32 v105, v105, v61
	v_add_f32_e32 v104, v104, v46
	v_add_f32_e32 v105, v105, v62
	v_add_f32_e32 v104, v104, v47
	v_add_f32_e32 v105, v105, v63
	v_add_f32_e32 v104, v104, v48
	v_add_f32_e32 v105, v105, v64
	v_add_f32_e32 v104, v104, v49
	v_add_f32_e32 v105, v105, v65
	v_add_f32_e32 v104, v104, v50
	v_add_f32_e32 v105, v105, v66
	v_add_f32_e32 v104, v104, v51
	v_add_f32_e32 v105, v105, v67
	v_add_f32_e32 v104, v104, v52
	v_add_f32_e32 v105, v105, v68
	v_add_f32_e32 v104, v104, v53
	v_add_f32_e32 v105, v105, v69
	v_add_f32_e32 v104, v104, v54
	v_add_f32_e32 v105, v105, v70
	v_add_f32_e32 v104, v104, v55
	v_add_f32_e32 v105, v105, v71
	s_nop 1
	v_add_f32_dpp v104, v104, v104 quad_perm:[1,0,3,2] row_mask:0xf bank_mask:0xf
	v_add_f32_dpp v105, v105, v105 quad_perm:[1,0,3,2] row_mask:0xf bank_mask:0xf
	s_nop 1
	v_add_f32_dpp v104, v104, v104 quad_perm:[2,3,0,1] row_mask:0xf bank_mask:0xf
	v_add_f32_dpp v105, v105, v105 quad_perm:[2,3,0,1] row_mask:0xf bank_mask:0xf
	s_nop 1
	v_add_f32_dpp v104, v104, v104 row_half_mirror row_mask:0xf bank_mask:0xf
	v_add_f32_dpp v105, v105, v105 row_half_mirror row_mask:0xf bank_mask:0xf
	s_nop 1
	v_add_f32_dpp v104, v104, v104 row_mirror row_mask:0xf bank_mask:0xf
	v_add_f32_dpp v105, v105, v105 row_mirror row_mask:0xf bank_mask:0xf
	s_nop 1
	v_readlane_b32 s2, v104, 0
	v_readlane_b32 s10, v104, 16
	v_readlane_b32 s16, v104, 32
	v_readlane_b32 s17, v104, 48
	v_readlane_b32 s18, v105, 0
	v_readlane_b32 s19, v105, 16
	v_mov_b32_e32 v104, s2
	v_add_f32_e32 v104, s10, v104
	v_add_f32_e32 v104, s16, v104
	v_add_f32_e32 v104, s17, v104
	v_readlane_b32 s2, v105, 32
	v_readlane_b32 s10, v105, 48
	v_mov_b32_e32 v105, s18
	v_add_f32_e32 v105, s19, v105
	s_nop 0
	v_add_f32_e32 v105, s2, v105
	v_add_f32_e32 v105, s10, v105
	v_mul_f32_e32 v108, 0x3a800000, v104
	v_mul_f32_e32 v110, 0x3a800000, v105
	v_sub_f32_e32 v40, v40, v108
	v_sub_f32_e32 v56, v56, v110
	v_sub_f32_e32 v41, v41, v108
	v_sub_f32_e32 v57, v57, v110
	v_sub_f32_e32 v42, v42, v108
	v_sub_f32_e32 v58, v58, v110
	v_sub_f32_e32 v43, v43, v108
	v_sub_f32_e32 v59, v59, v110
	v_sub_f32_e32 v44, v44, v108
	v_sub_f32_e32 v60, v60, v110
	v_sub_f32_e32 v45, v45, v108
	v_sub_f32_e32 v61, v61, v110
	v_sub_f32_e32 v46, v46, v108
	v_sub_f32_e32 v62, v62, v110
	v_sub_f32_e32 v47, v47, v108
	v_sub_f32_e32 v63, v63, v110
	v_sub_f32_e32 v48, v48, v108
; __device__ __forceinline__ void ln_phase(const PRef& P, const float* __restrict__ gw, const float* __restrict__ bw, bool write_f32) {
;     ...
;     const float mu0 = s0 * (1.f / DM), mu1 = s1 * (1.f / DM); float q0 = 0.f, q1 = 0.f;
; #pragma unroll
;     for (int i = 0; i < 4; ++i) { float a = v[0][i].x - mu0, b = v[0][i].y - mu0, c = v[0][i].z - mu0, d = v[0][i].w - mu0; q0 += a * a + b * b + c * c + d * d;
;       float e = v[1][i].x - mu1, f = v[1][i].y - mu1, g = v[1][i].z - mu1, h = v[1][i].w - mu1; q1 += e * e + f * f + g * g + h * h; }
; #pragma unroll
;     for (int o = 32; o > 0; o >>= 1) { q0 += __shfl_xor(q0, o); q1 += __shfl_xor(q1, o); }
;     const float rs0 = rsqrtf(q0 * (1.f / DM) + 1e-5f), rs1 = rsqrtf(q1 * (1.f / DM) + 1e-5f);
;     if (lane == 0) { st[row] = make_float2(mu0, rs0); st[row + nw] = make_float2(mu1, rs1); }
; #pragma unroll
;     for (int i = 0; i < 4; ++i) { float4 g4 = ((const float4*)gw)[lane + 64 * i], b4 = ((const float4*)bw)[lane + 64 * i]; float4 o4, p4;
;       o4.x = (v[0][i].x - mu0) * rs0 * g4.x + b4.x; o4.y = (v[0][i].y - mu0) * rs0 * g4.y + b4.y; o4.z = (v[0][i].z - mu0) * rs0 * g4.z + b4.z; o4.w = (v[0][i].w - mu0) * rs0 * g4.w + b4.w;
;       p4.x = (v[1][i].x - mu1) * rs1 * g4.x + b4.x; p4.y = (v[1][i].y - mu1) * rs1 * g4.y + b4.y; p4.z = (v[1][i].z - mu1) * rs1 * g4.z + b4.z; p4.w = (v[1][i].w - mu1) * rs1 * g4.w + b4.w;
;       if (write_f32) { hp0[lane + 64 * i] = o4; hp1[lane + 64 * i] = p4; }
	v_sub_f32_e32 v64, v64, v110
	v_sub_f32_e32 v49, v49, v108
	v_sub_f32_e32 v65, v65, v110
	v_sub_f32_e32 v50, v50, v108
	v_sub_f32_e32 v66, v66, v110
	v_sub_f32_e32 v51, v51, v108
	v_sub_f32_e32 v67, v67, v110
	v_sub_f32_e32 v52, v52, v108
	v_sub_f32_e32 v68, v68, v110
	v_sub_f32_e32 v53, v53, v108
	v_sub_f32_e32 v69, v69, v110
	v_sub_f32_e32 v54, v54, v108
	v_sub_f32_e32 v70, v70, v110
	v_sub_f32_e32 v55, v55, v108
	v_sub_f32_e32 v71, v71, v110
	v_mul_f32_e32 v106, v40, v40
	v_mul_f32_e32 v107, v56, v56
	v_fmac_f32_e32 v106, v41, v41
	v_fmac_f32_e32 v107, v57, v57
	v_fmac_f32_e32 v106, v42, v42
	v_fmac_f32_e32 v107, v58, v58
	v_fmac_f32_e32 v106, v43, v43
	v_fmac_f32_e32 v107, v59, v59
	v_fmac_f32_e32 v106, v44, v44
	v_fmac_f32_e32 v107, v60, v60
	v_fmac_f32_e32 v106, v45, v45
	v_fmac_f32_e32 v107, v61, v61
	v_fmac_f32_e32 v106, v46, v46
	v_fmac_f32_e32 v107, v62, v62
	v_fmac_f32_e32 v106, v47, v47
	v_fmac_f32_e32 v107, v63, v63
	v_fmac_f32_e32 v106, v48, v48
	v_fmac_f32_e32 v107, v64, v64
	v_fmac_f32_e32 v106, v49, v49
	v_fmac_f32_e32 v107, v65, v65
	v_fmac_f32_e32 v106, v50, v50
	v_fmac_f32_e32 v107, v66, v66
	v_fmac_f32_e32 v106, v51, v51
	v_fmac_f32_e32 v107, v67, v67
	v_fmac_f32_e32 v106, v52, v52
	v_fmac_f32_e32 v107, v68, v68
	v_fmac_f32_e32 v106, v53, v53
	v_fmac_f32_e32 v107, v69, v69
	v_fmac_f32_e32 v106, v54, v54
	v_fmac_f32_e32 v107, v70, v70
	v_fmac_f32_e32 v106, v55, v55
	v_fmac_f32_e32 v107, v71, v71
	s_nop 1
	v_add_f32_dpp v106, v106, v106 quad_perm:[1,0,3,2] row_mask:0xf bank_mask:0xf
	v_add_f32_dpp v107, v107, v107 quad_perm:[1,0,3,2] row_mask:0xf bank_mask:0xf
	s_nop 1
	v_add_f32_dpp v106, v106, v106 quad_perm:[2,3,0,1] row_mask:0xf bank_mask:0xf
	v_add_f32_dpp v107, v107, v107 quad_perm:[2,3,0,1] row_mask:0xf bank_mask:0xf
	s_nop 1
	v_add_f32_dpp v106, v106, v106 row_half_mirror row_mask:0xf bank_mask:0xf
	v_add_f32_dpp v107, v107, v107 row_half_mirror row_mask:0xf bank_mask:0xf
	s_nop 1
	v_add_f32_dpp v106, v106, v106 row_mirror row_mask:0xf bank_mask:0xf
	v_add_f32_dpp v107, v107, v107 row_mirror row_mask:0xf bank_mask:0xf
	s_nop 1
	v_readlane_b32 s2, v106, 0
	v_readlane_b32 s10, v106, 16
	v_readlane_b32 s16, v106, 32
	v_readlane_b32 s17, v106, 48
	v_readlane_b32 s18, v107, 0
	v_readlane_b32 s19, v107, 16
	v_mov_b32_e32 v106, s2
	v_add_f32_e32 v106, s10, v106
	v_add_f32_e32 v106, s16, v106
	v_add_f32_e32 v106, s17, v106
	v_readlane_b32 s2, v107, 32
	v_readlane_b32 s10, v107, 48
	v_mov_b32_e32 v107, s18
	v_add_f32_e32 v107, s19, v107
	s_nop 0
	v_add_f32_e32 v107, s2, v107
	v_add_f32_e32 v107, s10, v107
	v_mul_f32_e32 v106, 0x3a800000, v106
	v_mul_f32_e32 v107, 0x3a800000, v107
	v_add_f32_e32 v106, 0x3727c5ac, v106
	v_add_f32_e32 v107, 0x3727c5ac, v107
	v_rsq_f32_e32 v109, v106
	v_rsq_f32_e32 v111, v107
	s_nop 0
	v_mul_f32_e32 v40, v40, v109
	v_mul_f32_e32 v56, v56, v111
	v_mul_f32_e32 v41, v41, v109
	v_mul_f32_e32 v57, v57, v111
	v_mul_f32_e32 v42, v42, v109
	v_mul_f32_e32 v58, v58, v111
	v_mul_f32_e32 v43, v43, v109
	v_mul_f32_e32 v59, v59, v111
	v_mul_f32_e32 v44, v44, v109
	v_mul_f32_e32 v60, v60, v111
	v_mul_f32_e32 v45, v45, v109
	v_mul_f32_e32 v61, v61, v111
	v_mul_f32_e32 v46, v46, v109
	v_mul_f32_e32 v62, v62, v111
	v_mul_f32_e32 v47, v47, v109
	v_mul_f32_e32 v63, v63, v111
	v_mul_f32_e32 v48, v48, v109
	v_mul_f32_e32 v64, v64, v111
	v_mul_f32_e32 v49, v49, v109
	v_mul_f32_e32 v65, v65, v111
	v_mul_f32_e32 v50, v50, v109
	v_mul_f32_e32 v66, v66, v111
	v_mul_f32_e32 v51, v51, v109
	v_mul_f32_e32 v67, v67, v111
	v_mul_f32_e32 v52, v52, v109
	v_mul_f32_e32 v68, v68, v111
	v_mul_f32_e32 v53, v53, v109
	v_mul_f32_e32 v69, v69, v111
	v_mul_f32_e32 v54, v54, v109
	v_mul_f32_e32 v70, v70, v111
	v_mul_f32_e32 v55, v55, v109
	v_mul_f32_e32 v71, v71, v111
	v_fma_f32 v40, v40, v8, v24
	v_fma_f32 v56, v56, v8, v24
	v_fma_f32 v41, v41, v9, v25
	v_fma_f32 v57, v57, v9, v25
	v_fma_f32 v42, v42, v10, v26
	v_fma_f32 v58, v58, v10, v26
	v_fma_f32 v43, v43, v11, v27
	v_fma_f32 v59, v59, v11, v27
	v_fma_f32 v44, v44, v12, v28
	v_fma_f32 v60, v60, v12, v28
	v_fma_f32 v45, v45, v13, v29
	v_fma_f32 v61, v61, v13, v29
	v_fma_f32 v46, v46, v14, v30
	v_fma_f32 v62, v62, v14, v30
	v_fma_f32 v47, v47, v15, v31
	v_fma_f32 v63, v63, v15, v31
	v_fma_f32 v48, v48, v16, v32
	v_fma_f32 v64, v64, v16, v32
	v_fma_f32 v49, v49, v17, v33
	v_fma_f32 v65, v65, v17, v33
	v_fma_f32 v50, v50, v18, v34
	v_fma_f32 v66, v66, v18, v34
	v_fma_f32 v51, v51, v19, v35
	v_fma_f32 v67, v67, v19, v35
	v_fma_f32 v52, v52, v20, v36
	v_fma_f32 v68, v68, v20, v36
	v_fma_f32 v53, v53, v21, v37
	v_fma_f32 v69, v69, v21, v37
	v_fma_f32 v54, v54, v22, v38
	v_fma_f32 v70, v70, v22, v38
	v_fma_f32 v55, v55, v23, v39
	v_fma_f32 v71, v71, v23, v39
	s_lshl_b32 s2, s11, 12
	s_add_u32 s16, s20, s2
	s_addc_u32 s17, s21, 0
	s_lshl_b32 s10, s15, 12
	s_add_u32 s18, s16, s10
	s_addc_u32 s19, s17, 0
	s_cmp_eq_u32 s14, 0
	s_cbranch_scc1 .Llnb_nof32_p0
	global_store_dwordx4 v4, v[40:43], s[16:17]
	global_store_dwordx4 v4, v[44:47], s[16:17] offset:1024
	global_store_dwordx4 v4, v[48:51], s[16:17] offset:2048
	global_store_dwordx4 v4, v[52:55], s[16:17] offset:3072
	global_store_dwordx4 v4, v[56:59], s[18:19]
	global_store_dwordx4 v4, v[60:63], s[18:19] offset:1024
	global_store_dwordx4 v4, v[64:67], s[18:19] offset:2048
	global_store_dwordx4 v4, v[68:71], s[18:19] offset:3072

; __device__ __forceinline__ void ln_phase(const PRef& P, const float* __restrict__ gw, const float* __restrict__ bw, bool write_f32) {
;     ...
;   for (int row = wv; row < TT; row += 2 * nw) {
;     float4* hp0 = (float4*)(H + (long)row * DM); float4* hp1 = (float4*)(H + (long)(row + nw) * DM); float4 v[2][4]; float s0 = 0.f, s1 = 0.f;
; #pragma unroll
;     for (int i = 0; i < 4; ++i) { v[0][i] = hp0[lane + 64 * i]; v[1][i] = hp1[lane + 64 * i]; }
; #pragma unroll
;     for (int i = 0; i < 4; ++i) { s0 += v[0][i].x + v[0][i].y + v[0][i].z + v[0][i].w; s1 += v[1][i].x + v[1][i].y + v[1][i].z + v[1][i].w; }
; #pragma unroll
;     for (int o = 32; o > 0; o >>= 1) { s0 += __shfl_xor(s0, o); s1 += __shfl_xor(s1, o); }
;     const float mu0 = s0 * (1.f / DM), mu1 = s1 * (1.f / DM); float q0 = 0.f, q1 = 0.f;
; #pragma unroll
;     for (int i = 0; i < 4; ++i) { float a = v[0][i].x - mu0, b = v[0][i].y - mu0, c = v[0][i].z - mu0, d = v[0][i].w - mu0; q0 += a * a + b * b + c * c + d * d;
;       float e = v[1][i].x - mu1, f = v[1][i].y - mu1, g = v[1][i].z - mu1, h = v[1][i].w - mu1; q1 += e * e + f * f + g * g + h * h; }
; #pragma unroll
;     for (int o = 32; o > 0; o >>= 1) { q0 += __shfl_xor(q0, o); q1 += __shfl_xor(q1, o); }
;     const float rs0 = rsqrtf(q0 * (1.f / DM) + 1e-5f), rs1 = rsqrtf(q1 * (1.f / DM) + 1e-5f);
;     if (lane == 0) { st[row] = make_float2(mu0, rs0); st[row + nw] = make_float2(mu1, rs1); }
; #pragma unroll
;     for (int i = 0; i < 4; ++i) { float4 g4 = ((const float4*)gw)[lane + 64 * i], b4 = ((const float4*)bw)[lane + 64 * i]; float4 o4, p4;
;       o4.x = (v[0][i].x - mu0) * rs0 * g4.x + b4.x; o4.y = (v[0][i].y - mu0) * rs0 * g4.y + b4.y; o4.z = (v[0][i].z - mu0) * rs0 * g4.z + b4.z; o4.w = (v[0][i].w - mu0) * rs0 * g4.w + b4.w;
;       p4.x = (v[1][i].x - mu1) * rs1 * g4.x + b4.x; p4.y = (v[1][i].y - mu1) * rs1 * g4.y + b4.y; p4.z = (v[1][i].z - mu1) * rs1 * g4.z + b4.z; p4.w = (v[1][i].w - mu1) * rs1 * g4.w + b4.w;
;       if (write_f32) { hp0[lane + 64 * i] = o4; hp1[lane + 64 * i] = p4; }
;       ((u32x2*)(hb + (long)row * DM))[lane + 64 * i] = u32x2{pk2(o4.x, o4.y), pk2(o4.z, o4.w)};
;       ((u32x2*)(hb + (long)(row + nw) * DM))[lane + 64 * i] = u32x2{pk2(p4.x, p4.y), pk2(p4.z, p4.w)}; }
;   }
; }
.Llnb_done:
	s_waitcnt vmcnt(0)
.LBB0_1502:
	s_or_b64 exec, exec, s[12:13]
	s_mov_b64 s[8:9], 0
